# 4-phase GEMM loops, balanced 4/4/4/4 stagings (ph8 staging in next iteration's phase 1), no per-segment setprio flips
# baseline (speedup 1.0000x reference)
; #define PG8_STAGE(bufoff, gbase, voff) do { _Pragma("unroll") for (int _i = 0; _i < 2; ++_i) \
;         __builtin_amdgcn_global_load_lds((const unsigned*)((const char*)(gbase) + (voff)[_i]), (LAS unsigned*)(lds + (bufoff) + ldsw + _i * 8192), 16, 0, 0); } while (0)
; #define PG8_LDA(dst, b, h) do { _Pragma("unroll") for (int m = 0; m < 4; ++m) _Pragma("unroll") for (int k = 0; k < 2; ++k) dst[m][k] = *(const LAS bf16x8*)(lds + PG8_SA(b, h) + aoff + m * 2048 + k * 1024); } while (0)
; #define PG8_LDB(dst, b, h) do { _Pragma("unroll") for (int n = 0; n < 2; ++n) _Pragma("unroll") for (int k = 0; k < 2; ++k) dst[n][k] = *(const LAS bf16x8*)(lds + PG8_SB(b, h) + boff + n * 2048 + k * 1024); } while (0)
; #define PG8_MMA(ai, bj, At, Bt) do { __builtin_amdgcn_s_setprio(1); _Pragma("unroll") for (int m = 0; m < 4; ++m) _Pragma("unroll") for (int n = 0; n < 2; ++n) _Pragma("unroll") for (int k = 0; k < 2; ++k) \
;         acc[ai][bj][m][n] = __builtin_amdgcn_mfma_f32_16x16x32_bf16(Bt[n][k], At[m][k], acc[ai][bj][m][n], 0, 0, 0); __builtin_amdgcn_s_setprio(0); } while (0)
; #define PG8_BAR __builtin_amdgcn_s_barrier()
; template <class Epi, class Sched>
; __device__ __forceinline__ void gemm_phase(LAS unsigned char* lds, const Gemm g, const Sched& S, const Epi& E) {
;     ...
;         const char* nA = has_next ? (const char*)g.A + (size_t)nxt.pm * tstep + (size_t)nxt.ks * sstep : cA; const char* nB = has_next ? (const char*)g.Bt + (size_t)nxt.pn * tstep + (size_t)nxt.ks * sstep : cB;
;         for (int t = 0; t < nt; t += 2) {
;             const bool last = (t == nt - 2);
;             const char* a1 = cA + (size_t)(t + 1) * kstep;
;             const char* a2 = last ? nA : cA + (size_t)(t + 2) * kstep; const char* b2 = last ? nB : cB + (size_t)(t + 2) * kstep;
;             const char* a3 = a2 + kstep; const char* b3 = b2 + kstep;
;             PG8_LDB(B0, 0, 0); PG8_SCHED; PG8_LDA(At, 0, 0); PG8_STAGE(PG8_SA(1, 1), a1 + hstep, voffA);
;             PG8_WAIT_L(8); PG8_BAR; PG8_WAIT_L(0); PG8_MMA(0, 0, At, B0); PG8_BAR; PG8_SCHED;
;             PG8_LDB(B1, 0, 1); PG8_STAGE(PG8_SB(0, 0), b2, voffB);
;             PG8_BAR; PG8_WAIT_L(0); PG8_MMA(0, 1, At, B1); PG8_BAR;
;             PG8_LDA(At, 0, 1); PG8_STAGE(PG8_SA(0, 0), a2, voffA);
;             PG8_BAR; PG8_WAIT_L(0); PG8_MMA(1, 0, At, B0); PG8_BAR; PG8_SCHED;
;             PG8_STAGE(PG8_SB(0, 1), b2 + hstep, voffB);
.LBB0_44:
	s_add_u32 s100, s73, 0x1fff80
	s_addc_u32 s101, s74, 0
	v_lshl_add_u64 v[66:67], s[100:101], 0, v[0:1]
	s_add_i32 m0, s60, 0x1c000
	s_nop 0
	global_load_lds_dwordx4 v[66:67], off
	v_lshl_add_u64 v[66:67], s[100:101], 0, v[146:147]
	s_add_i32 m0, s60, 0x1e000
	s_nop 0
	global_load_lds_dwordx4 v[66:67], off
	s_add_u32 s50, s28, 0x100
	s_addc_u32 s51, s29, 0
	s_cmpk_eq_i32 s75, 0x7c
	s_cselect_b32 s55, s27, s51
	s_cselect_b32 s54, s71, s50
	s_cselect_b32 s53, s25, s74
	s_cselect_b32 s52, s72, s73
	v_lshl_add_u64 v[156:157], s[28:29], 0, v[150:151]
	s_add_i32 m0, s9, 0xc000
	s_nop 0
	global_load_lds_dwordx4 v[156:157], off
	v_lshl_add_u64 v[156:157], s[28:29], 0, v[148:149]
	s_add_i32 m0, s9, 0xe000
	s_nop 0
	global_load_lds_dwordx4 v[156:157], off
	s_add_i32 s38, 0, 0x10000
	v_add_u32_e32 v78, s38, v163
	ds_read_b128 v[66:69], v78
	ds_read_b128 v[70:73], v78 offset:1024
	ds_read_b128 v[74:77], v78 offset:2048
	ds_read_b128 v[78:81], v78 offset:3072
	ds_read_b128 v[152:155], v165
	ds_read_b128 v[166:169], v165 offset:1024
	ds_read_b128 v[170:173], v165 offset:2048
	ds_read_b128 v[174:177], v165 offset:3072
	ds_read_b128 v[178:181], v165 offset:4096
	ds_read_b128 v[182:185], v165 offset:5120
	ds_read_b128 v[186:189], v165 offset:6144
	ds_read_b128 v[190:193], v165 offset:7168
	s_add_i32 s39, 0, 0x14000
	v_add_u32_e32 v156, s39, v163
	ds_read_b128 v[194:197], v156
	ds_read_b128 v[198:201], v156 offset:1024
	ds_read_b128 v[202:205], v156 offset:2048
	ds_read_b128 v[210:213], v156 offset:3072
	s_waitcnt lgkmcnt(4)
	s_barrier
	s_waitcnt lgkmcnt(0)
	v_mfma_f32_16x16x32_bf16 v[142:145], v[66:69], v[152:155], v[142:145]
	v_mfma_f32_16x16x32_bf16 v[138:141], v[74:77], v[152:155], v[138:141]
	v_mfma_f32_16x16x32_bf16 v[126:129], v[66:69], v[170:173], v[126:129]
	v_mfma_f32_16x16x32_bf16 v[122:125], v[74:77], v[170:173], v[122:125]
	v_mfma_f32_16x16x32_bf16 v[110:113], v[66:69], v[178:181], v[110:113]
	v_mfma_f32_16x16x32_bf16 v[106:109], v[74:77], v[178:181], v[106:109]
	v_mfma_f32_16x16x32_bf16 v[102:105], v[66:69], v[186:189], v[102:105]
	v_mfma_f32_16x16x32_bf16 v[98:101], v[74:77], v[186:189], v[98:101]
	v_mfma_f32_16x16x32_bf16 v[142:145], v[70:73], v[166:169], v[142:145]
	v_mfma_f32_16x16x32_bf16 v[138:141], v[78:81], v[166:169], v[138:141]
	v_mfma_f32_16x16x32_bf16 v[126:129], v[70:73], v[174:177], v[126:129]
	v_mfma_f32_16x16x32_bf16 v[122:125], v[78:81], v[174:177], v[122:125]
	v_mfma_f32_16x16x32_bf16 v[110:113], v[70:73], v[182:185], v[110:113]
	v_mfma_f32_16x16x32_bf16 v[106:109], v[78:81], v[182:185], v[106:109]
	v_mfma_f32_16x16x32_bf16 v[102:105], v[70:73], v[190:193], v[102:105]
	v_mfma_f32_16x16x32_bf16 v[98:101], v[78:81], v[190:193], v[98:101]
	v_mfma_f32_16x16x32_bf16 v[134:137], v[194:197], v[152:155], v[134:137]
	v_mfma_f32_16x16x32_bf16 v[130:133], v[202:205], v[152:155], v[130:133]
	v_mfma_f32_16x16x32_bf16 v[118:121], v[194:197], v[170:173], v[118:121]
	v_mfma_f32_16x16x32_bf16 v[114:117], v[202:205], v[170:173], v[114:117]
	v_mfma_f32_16x16x32_bf16 v[94:97], v[194:197], v[178:181], v[94:97]
	v_mfma_f32_16x16x32_bf16 v[90:93], v[202:205], v[178:181], v[90:93]
	v_mfma_f32_16x16x32_bf16 v[86:89], v[194:197], v[186:189], v[86:89]
	v_mfma_f32_16x16x32_bf16 v[82:85], v[202:205], v[186:189], v[82:85]
	v_mfma_f32_16x16x32_bf16 v[134:137], v[198:201], v[166:169], v[134:137]
	v_mfma_f32_16x16x32_bf16 v[130:133], v[210:213], v[166:169], v[130:133]
	v_mfma_f32_16x16x32_bf16 v[118:121], v[198:201], v[174:177], v[118:121]
	v_mfma_f32_16x16x32_bf16 v[114:117], v[210:213], v[174:177], v[114:117]
	v_mfma_f32_16x16x32_bf16 v[94:97], v[198:201], v[182:185], v[94:97]
	v_mfma_f32_16x16x32_bf16 v[90:93], v[210:213], v[182:185], v[90:93]
	v_mfma_f32_16x16x32_bf16 v[86:89], v[198:201], v[190:193], v[86:89]
	v_mfma_f32_16x16x32_bf16 v[82:85], v[210:213], v[190:193], v[82:85]
	s_barrier
	s_add_i32 s28, s38, s60
	v_lshl_add_u64 v[156:157], s[52:53], 0, v[0:1]
	s_mov_b32 m0, s28
	v_lshl_add_u64 v[160:161], s[52:53], 0, v[146:147]
	global_load_lds_dwordx4 v[156:157], off
	s_add_i32 m0, s28, 0x2000
	s_nop 0
	global_load_lds_dwordx4 v[160:161], off
	s_mov_b32 m0, s9
	v_lshl_add_u64 v[206:207], s[54:55], 0, v[0:1]
	global_load_lds_dwordx4 v[206:207], off
	v_lshl_add_u64 v[214:215], s[54:55], 0, v[146:147]
	s_mov_b32 m0, s61
	s_nop 0
	global_load_lds_dwordx4 v[214:215], off
	ds_read_b128 v[152:155], v165 offset:16384
	ds_read_b128 v[166:169], v165 offset:17408
	ds_read_b128 v[170:173], v165 offset:18432
	ds_read_b128 v[174:177], v165 offset:19456
	ds_read_b128 v[178:181], v165 offset:20480
	ds_read_b128 v[182:185], v165 offset:21504
	ds_read_b128 v[186:189], v165 offset:22528
	ds_read_b128 v[190:193], v165 offset:23552
	s_waitcnt vmcnt(4)
	s_waitcnt lgkmcnt(0)
	s_barrier
; #define PG8_STAGE(bufoff, gbase, voff) do { _Pragma("unroll") for (int _i = 0; _i < 2; ++_i) \
;         __builtin_amdgcn_global_load_lds((const unsigned*)((const char*)(gbase) + (voff)[_i]), (LAS unsigned*)(lds + (bufoff) + ldsw + _i * 8192), 16, 0, 0); } while (0)
; #define PG8_LDA(dst, b, h) do { _Pragma("unroll") for (int m = 0; m < 4; ++m) _Pragma("unroll") for (int k = 0; k < 2; ++k) dst[m][k] = *(const LAS bf16x8*)(lds + PG8_SA(b, h) + aoff + m * 2048 + k * 1024); } while (0)
; #define PG8_LDB(dst, b, h) do { _Pragma("unroll") for (int n = 0; n < 2; ++n) _Pragma("unroll") for (int k = 0; k < 2; ++k) dst[n][k] = *(const LAS bf16x8*)(lds + PG8_SB(b, h) + boff + n * 2048 + k * 1024); } while (0)
; #define PG8_MMA(ai, bj, At, Bt) do { __builtin_amdgcn_s_setprio(1); _Pragma("unroll") for (int m = 0; m < 4; ++m) _Pragma("unroll") for (int n = 0; n < 2; ++n) _Pragma("unroll") for (int k = 0; k < 2; ++k) \
;         acc[ai][bj][m][n] = __builtin_amdgcn_mfma_f32_16x16x32_bf16(Bt[n][k], At[m][k], acc[ai][bj][m][n], 0, 0, 0); __builtin_amdgcn_s_setprio(0); } while (0)
; #define PG8_WAIT_V(n) asm volatile("s_waitcnt vmcnt(" #n ")" ::: "memory")
; #define PG8_WAIT_L(n) asm volatile("s_waitcnt lgkmcnt(" #n ")" ::: "memory")
; #define PG8_BAR __builtin_amdgcn_s_barrier()
; #define PG8_SCHED __builtin_amdgcn_sched_barrier(0)
; template <class Epi, class Sched>
; __device__ __forceinline__ void gemm_phase(LAS unsigned char* lds, const Gemm g, const Sched& S, const Epi& E) {
;     ...
;             PG8_BAR; PG8_WAIT_L(0); PG8_MMA(1, 0, At, B0); PG8_BAR; PG8_SCHED;
;             PG8_STAGE(PG8_SB(0, 1), b2 + hstep, voffB);
;             PG8_WAIT_V(6); PG8_BAR; PG8_MMA(1, 1, At, B1); PG8_BAR;
;             PG8_LDB(B0, 1, 0); PG8_SCHED; PG8_LDA(At, 1, 0); PG8_STAGE(PG8_SA(0, 1), a2 + hstep, voffA);
;             PG8_WAIT_L(8); PG8_BAR; PG8_WAIT_L(0); PG8_MMA(0, 0, At, B0); PG8_BAR; PG8_SCHED;
;             PG8_LDB(B1, 1, 1); PG8_STAGE(PG8_SB(1, 0), b3, voffB);
	v_mfma_f32_16x16x32_bf16 v[62:65], v[66:69], v[152:155], v[62:65]
	v_mfma_f32_16x16x32_bf16 v[58:61], v[74:77], v[152:155], v[58:61]
	v_mfma_f32_16x16x32_bf16 v[46:49], v[66:69], v[170:173], v[46:49]
	v_mfma_f32_16x16x32_bf16 v[42:45], v[74:77], v[170:173], v[42:45]
	v_mfma_f32_16x16x32_bf16 v[30:33], v[66:69], v[178:181], v[30:33]
	v_mfma_f32_16x16x32_bf16 v[26:29], v[74:77], v[178:181], v[26:29]
	v_mfma_f32_16x16x32_bf16 v[22:25], v[66:69], v[186:189], v[22:25]
	v_mfma_f32_16x16x32_bf16 v[14:17], v[74:77], v[186:189], v[14:17]
	v_mfma_f32_16x16x32_bf16 v[62:65], v[70:73], v[166:169], v[62:65]
	v_mfma_f32_16x16x32_bf16 v[58:61], v[78:81], v[166:169], v[58:61]
	v_mfma_f32_16x16x32_bf16 v[46:49], v[70:73], v[174:177], v[46:49]
	v_mfma_f32_16x16x32_bf16 v[42:45], v[78:81], v[174:177], v[42:45]
	v_mfma_f32_16x16x32_bf16 v[30:33], v[70:73], v[182:185], v[30:33]
	v_mfma_f32_16x16x32_bf16 v[26:29], v[78:81], v[182:185], v[26:29]
	v_mfma_f32_16x16x32_bf16 v[22:25], v[70:73], v[190:193], v[22:25]
	v_mfma_f32_16x16x32_bf16 v[14:17], v[78:81], v[190:193], v[14:17]
	v_mfma_f32_16x16x32_bf16 v[54:57], v[194:197], v[152:155], v[54:57]
	v_mfma_f32_16x16x32_bf16 v[50:53], v[202:205], v[152:155], v[50:53]
	v_mfma_f32_16x16x32_bf16 v[38:41], v[194:197], v[170:173], v[38:41]
	v_mfma_f32_16x16x32_bf16 v[34:37], v[202:205], v[170:173], v[34:37]
	v_mfma_f32_16x16x32_bf16 v[18:21], v[194:197], v[178:181], v[18:21]
	v_mfma_f32_16x16x32_bf16 v[10:13], v[202:205], v[178:181], v[10:13]
	v_mfma_f32_16x16x32_bf16 v[6:9], v[194:197], v[186:189], v[6:9]
	v_mfma_f32_16x16x32_bf16 v[2:5], v[202:205], v[186:189], v[2:5]
	v_mfma_f32_16x16x32_bf16 v[54:57], v[198:201], v[166:169], v[54:57]
	v_mfma_f32_16x16x32_bf16 v[50:53], v[210:213], v[166:169], v[50:53]
	v_mfma_f32_16x16x32_bf16 v[38:41], v[198:201], v[174:177], v[38:41]
	v_mfma_f32_16x16x32_bf16 v[34:37], v[210:213], v[174:177], v[34:37]
	v_mfma_f32_16x16x32_bf16 v[18:21], v[198:201], v[182:185], v[18:21]
	v_mfma_f32_16x16x32_bf16 v[10:13], v[210:213], v[182:185], v[10:13]
	v_mfma_f32_16x16x32_bf16 v[6:9], v[198:201], v[190:193], v[6:9]
	v_mfma_f32_16x16x32_bf16 v[2:5], v[210:213], v[190:193], v[2:5]
	s_barrier
	s_add_u32 s28, s52, 0x200000
	s_addc_u32 s29, s53, 0
	s_add_i32 s38, s39, s60
	v_lshl_add_u64 v[66:67], s[28:29], 0, v[0:1]
	s_mov_b32 m0, s38
	s_nop 0
	global_load_lds_dwordx4 v[66:67], off
	v_lshl_add_u64 v[66:67], s[28:29], 0, v[146:147]
	s_add_i32 m0, s38, 0x2000
	s_nop 0
	global_load_lds_dwordx4 v[66:67], off
	s_add_u32 s28, s54, 0x200000
	s_addc_u32 s29, s55, 0
	s_mov_b32 m0, s62
	v_lshl_add_u64 v[194:195], s[28:29], 0, v[0:1]
	global_load_lds_dwordx4 v[194:195], off
	v_lshl_add_u64 v[194:195], s[28:29], 0, v[146:147]
	s_mov_b32 m0, s63
	s_nop 0
	global_load_lds_dwordx4 v[194:195], off
	s_add_i32 s38, 0, 0x18000
	v_add_u32_e32 v78, s38, v163
	ds_read_b128 v[66:69], v78
	ds_read_b128 v[70:73], v78 offset:1024
	ds_read_b128 v[74:77], v78 offset:2048
	ds_read_b128 v[78:81], v78 offset:3072
	ds_read_b128 v[152:155], v165 offset:32768
	ds_read_b128 v[166:169], v165 offset:33792
	ds_read_b128 v[170:173], v165 offset:34816
	ds_read_b128 v[174:177], v165 offset:35840
	ds_read_b128 v[178:181], v165 offset:36864
	ds_read_b128 v[182:185], v165 offset:37888
	ds_read_b128 v[186:189], v165 offset:38912
	ds_read_b128 v[190:193], v165 offset:39936
	s_add_i32 s39, 0, 0x1c000
	v_add_u32_e32 v210, s39, v163
	ds_read_b128 v[194:197], v210
	ds_read_b128 v[198:201], v210 offset:1024
	ds_read_b128 v[202:205], v210 offset:2048
	ds_read_b128 v[210:213], v210 offset:3072
	s_waitcnt lgkmcnt(4)
	s_barrier
; #define PG8_STAGE(bufoff, gbase, voff) do { _Pragma("unroll") for (int _i = 0; _i < 2; ++_i) \
;         __builtin_amdgcn_global_load_lds((const unsigned*)((const char*)(gbase) + (voff)[_i]), (LAS unsigned*)(lds + (bufoff) + ldsw + _i * 8192), 16, 0, 0); } while (0)
; #define PG8_LDA(dst, b, h) do { _Pragma("unroll") for (int m = 0; m < 4; ++m) _Pragma("unroll") for (int k = 0; k < 2; ++k) dst[m][k] = *(const LAS bf16x8*)(lds + PG8_SA(b, h) + aoff + m * 2048 + k * 1024); } while (0)
; #define PG8_LDB(dst, b, h) do { _Pragma("unroll") for (int n = 0; n < 2; ++n) _Pragma("unroll") for (int k = 0; k < 2; ++k) dst[n][k] = *(const LAS bf16x8*)(lds + PG8_SB(b, h) + boff + n * 2048 + k * 1024); } while (0)
; #define PG8_MMA(ai, bj, At, Bt) do { __builtin_amdgcn_s_setprio(1); _Pragma("unroll") for (int m = 0; m < 4; ++m) _Pragma("unroll") for (int n = 0; n < 2; ++n) _Pragma("unroll") for (int k = 0; k < 2; ++k) \
;         acc[ai][bj][m][n] = __builtin_amdgcn_mfma_f32_16x16x32_bf16(Bt[n][k], At[m][k], acc[ai][bj][m][n], 0, 0, 0); __builtin_amdgcn_s_setprio(0); } while (0)
; #define PG8_WAIT_V(n) asm volatile("s_waitcnt vmcnt(" #n ")" ::: "memory")
; #define PG8_WAIT_L(n) asm volatile("s_waitcnt lgkmcnt(" #n ")" ::: "memory")
; #define PG8_BAR __builtin_amdgcn_s_barrier()
; #define PG8_SCHED __builtin_amdgcn_sched_barrier(0)
; template <class Epi, class Sched>
; __device__ __forceinline__ void gemm_phase(LAS unsigned char* lds, const Gemm g, const Sched& S, const Epi& E) {
;     ...
;             PG8_WAIT_L(8); PG8_BAR; PG8_WAIT_L(0); PG8_MMA(0, 0, At, B0); PG8_BAR; PG8_SCHED;
;             PG8_LDB(B1, 1, 1); PG8_STAGE(PG8_SB(1, 0), b3, voffB);
;             PG8_BAR; PG8_WAIT_L(0); PG8_MMA(0, 1, At, B1); PG8_BAR;
;             PG8_LDA(At, 1, 1); PG8_STAGE(PG8_SA(1, 0), a3, voffA);
;             PG8_BAR; PG8_WAIT_L(0); PG8_MMA(1, 0, At, B0); PG8_BAR; PG8_SCHED;
;             PG8_STAGE(PG8_SB(1, 1), b3 + hstep, voffB);
;             PG8_WAIT_V(6); PG8_BAR; PG8_MMA(1, 1, At, B1); PG8_BAR;
;         }
;         E(acc, cur, wr, wc, fr, fq);
;         if (!has_next) break;
	s_waitcnt lgkmcnt(0)
	v_mfma_f32_16x16x32_bf16 v[142:145], v[66:69], v[152:155], v[142:145]
	v_mfma_f32_16x16x32_bf16 v[138:141], v[74:77], v[152:155], v[138:141]
	v_mfma_f32_16x16x32_bf16 v[126:129], v[66:69], v[170:173], v[126:129]
	v_mfma_f32_16x16x32_bf16 v[122:125], v[74:77], v[170:173], v[122:125]
	v_mfma_f32_16x16x32_bf16 v[110:113], v[66:69], v[178:181], v[110:113]
	v_mfma_f32_16x16x32_bf16 v[106:109], v[74:77], v[178:181], v[106:109]
	v_mfma_f32_16x16x32_bf16 v[102:105], v[66:69], v[186:189], v[102:105]
	v_mfma_f32_16x16x32_bf16 v[98:101], v[74:77], v[186:189], v[98:101]
	v_mfma_f32_16x16x32_bf16 v[142:145], v[70:73], v[166:169], v[142:145]
	v_mfma_f32_16x16x32_bf16 v[138:141], v[78:81], v[166:169], v[138:141]
	v_mfma_f32_16x16x32_bf16 v[126:129], v[70:73], v[174:177], v[126:129]
	v_mfma_f32_16x16x32_bf16 v[122:125], v[78:81], v[174:177], v[122:125]
	v_mfma_f32_16x16x32_bf16 v[110:113], v[70:73], v[182:185], v[110:113]
	v_mfma_f32_16x16x32_bf16 v[106:109], v[78:81], v[182:185], v[106:109]
	v_mfma_f32_16x16x32_bf16 v[102:105], v[70:73], v[190:193], v[102:105]
	v_mfma_f32_16x16x32_bf16 v[98:101], v[78:81], v[190:193], v[98:101]
	v_mfma_f32_16x16x32_bf16 v[134:137], v[194:197], v[152:155], v[134:137]
	v_mfma_f32_16x16x32_bf16 v[130:133], v[202:205], v[152:155], v[130:133]
	v_mfma_f32_16x16x32_bf16 v[118:121], v[194:197], v[170:173], v[118:121]
	v_mfma_f32_16x16x32_bf16 v[114:117], v[202:205], v[170:173], v[114:117]
	v_mfma_f32_16x16x32_bf16 v[94:97], v[194:197], v[178:181], v[94:97]
	v_mfma_f32_16x16x32_bf16 v[90:93], v[202:205], v[178:181], v[90:93]
	v_mfma_f32_16x16x32_bf16 v[86:89], v[194:197], v[186:189], v[86:89]
	v_mfma_f32_16x16x32_bf16 v[82:85], v[202:205], v[186:189], v[82:85]
	v_mfma_f32_16x16x32_bf16 v[134:137], v[198:201], v[166:169], v[134:137]
	v_mfma_f32_16x16x32_bf16 v[130:133], v[210:213], v[166:169], v[130:133]
	v_mfma_f32_16x16x32_bf16 v[118:121], v[198:201], v[174:177], v[118:121]
	v_mfma_f32_16x16x32_bf16 v[114:117], v[210:213], v[174:177], v[114:117]
	v_mfma_f32_16x16x32_bf16 v[94:97], v[198:201], v[182:185], v[94:97]
	v_mfma_f32_16x16x32_bf16 v[90:93], v[210:213], v[182:185], v[90:93]
	v_mfma_f32_16x16x32_bf16 v[86:89], v[198:201], v[190:193], v[86:89]
	v_mfma_f32_16x16x32_bf16 v[82:85], v[210:213], v[190:193], v[82:85]
	s_barrier
	s_add_i32 s28, s38, s60
	v_lshl_add_u64 v[156:157], v[156:157], 0, s[36:37]
	s_mov_b32 m0, s28
	s_nop 0
	global_load_lds_dwordx4 v[156:157], off
	v_lshl_add_u64 v[156:157], v[160:161], 0, s[36:37]
	s_add_i32 m0, s28, 0x2000
	s_nop 0
	global_load_lds_dwordx4 v[156:157], off
	s_mov_b32 m0, s66
	v_lshl_add_u64 v[156:157], v[206:207], 0, s[36:37]
	global_load_lds_dwordx4 v[156:157], off
	v_lshl_add_u64 v[156:157], v[214:215], 0, s[36:37]
	s_mov_b32 m0, s67
	s_nop 0
	global_load_lds_dwordx4 v[156:157], off
	ds_read_b128 v[152:155], v165 offset:49152
	ds_read_b128 v[166:169], v165 offset:50176
	ds_read_b128 v[170:173], v165 offset:51200
	ds_read_b128 v[174:177], v165 offset:52224
	ds_read_b128 v[178:181], v165 offset:53248
	ds_read_b128 v[182:185], v165 offset:54272
	ds_read_b128 v[186:189], v165 offset:55296
	ds_read_b128 v[190:193], v165 offset:56320
	s_waitcnt vmcnt(4)
	s_waitcnt lgkmcnt(0)
	s_barrier
	v_mfma_f32_16x16x32_bf16 v[62:65], v[66:69], v[152:155], v[62:65]
	v_mfma_f32_16x16x32_bf16 v[58:61], v[74:77], v[152:155], v[58:61]
	v_mfma_f32_16x16x32_bf16 v[46:49], v[66:69], v[170:173], v[46:49]
	v_mfma_f32_16x16x32_bf16 v[42:45], v[74:77], v[170:173], v[42:45]
	v_mfma_f32_16x16x32_bf16 v[30:33], v[66:69], v[178:181], v[30:33]
	v_mfma_f32_16x16x32_bf16 v[26:29], v[74:77], v[178:181], v[26:29]
	v_mfma_f32_16x16x32_bf16 v[22:25], v[66:69], v[186:189], v[22:25]
	v_mfma_f32_16x16x32_bf16 v[14:17], v[74:77], v[186:189], v[14:17]
	v_mfma_f32_16x16x32_bf16 v[62:65], v[70:73], v[166:169], v[62:65]
	v_mfma_f32_16x16x32_bf16 v[58:61], v[78:81], v[166:169], v[58:61]
	v_mfma_f32_16x16x32_bf16 v[46:49], v[70:73], v[174:177], v[46:49]
	v_mfma_f32_16x16x32_bf16 v[42:45], v[78:81], v[174:177], v[42:45]
	v_mfma_f32_16x16x32_bf16 v[30:33], v[70:73], v[182:185], v[30:33]
	v_mfma_f32_16x16x32_bf16 v[26:29], v[78:81], v[182:185], v[26:29]
	v_mfma_f32_16x16x32_bf16 v[22:25], v[70:73], v[190:193], v[22:25]
	v_mfma_f32_16x16x32_bf16 v[14:17], v[78:81], v[190:193], v[14:17]
	v_mfma_f32_16x16x32_bf16 v[54:57], v[194:197], v[152:155], v[54:57]
	v_mfma_f32_16x16x32_bf16 v[50:53], v[202:205], v[152:155], v[50:53]
	v_mfma_f32_16x16x32_bf16 v[38:41], v[194:197], v[170:173], v[38:41]
	v_mfma_f32_16x16x32_bf16 v[34:37], v[202:205], v[170:173], v[34:37]
	v_mfma_f32_16x16x32_bf16 v[18:21], v[194:197], v[178:181], v[18:21]
	v_mfma_f32_16x16x32_bf16 v[10:13], v[202:205], v[178:181], v[10:13]
	v_mfma_f32_16x16x32_bf16 v[6:9], v[194:197], v[186:189], v[6:9]
	v_mfma_f32_16x16x32_bf16 v[2:5], v[202:205], v[186:189], v[2:5]
	v_mfma_f32_16x16x32_bf16 v[54:57], v[198:201], v[166:169], v[54:57]
	v_mfma_f32_16x16x32_bf16 v[50:53], v[210:213], v[166:169], v[50:53]
	v_mfma_f32_16x16x32_bf16 v[38:41], v[198:201], v[174:177], v[38:41]
	v_mfma_f32_16x16x32_bf16 v[34:37], v[210:213], v[174:177], v[34:37]
	v_mfma_f32_16x16x32_bf16 v[18:21], v[198:201], v[182:185], v[18:21]
	v_mfma_f32_16x16x32_bf16 v[10:13], v[210:213], v[182:185], v[10:13]
	v_mfma_f32_16x16x32_bf16 v[6:9], v[198:201], v[190:193], v[6:9]
	v_mfma_f32_16x16x32_bf16 v[2:5], v[210:213], v[190:193], v[2:5]
	s_add_i32 s75, s75, 2
	s_add_u32 s73, s73, 0x100
	s_addc_u32 s74, s74, 0
	s_cmpk_gt_u32 s75, 0x7d
	s_mov_b64 s[28:29], s[50:51]
	s_barrier
	s_cbranch_scc0 .LBB0_44
	s_cmp_lt_i32 s8, 64
	s_cselect_b64 s[50:51], -1, 0
	s_cmp_gt_i32 s8, 63
	s_cbranch_scc0 .LBB0_35
	s_mov_b64 s[52:53], 0x18000
	s_mov_b64 s[28:29], s[46:47]
	s_branch .LBB0_36

; #define PG8_STAGE(bufoff, gbase, voff) do { _Pragma("unroll") for (int _i = 0; _i < 2; ++_i) \
;         __builtin_amdgcn_global_load_lds((const unsigned*)((const char*)(gbase) + (voff)[_i]), (LAS unsigned*)(lds + (bufoff) + ldsw + _i * 8192), 16, 0, 0); } while (0)
; #define PG8_LDA(dst, b, h) do { _Pragma("unroll") for (int m = 0; m < 4; ++m) _Pragma("unroll") for (int k = 0; k < 2; ++k) dst[m][k] = *(const LAS bf16x8*)(lds + PG8_SA(b, h) + aoff + m * 2048 + k * 1024); } while (0)
; #define PG8_LDB(dst, b, h) do { _Pragma("unroll") for (int n = 0; n < 2; ++n) _Pragma("unroll") for (int k = 0; k < 2; ++k) dst[n][k] = *(const LAS bf16x8*)(lds + PG8_SB(b, h) + boff + n * 2048 + k * 1024); } while (0)
; #define PG8_MMA(ai, bj, At, Bt) do { __builtin_amdgcn_s_setprio(1); _Pragma("unroll") for (int m = 0; m < 4; ++m) _Pragma("unroll") for (int n = 0; n < 2; ++n) _Pragma("unroll") for (int k = 0; k < 2; ++k) \
;         acc[ai][bj][m][n] = __builtin_amdgcn_mfma_f32_16x16x32_bf16(Bt[n][k], At[m][k], acc[ai][bj][m][n], 0, 0, 0); __builtin_amdgcn_s_setprio(0); } while (0)
; #define PG8_WAIT_L(n) asm volatile("s_waitcnt lgkmcnt(" #n ")" ::: "memory")
; #define PG8_BAR __builtin_amdgcn_s_barrier()
; #define PG8_SCHED __builtin_amdgcn_sched_barrier(0)
; template <class Epi, class Sched>
; __device__ __forceinline__ void gemm_phase(LAS unsigned char* lds, const Gemm g, const Sched& S, const Epi& E) {
;     ...
;         for (int t = 0; t < nt; t += 2) {
;             const bool last = (t == nt - 2);
;             const char* a1 = cA + (size_t)(t + 1) * kstep;
;             const char* a2 = last ? nA : cA + (size_t)(t + 2) * kstep; const char* b2 = last ? nB : cB + (size_t)(t + 2) * kstep;
;             const char* a3 = a2 + kstep; const char* b3 = b2 + kstep;
;             PG8_LDB(B0, 0, 0); PG8_SCHED; PG8_LDA(At, 0, 0); PG8_STAGE(PG8_SA(1, 1), a1 + hstep, voffA);
;             PG8_WAIT_L(8); PG8_BAR; PG8_WAIT_L(0); PG8_MMA(0, 0, At, B0); PG8_BAR; PG8_SCHED;
;             PG8_LDB(B1, 0, 1); PG8_STAGE(PG8_SB(0, 0), b2, voffB);
;             PG8_BAR; PG8_WAIT_L(0); PG8_MMA(0, 1, At, B1); PG8_BAR;
;             PG8_LDA(At, 0, 1); PG8_STAGE(PG8_SA(0, 0), a2, voffA);
;             PG8_BAR; PG8_WAIT_L(0); PG8_MMA(1, 0, At, B0); PG8_BAR; PG8_SCHED;
.LBB0_58:
	s_add_u32 s100, s69, 0x1fff80
	s_addc_u32 s101, s70, 0
	v_lshl_add_u64 v[140:141], s[100:101], 0, v[0:1]
	s_add_i32 m0, s63, 0x1c000
	s_nop 0
	global_load_lds_dwordx4 v[140:141], off
	v_lshl_add_u64 v[140:141], s[100:101], 0, v[130:131]
	s_add_i32 m0, s63, 0x1e000
	s_nop 0
	global_load_lds_dwordx4 v[140:141], off
	s_add_u32 s52, s50, 0x100
	s_addc_u32 s53, s51, 0
	s_cmp_eq_u32 s71, 28
	s_cselect_b32 s57, s11, s53
	s_cselect_b32 s56, s29, s52
	s_cselect_b32 s55, s41, s70
	s_cselect_b32 s54, s43, s69
	v_lshl_add_u64 v[156:157], s[50:51], 0, v[134:135]
	s_add_i32 m0, s25, 0xc000
	s_nop 0
	global_load_lds_dwordx4 v[156:157], off
	v_lshl_add_u64 v[156:157], s[50:51], 0, v[132:133]
	s_add_i32 m0, s25, 0xe000
	s_nop 0
	global_load_lds_dwordx4 v[156:157], off
	s_add_i32 s38, 0, 0x10000
	v_add_u32_e32 v152, s38, v137
	ds_read_b128 v[140:143], v152
	ds_read_b128 v[144:147], v152 offset:1024
	ds_read_b128 v[148:151], v152 offset:2048
	ds_read_b128 v[152:155], v152 offset:3072
	ds_read_b128 v[160:163], v139
	ds_read_b128 v[164:167], v139 offset:1024
	ds_read_b128 v[168:171], v139 offset:2048
	ds_read_b128 v[172:175], v139 offset:3072
	ds_read_b128 v[176:179], v139 offset:4096
	ds_read_b128 v[180:183], v139 offset:5120
	ds_read_b128 v[184:187], v139 offset:6144
	ds_read_b128 v[188:191], v139 offset:7168
	s_add_i32 s50, 0, 0x14000
	v_add_u32_e32 v156, s50, v137
	ds_read_b128 v[192:195], v156
	ds_read_b128 v[196:199], v156 offset:1024
	ds_read_b128 v[200:203], v156 offset:2048
	ds_read_b128 v[204:207], v156 offset:3072
	s_waitcnt lgkmcnt(4)
	s_barrier
	s_waitcnt lgkmcnt(0)
	v_mfma_f32_16x16x32_bf16 v[126:129], v[140:143], v[160:163], v[126:129]
	v_mfma_f32_16x16x32_bf16 v[122:125], v[148:151], v[160:163], v[122:125]
	v_mfma_f32_16x16x32_bf16 v[118:121], v[140:143], v[168:171], v[118:121]
	v_mfma_f32_16x16x32_bf16 v[114:117], v[148:151], v[168:171], v[114:117]
	v_mfma_f32_16x16x32_bf16 v[106:109], v[140:143], v[176:179], v[106:109]
	v_mfma_f32_16x16x32_bf16 v[98:101], v[148:151], v[176:179], v[98:101]
	v_mfma_f32_16x16x32_bf16 v[90:93], v[140:143], v[184:187], v[90:93]
	v_mfma_f32_16x16x32_bf16 v[82:85], v[148:151], v[184:187], v[82:85]
	v_mfma_f32_16x16x32_bf16 v[126:129], v[144:147], v[164:167], v[126:129]
	v_mfma_f32_16x16x32_bf16 v[122:125], v[152:155], v[164:167], v[122:125]
	v_mfma_f32_16x16x32_bf16 v[118:121], v[144:147], v[172:175], v[118:121]
	v_mfma_f32_16x16x32_bf16 v[114:117], v[152:155], v[172:175], v[114:117]
	v_mfma_f32_16x16x32_bf16 v[106:109], v[144:147], v[180:183], v[106:109]
	v_mfma_f32_16x16x32_bf16 v[98:101], v[152:155], v[180:183], v[98:101]
	v_mfma_f32_16x16x32_bf16 v[90:93], v[144:147], v[188:191], v[90:93]
	v_mfma_f32_16x16x32_bf16 v[82:85], v[152:155], v[188:191], v[82:85]
	v_mfma_f32_16x16x32_bf16 v[110:113], v[192:195], v[160:163], v[110:113]
	v_mfma_f32_16x16x32_bf16 v[102:105], v[200:203], v[160:163], v[102:105]
	v_mfma_f32_16x16x32_bf16 v[94:97], v[192:195], v[168:171], v[94:97]
	v_mfma_f32_16x16x32_bf16 v[86:89], v[200:203], v[168:171], v[86:89]
	v_mfma_f32_16x16x32_bf16 v[78:81], v[192:195], v[176:179], v[78:81]
	v_mfma_f32_16x16x32_bf16 v[74:77], v[200:203], v[176:179], v[74:77]
	v_mfma_f32_16x16x32_bf16 v[70:73], v[192:195], v[184:187], v[70:73]
	v_mfma_f32_16x16x32_bf16 v[66:69], v[200:203], v[184:187], v[66:69]
	v_mfma_f32_16x16x32_bf16 v[110:113], v[196:199], v[164:167], v[110:113]
	v_mfma_f32_16x16x32_bf16 v[102:105], v[204:207], v[164:167], v[102:105]
	v_mfma_f32_16x16x32_bf16 v[94:97], v[196:199], v[172:175], v[94:97]
	v_mfma_f32_16x16x32_bf16 v[86:89], v[204:207], v[172:175], v[86:89]
	v_mfma_f32_16x16x32_bf16 v[78:81], v[196:199], v[180:183], v[78:81]
	v_mfma_f32_16x16x32_bf16 v[74:77], v[204:207], v[180:183], v[74:77]
	v_mfma_f32_16x16x32_bf16 v[70:73], v[196:199], v[188:191], v[70:73]
	v_mfma_f32_16x16x32_bf16 v[66:69], v[204:207], v[188:191], v[66:69]
	s_barrier
	s_add_i32 s38, s38, s63
	v_lshl_add_u64 v[156:157], s[54:55], 0, v[0:1]
	s_mov_b32 m0, s38
	v_lshl_add_u64 v[210:211], s[54:55], 0, v[130:131]
	global_load_lds_dwordx4 v[156:157], off
	s_add_i32 m0, s38, 0x2000
	s_nop 0
	global_load_lds_dwordx4 v[210:211], off
	s_mov_b32 m0, s25
	v_lshl_add_u64 v[212:213], s[56:57], 0, v[0:1]
	global_load_lds_dwordx4 v[212:213], off
	v_lshl_add_u64 v[214:215], s[56:57], 0, v[130:131]
	s_mov_b32 m0, s27
	s_nop 0
	global_load_lds_dwordx4 v[214:215], off
	ds_read_b128 v[160:163], v139 offset:16384
	ds_read_b128 v[164:167], v139 offset:17408
	ds_read_b128 v[168:171], v139 offset:18432
	ds_read_b128 v[172:175], v139 offset:19456
	ds_read_b128 v[176:179], v139 offset:20480
	ds_read_b128 v[180:183], v139 offset:21504
	ds_read_b128 v[184:187], v139 offset:22528
	ds_read_b128 v[188:191], v139 offset:23552
	s_waitcnt vmcnt(4)
	s_waitcnt lgkmcnt(0)
	s_barrier
; #define PG8_STAGE(bufoff, gbase, voff) do { _Pragma("unroll") for (int _i = 0; _i < 2; ++_i) \
;         __builtin_amdgcn_global_load_lds((const unsigned*)((const char*)(gbase) + (voff)[_i]), (LAS unsigned*)(lds + (bufoff) + ldsw + _i * 8192), 16, 0, 0); } while (0)
; #define PG8_LDA(dst, b, h) do { _Pragma("unroll") for (int m = 0; m < 4; ++m) _Pragma("unroll") for (int k = 0; k < 2; ++k) dst[m][k] = *(const LAS bf16x8*)(lds + PG8_SA(b, h) + aoff + m * 2048 + k * 1024); } while (0)
; #define PG8_MMA(ai, bj, At, Bt) do { __builtin_amdgcn_s_setprio(1); _Pragma("unroll") for (int m = 0; m < 4; ++m) _Pragma("unroll") for (int n = 0; n < 2; ++n) _Pragma("unroll") for (int k = 0; k < 2; ++k) \
;         acc[ai][bj][m][n] = __builtin_amdgcn_mfma_f32_16x16x32_bf16(Bt[n][k], At[m][k], acc[ai][bj][m][n], 0, 0, 0); __builtin_amdgcn_s_setprio(0); } while (0)
; #define PG8_WAIT_V(n) asm volatile("s_waitcnt vmcnt(" #n ")" ::: "memory")
; #define PG8_WAIT_L(n) asm volatile("s_waitcnt lgkmcnt(" #n ")" ::: "memory")
; #define PG8_BAR __builtin_amdgcn_s_barrier()
; #define PG8_SCHED __builtin_amdgcn_sched_barrier(0)
; template <class Epi, class Sched>
; __device__ __forceinline__ void gemm_phase(LAS unsigned char* lds, const Gemm g, const Sched& S, const Epi& E) {
;     ...
;             PG8_BAR; PG8_WAIT_L(0); PG8_MMA(0, 1, At, B1); PG8_BAR;
;             PG8_LDA(At, 0, 1); PG8_STAGE(PG8_SA(0, 0), a2, voffA);
;             PG8_BAR; PG8_WAIT_L(0); PG8_MMA(1, 0, At, B0); PG8_BAR; PG8_SCHED;
;             PG8_STAGE(PG8_SB(0, 1), b2 + hstep, voffB);
;             PG8_WAIT_V(6); PG8_BAR; PG8_MMA(1, 1, At, B1); PG8_BAR;
	v_mfma_f32_16x16x32_bf16 v[62:65], v[140:143], v[160:163], v[62:65]
	v_mfma_f32_16x16x32_bf16 v[58:61], v[148:151], v[160:163], v[58:61]
	v_mfma_f32_16x16x32_bf16 v[54:57], v[140:143], v[168:171], v[54:57]
	v_mfma_f32_16x16x32_bf16 v[50:53], v[148:151], v[168:171], v[50:53]
	v_mfma_f32_16x16x32_bf16 v[38:41], v[140:143], v[176:179], v[38:41]
	v_mfma_f32_16x16x32_bf16 v[34:37], v[148:151], v[176:179], v[34:37]
	v_mfma_f32_16x16x32_bf16 v[22:25], v[140:143], v[184:187], v[22:25]
	v_mfma_f32_16x16x32_bf16 v[18:21], v[148:151], v[184:187], v[18:21]
	v_mfma_f32_16x16x32_bf16 v[62:65], v[144:147], v[164:167], v[62:65]
	v_mfma_f32_16x16x32_bf16 v[58:61], v[152:155], v[164:167], v[58:61]
	v_mfma_f32_16x16x32_bf16 v[54:57], v[144:147], v[172:175], v[54:57]
	v_mfma_f32_16x16x32_bf16 v[50:53], v[152:155], v[172:175], v[50:53]
	v_mfma_f32_16x16x32_bf16 v[38:41], v[144:147], v[180:183], v[38:41]
	v_mfma_f32_16x16x32_bf16 v[34:37], v[152:155], v[180:183], v[34:37]
	v_mfma_f32_16x16x32_bf16 v[22:25], v[144:147], v[188:191], v[22:25]
	v_mfma_f32_16x16x32_bf16 v[18:21], v[152:155], v[188:191], v[18:21]
	v_mfma_f32_16x16x32_bf16 v[46:49], v[192:195], v[160:163], v[46:49]
	v_mfma_f32_16x16x32_bf16 v[42:45], v[200:203], v[160:163], v[42:45]
	v_mfma_f32_16x16x32_bf16 v[30:33], v[192:195], v[168:171], v[30:33]
	v_mfma_f32_16x16x32_bf16 v[26:29], v[200:203], v[168:171], v[26:29]
	v_mfma_f32_16x16x32_bf16 v[14:17], v[192:195], v[176:179], v[14:17]
	v_mfma_f32_16x16x32_bf16 v[10:13], v[200:203], v[176:179], v[10:13]
	v_mfma_f32_16x16x32_bf16 v[6:9], v[192:195], v[184:187], v[6:9]
	v_mfma_f32_16x16x32_bf16 v[2:5], v[200:203], v[184:187], v[2:5]
	v_mfma_f32_16x16x32_bf16 v[46:49], v[196:199], v[164:167], v[46:49]
	v_mfma_f32_16x16x32_bf16 v[42:45], v[204:207], v[164:167], v[42:45]
	v_mfma_f32_16x16x32_bf16 v[30:33], v[196:199], v[172:175], v[30:33]
	v_mfma_f32_16x16x32_bf16 v[26:29], v[204:207], v[172:175], v[26:29]
	v_mfma_f32_16x16x32_bf16 v[14:17], v[196:199], v[180:183], v[14:17]
	v_mfma_f32_16x16x32_bf16 v[10:13], v[204:207], v[180:183], v[10:13]
	v_mfma_f32_16x16x32_bf16 v[6:9], v[196:199], v[188:191], v[6:9]
	v_mfma_f32_16x16x32_bf16 v[2:5], v[204:207], v[188:191], v[2:5]
	s_barrier
	s_add_u32 s38, s54, 0x200000
	s_addc_u32 s39, s55, 0
	s_add_i32 s50, s50, s63
	v_lshl_add_u64 v[140:141], s[38:39], 0, v[0:1]
	s_mov_b32 m0, s50
	s_nop 0
	global_load_lds_dwordx4 v[140:141], off
	v_lshl_add_u64 v[140:141], s[38:39], 0, v[130:131]
	s_add_i32 m0, s50, 0x2000
	s_nop 0
	global_load_lds_dwordx4 v[140:141], off
	s_add_u32 s38, s56, 0x200000
	s_addc_u32 s39, s57, 0
	s_mov_b32 m0, s64
	v_lshl_add_u64 v[192:193], s[38:39], 0, v[0:1]
	global_load_lds_dwordx4 v[192:193], off
	v_lshl_add_u64 v[192:193], s[38:39], 0, v[130:131]
	s_mov_b32 m0, s65
	s_nop 0
	global_load_lds_dwordx4 v[192:193], off
	s_add_i32 s50, 0, 0x18000
	v_add_u32_e32 v152, s50, v137
	ds_read_b128 v[140:143], v152
	ds_read_b128 v[144:147], v152 offset:1024
	ds_read_b128 v[148:151], v152 offset:2048
	ds_read_b128 v[152:155], v152 offset:3072
	ds_read_b128 v[160:163], v139 offset:32768
	ds_read_b128 v[164:167], v139 offset:33792
	ds_read_b128 v[168:171], v139 offset:34816
	ds_read_b128 v[172:175], v139 offset:35840
	ds_read_b128 v[176:179], v139 offset:36864
	ds_read_b128 v[180:183], v139 offset:37888
	ds_read_b128 v[184:187], v139 offset:38912
	ds_read_b128 v[188:191], v139 offset:39936
	s_add_i32 s51, 0, 0x1c000
	v_add_u32_e32 v204, s51, v137
	ds_read_b128 v[192:195], v204
	ds_read_b128 v[196:199], v204 offset:1024
	ds_read_b128 v[200:203], v204 offset:2048
	ds_read_b128 v[204:207], v204 offset:3072
	s_waitcnt lgkmcnt(4)
	s_barrier
	s_waitcnt lgkmcnt(0)
	v_mfma_f32_16x16x32_bf16 v[126:129], v[140:143], v[160:163], v[126:129]
	v_mfma_f32_16x16x32_bf16 v[122:125], v[148:151], v[160:163], v[122:125]
	v_mfma_f32_16x16x32_bf16 v[118:121], v[140:143], v[168:171], v[118:121]
	v_mfma_f32_16x16x32_bf16 v[114:117], v[148:151], v[168:171], v[114:117]
	v_mfma_f32_16x16x32_bf16 v[106:109], v[140:143], v[176:179], v[106:109]
	v_mfma_f32_16x16x32_bf16 v[98:101], v[148:151], v[176:179], v[98:101]
	v_mfma_f32_16x16x32_bf16 v[90:93], v[140:143], v[184:187], v[90:93]
	v_mfma_f32_16x16x32_bf16 v[82:85], v[148:151], v[184:187], v[82:85]
	v_mfma_f32_16x16x32_bf16 v[126:129], v[144:147], v[164:167], v[126:129]
	v_mfma_f32_16x16x32_bf16 v[122:125], v[152:155], v[164:167], v[122:125]
	v_mfma_f32_16x16x32_bf16 v[118:121], v[144:147], v[172:175], v[118:121]
	v_mfma_f32_16x16x32_bf16 v[114:117], v[152:155], v[172:175], v[114:117]
	v_mfma_f32_16x16x32_bf16 v[106:109], v[144:147], v[180:183], v[106:109]
	v_mfma_f32_16x16x32_bf16 v[98:101], v[152:155], v[180:183], v[98:101]
	v_mfma_f32_16x16x32_bf16 v[90:93], v[144:147], v[188:191], v[90:93]
	v_mfma_f32_16x16x32_bf16 v[82:85], v[152:155], v[188:191], v[82:85]
	v_mfma_f32_16x16x32_bf16 v[110:113], v[192:195], v[160:163], v[110:113]
	v_mfma_f32_16x16x32_bf16 v[102:105], v[200:203], v[160:163], v[102:105]
	v_mfma_f32_16x16x32_bf16 v[94:97], v[192:195], v[168:171], v[94:97]
	v_mfma_f32_16x16x32_bf16 v[86:89], v[200:203], v[168:171], v[86:89]
	v_mfma_f32_16x16x32_bf16 v[78:81], v[192:195], v[176:179], v[78:81]
	v_mfma_f32_16x16x32_bf16 v[74:77], v[200:203], v[176:179], v[74:77]
	v_mfma_f32_16x16x32_bf16 v[70:73], v[192:195], v[184:187], v[70:73]
	v_mfma_f32_16x16x32_bf16 v[66:69], v[200:203], v[184:187], v[66:69]
	v_mfma_f32_16x16x32_bf16 v[110:113], v[196:199], v[164:167], v[110:113]
	v_mfma_f32_16x16x32_bf16 v[102:105], v[204:207], v[164:167], v[102:105]
	v_mfma_f32_16x16x32_bf16 v[94:97], v[196:199], v[172:175], v[94:97]
	v_mfma_f32_16x16x32_bf16 v[86:89], v[204:207], v[172:175], v[86:89]
	v_mfma_f32_16x16x32_bf16 v[78:81], v[196:199], v[180:183], v[78:81]
	v_mfma_f32_16x16x32_bf16 v[74:77], v[204:207], v[180:183], v[74:77]
	v_mfma_f32_16x16x32_bf16 v[70:73], v[196:199], v[188:191], v[70:73]
	v_mfma_f32_16x16x32_bf16 v[66:69], v[204:207], v[188:191], v[66:69]
	s_barrier
; #define PG8_STAGE(bufoff, gbase, voff) do { _Pragma("unroll") for (int _i = 0; _i < 2; ++_i) \
;         __builtin_amdgcn_global_load_lds((const unsigned*)((const char*)(gbase) + (voff)[_i]), (LAS unsigned*)(lds + (bufoff) + ldsw + _i * 8192), 16, 0, 0); } while (0)
; #define PG8_LDA(dst, b, h) do { _Pragma("unroll") for (int m = 0; m < 4; ++m) _Pragma("unroll") for (int k = 0; k < 2; ++k) dst[m][k] = *(const LAS bf16x8*)(lds + PG8_SA(b, h) + aoff + m * 2048 + k * 1024); } while (0)
; #define PG8_LDB(dst, b, h) do { _Pragma("unroll") for (int n = 0; n < 2; ++n) _Pragma("unroll") for (int k = 0; k < 2; ++k) dst[n][k] = *(const LAS bf16x8*)(lds + PG8_SB(b, h) + boff + n * 2048 + k * 1024); } while (0)
; #define PG8_WAIT_V(n) asm volatile("s_waitcnt vmcnt(" #n ")" ::: "memory")
; #define PG8_BAR __builtin_amdgcn_s_barrier()
;     __device__ __forceinline__ void operator()(const f32x4 (&acc)[2][2][4][2], const Unit& u, int wr, int wc, int fr, int fq) const {
;         const int row0 = u.pm * BM + wr * 64 + fr, col0 = u.pn * BM + wc * 32 + 4 * fq;
;         float* base = part + (size_t)u.ks * Mp * ldc;
; #pragma unroll
;         for (int ai = 0; ai < 2; ++ai)
; #pragma unroll
;             for (int m = 0; m < 4; ++m) { float* rowp = base + (size_t)(row0 + ai * HALF + m * 16) * ldc + col0;
; #pragma unroll
;                 for (int bj = 0; bj < 2; ++bj)
; #pragma unroll
;                     for (int n = 0; n < 2; ++n) *(f32x4*)(rowp + bj * HALF + n * 16) = acc[ai][bj][m][n]; }
;     }
; template <class Epi, class Sched>
; __device__ __forceinline__ void gemm_phase(LAS unsigned char* lds, const Gemm g, const Sched& S, const Epi& E) {
;     ...
;             PG8_WAIT_V(6); PG8_BAR; PG8_MMA(1, 1, At, B1); PG8_BAR;
;             PG8_LDB(B0, 1, 0); PG8_SCHED; PG8_LDA(At, 1, 0); PG8_STAGE(PG8_SA(0, 1), a2 + hstep, voffA);
;             PG8_WAIT_L(8); PG8_BAR; PG8_WAIT_L(0); PG8_MMA(0, 0, At, B0); PG8_BAR; PG8_SCHED;
;             PG8_LDB(B1, 1, 1); PG8_STAGE(PG8_SB(1, 0), b3, voffB);
;             PG8_BAR; PG8_WAIT_L(0); PG8_MMA(0, 1, At, B1); PG8_BAR;
;             PG8_LDA(At, 1, 1); PG8_STAGE(PG8_SA(1, 0), a3, voffA);
;             PG8_BAR; PG8_WAIT_L(0); PG8_MMA(1, 0, At, B0); PG8_BAR; PG8_SCHED;
;             PG8_STAGE(PG8_SB(1, 1), b3 + hstep, voffB);
;             PG8_WAIT_V(6); PG8_BAR; PG8_MMA(1, 1, At, B1); PG8_BAR;
;         }
;         E(acc, cur, wr, wc, fr, fq);
	s_add_i32 s38, s50, s63
	v_lshl_add_u64 v[156:157], v[156:157], 0, s[36:37]
	s_mov_b32 m0, s38
	s_nop 0
	global_load_lds_dwordx4 v[156:157], off
	v_lshl_add_u64 v[156:157], v[210:211], 0, s[36:37]
	s_add_i32 m0, s38, 0x2000
	s_nop 0
	global_load_lds_dwordx4 v[156:157], off
	s_mov_b32 m0, s66
	v_lshl_add_u64 v[156:157], v[212:213], 0, s[36:37]
	global_load_lds_dwordx4 v[156:157], off
	v_lshl_add_u64 v[156:157], v[214:215], 0, s[36:37]
	s_mov_b32 m0, s67
	s_nop 0
	global_load_lds_dwordx4 v[156:157], off
	ds_read_b128 v[160:163], v139 offset:49152
	ds_read_b128 v[164:167], v139 offset:50176
	ds_read_b128 v[168:171], v139 offset:51200
	ds_read_b128 v[172:175], v139 offset:52224
	ds_read_b128 v[176:179], v139 offset:53248
	ds_read_b128 v[180:183], v139 offset:54272
	ds_read_b128 v[184:187], v139 offset:55296
	ds_read_b128 v[188:191], v139 offset:56320
	s_waitcnt vmcnt(4)
	s_waitcnt lgkmcnt(0)
	s_barrier
	v_mfma_f32_16x16x32_bf16 v[62:65], v[140:143], v[160:163], v[62:65]
	v_mfma_f32_16x16x32_bf16 v[58:61], v[148:151], v[160:163], v[58:61]
	v_mfma_f32_16x16x32_bf16 v[54:57], v[140:143], v[168:171], v[54:57]
	v_mfma_f32_16x16x32_bf16 v[50:53], v[148:151], v[168:171], v[50:53]
	v_mfma_f32_16x16x32_bf16 v[38:41], v[140:143], v[176:179], v[38:41]
	v_mfma_f32_16x16x32_bf16 v[34:37], v[148:151], v[176:179], v[34:37]
	v_mfma_f32_16x16x32_bf16 v[22:25], v[140:143], v[184:187], v[22:25]
	v_mfma_f32_16x16x32_bf16 v[18:21], v[148:151], v[184:187], v[18:21]
	v_mfma_f32_16x16x32_bf16 v[62:65], v[144:147], v[164:167], v[62:65]
	v_mfma_f32_16x16x32_bf16 v[58:61], v[152:155], v[164:167], v[58:61]
	v_mfma_f32_16x16x32_bf16 v[54:57], v[144:147], v[172:175], v[54:57]
	v_mfma_f32_16x16x32_bf16 v[50:53], v[152:155], v[172:175], v[50:53]
	v_mfma_f32_16x16x32_bf16 v[38:41], v[144:147], v[180:183], v[38:41]
	v_mfma_f32_16x16x32_bf16 v[34:37], v[152:155], v[180:183], v[34:37]
	v_mfma_f32_16x16x32_bf16 v[22:25], v[144:147], v[188:191], v[22:25]
	v_mfma_f32_16x16x32_bf16 v[18:21], v[152:155], v[188:191], v[18:21]
	v_mfma_f32_16x16x32_bf16 v[46:49], v[192:195], v[160:163], v[46:49]
	v_mfma_f32_16x16x32_bf16 v[42:45], v[200:203], v[160:163], v[42:45]
	v_mfma_f32_16x16x32_bf16 v[30:33], v[192:195], v[168:171], v[30:33]
	v_mfma_f32_16x16x32_bf16 v[26:29], v[200:203], v[168:171], v[26:29]
	v_mfma_f32_16x16x32_bf16 v[14:17], v[192:195], v[176:179], v[14:17]
	v_mfma_f32_16x16x32_bf16 v[10:13], v[200:203], v[176:179], v[10:13]
	v_mfma_f32_16x16x32_bf16 v[6:9], v[192:195], v[184:187], v[6:9]
	v_mfma_f32_16x16x32_bf16 v[2:5], v[200:203], v[184:187], v[2:5]
	v_mfma_f32_16x16x32_bf16 v[46:49], v[196:199], v[164:167], v[46:49]
	v_mfma_f32_16x16x32_bf16 v[42:45], v[204:207], v[164:167], v[42:45]
	v_mfma_f32_16x16x32_bf16 v[30:33], v[196:199], v[172:175], v[30:33]
	v_mfma_f32_16x16x32_bf16 v[26:29], v[204:207], v[172:175], v[26:29]
	v_mfma_f32_16x16x32_bf16 v[14:17], v[196:199], v[180:183], v[14:17]
	v_mfma_f32_16x16x32_bf16 v[10:13], v[204:207], v[180:183], v[10:13]
	v_mfma_f32_16x16x32_bf16 v[6:9], v[196:199], v[188:191], v[6:9]
	v_mfma_f32_16x16x32_bf16 v[2:5], v[204:207], v[188:191], v[2:5]
	s_add_i32 s71, s71, 2
	s_add_u32 s69, s69, 0x100
	s_addc_u32 s70, s70, 0
	s_cmp_gt_u32 s71, 29
	s_mov_b64 s[50:51], s[52:53]
	s_barrier
	s_cbranch_scc0 .LBB0_58
	s_ashr_i32 s11, s10, 31
	s_lshl_b64 s[10:11], s[10:11], 24
	v_lshl_or_b32 v140, s26, 8, v138
	s_add_u32 s10, s8, s10
	v_lshl_add_u32 v142, s24, 8, v136
	s_addc_u32 s11, s9, s11
	v_ashrrev_i32_e32 v141, 31, v140
	v_ashrrev_i32_e32 v143, 31, v142
	v_lshl_add_u64 v[140:141], v[140:141], 2, s[10:11]
	v_lshlrev_b64 v[144:145], 13, v[142:143]
	v_lshl_add_u64 v[144:145], v[140:141], 0, v[144:145]
	global_store_dwordx4 v[144:145], v[126:129], off
	global_store_dwordx4 v[144:145], v[122:125], off offset:64
	global_store_dwordx4 v[144:145], v[110:113], off offset:512
	global_store_dwordx4 v[144:145], v[102:105], off offset:576
	s_mov_b64 s[10:11], 0x100000
	s_mov_b32 s26, s40
	v_or_b32_e32 v102, 16, v142
	v_ashrrev_i32_e32 v103, 31, v102
	v_lshlrev_b64 v[102:103], 13, v[102:103]
	v_lshl_add_u64 v[102:103], v[140:141], 0, v[102:103]
	global_store_dwordx4 v[102:103], v[118:121], off
	global_store_dwordx4 v[102:103], v[114:117], off offset:64
	global_store_dwordx4 v[102:103], v[94:97], off offset:512
	global_store_dwordx4 v[102:103], v[86:89], off offset:576
	s_mov_b32 s24, s42
	s_mov_b64 s[52:53], s[48:49]
	v_or_b32_e32 v86, 32, v142
	v_ashrrev_i32_e32 v87, 31, v86
	v_lshlrev_b64 v[86:87], 13, v[86:87]
	v_lshl_add_u64 v[86:87], v[140:141], 0, v[86:87]
	global_store_dwordx4 v[86:87], v[106:109], off
	global_store_dwordx4 v[86:87], v[98:101], off offset:64
	global_store_dwordx4 v[86:87], v[78:81], off offset:512
	global_store_dwordx4 v[86:87], v[74:77], off offset:576
	s_mov_b64 s[50:51], s[46:47]
	s_nop 0
	v_or_b32_e32 v74, 48, v142
	v_ashrrev_i32_e32 v75, 31, v74
	v_lshlrev_b64 v[74:75], 13, v[74:75]
	v_lshl_add_u64 v[74:75], v[140:141], 0, v[74:75]
	global_store_dwordx4 v[74:75], v[90:93], off
	global_store_dwordx4 v[74:75], v[82:85], off offset:64
	global_store_dwordx4 v[74:75], v[70:73], off offset:512
	global_store_dwordx4 v[74:75], v[66:69], off offset:576
	s_nop 1
	v_add_co_u32_e32 v68, vcc, s93, v144
	v_lshl_add_u64 v[66:67], v[144:145], 0, s[10:11]
	s_nop 0
	v_addc_co_u32_e32 v69, vcc, 0, v145, vcc
	s_mov_b64 s[10:11], 0x120000
	global_store_dwordx4 v[68:69], v[62:65], off
	global_store_dwordx4 v[66:67], v[58:61], off offset:64
	global_store_dwordx4 v[66:67], v[46:49], off offset:512
	global_store_dwordx4 v[66:67], v[42:45], off offset:576
	s_nop 1
	v_lshl_add_u64 v[42:43], v[144:145], 0, s[10:11]
	s_mov_b32 s10, 0x120000
	v_add_co_u32_e32 v44, vcc, s10, v144
	s_mov_b64 s[10:11], 0x140000
	s_nop 0
	v_addc_co_u32_e32 v45, vcc, 0, v145, vcc
	global_store_dwordx4 v[44:45], v[54:57], off
	global_store_dwordx4 v[42:43], v[50:53], off offset:64
	global_store_dwordx4 v[42:43], v[30:33], off offset:512
	global_store_dwordx4 v[42:43], v[26:29], off offset:576
	s_nop 1
	v_lshl_add_u64 v[26:27], v[144:145], 0, s[10:11]
	s_mov_b32 s10, 0x140000
	v_add_co_u32_e32 v28, vcc, s10, v144
	s_mov_b64 s[10:11], 0x160000
	s_nop 0
	v_addc_co_u32_e32 v29, vcc, 0, v145, vcc
	global_store_dwordx4 v[28:29], v[38:41], off
	global_store_dwordx4 v[26:27], v[34:37], off offset:64
	global_store_dwordx4 v[26:27], v[14:17], off offset:512
	global_store_dwordx4 v[26:27], v[10:13], off offset:576
	s_nop 1
	v_add_co_u32_e32 v12, vcc, 0x160000, v144
	v_lshl_add_u64 v[10:11], v[144:145], 0, s[10:11]
	s_nop 0
	v_addc_co_u32_e32 v13, vcc, 0, v145, vcc
	s_and_b64 vcc, exec, s[44:45]
	s_mov_b32 s10, s28
	global_store_dwordx4 v[12:13], v[22:25], off
	global_store_dwordx4 v[10:11], v[18:21], off offset:64
	global_store_dwordx4 v[10:11], v[6:9], off offset:512
	global_store_dwordx4 v[10:11], v[2:5], off offset:576
	s_cbranch_vccz .LBB0_55
	s_waitcnt vmcnt(0)
	s_cmpk_gt_u32 s60, 0xff
	s_cbranch_scc1 .LBB0_62
	s_barrier

; #define PG8_STAGE(bufoff, gbase, voff) do { _Pragma("unroll") for (int _i = 0; _i < 2; ++_i) \
;         __builtin_amdgcn_global_load_lds((const unsigned*)((const char*)(gbase) + (voff)[_i]), (LAS unsigned*)(lds + (bufoff) + ldsw + _i * 8192), 16, 0, 0); } while (0)
; #define PG8_LDA(dst, b, h) do { _Pragma("unroll") for (int m = 0; m < 4; ++m) _Pragma("unroll") for (int k = 0; k < 2; ++k) dst[m][k] = *(const LAS bf16x8*)(lds + PG8_SA(b, h) + aoff + m * 2048 + k * 1024); } while (0)
; #define PG8_LDB(dst, b, h) do { _Pragma("unroll") for (int n = 0; n < 2; ++n) _Pragma("unroll") for (int k = 0; k < 2; ++k) dst[n][k] = *(const LAS bf16x8*)(lds + PG8_SB(b, h) + boff + n * 2048 + k * 1024); } while (0)
; #define PG8_MMA(ai, bj, At, Bt) do { __builtin_amdgcn_s_setprio(1); _Pragma("unroll") for (int m = 0; m < 4; ++m) _Pragma("unroll") for (int n = 0; n < 2; ++n) _Pragma("unroll") for (int k = 0; k < 2; ++k) \
;         acc[ai][bj][m][n] = __builtin_amdgcn_mfma_f32_16x16x32_bf16(Bt[n][k], At[m][k], acc[ai][bj][m][n], 0, 0, 0); __builtin_amdgcn_s_setprio(0); } while (0)
; #define PG8_WAIT_L(n) asm volatile("s_waitcnt lgkmcnt(" #n ")" ::: "memory")
; #define PG8_BAR __builtin_amdgcn_s_barrier()
; #define PG8_SCHED __builtin_amdgcn_sched_barrier(0)
; template <class Epi, class Sched>
; __device__ __forceinline__ void gemm_phase(LAS unsigned char* lds, const Gemm g, const Sched& S, const Epi& E) {
;     ...
;         for (int t = 0; t < nt; t += 2) {
;             const bool last = (t == nt - 2);
;             const char* a1 = cA + (size_t)(t + 1) * kstep;
;             const char* a2 = last ? nA : cA + (size_t)(t + 2) * kstep; const char* b2 = last ? nB : cB + (size_t)(t + 2) * kstep;
;             const char* a3 = a2 + kstep; const char* b3 = b2 + kstep;
;             PG8_LDB(B0, 0, 0); PG8_SCHED; PG8_LDA(At, 0, 0); PG8_STAGE(PG8_SA(1, 1), a1 + hstep, voffA);
;             PG8_WAIT_L(8); PG8_BAR; PG8_WAIT_L(0); PG8_MMA(0, 0, At, B0); PG8_BAR; PG8_SCHED;
;             PG8_LDB(B1, 0, 1); PG8_STAGE(PG8_SB(0, 0), b2, voffB);
;             PG8_BAR; PG8_WAIT_L(0); PG8_MMA(0, 1, At, B1); PG8_BAR;
;             PG8_LDA(At, 0, 1); PG8_STAGE(PG8_SA(0, 0), a2, voffA);
;             PG8_BAR; PG8_WAIT_L(0); PG8_MMA(1, 0, At, B0); PG8_BAR; PG8_SCHED;
.LBB0_73:
	s_add_u32 s100, s71, 0x7ff80
	s_addc_u32 s101, s72, 0
	v_lshl_add_u64 v[140:141], s[100:101], 0, v[0:1]
	s_add_i32 m0, s56, 0x1c000
	s_nop 0
	global_load_lds_dwordx4 v[140:141], off
	v_lshl_add_u64 v[140:141], s[100:101], 0, v[130:131]
	s_add_i32 m0, s56, 0x1e000
	s_nop 0
	global_load_lds_dwordx4 v[140:141], off
	s_add_u32 s38, s46, 0xfff80080
	s_addc_u32 s39, s47, -1
	s_cmp_eq_u32 s73, 28
	s_cselect_b32 s51, s29, s39
	s_cselect_b32 s50, s69, s38
	s_cselect_b32 s49, s27, s72
	s_cselect_b32 s48, s70, s71
	v_lshl_add_u64 v[140:141], s[46:47], 0, v[138:139]
	s_add_i32 m0, s9, 0xc000
	s_nop 0
	global_load_lds_dwordx4 v[140:141], off
	v_lshl_add_u64 v[140:141], s[46:47], 0, v[136:137]
	s_add_i32 m0, s9, 0xe000
	s_nop 0
	global_load_lds_dwordx4 v[140:141], off
	s_add_i32 s74, 0, 0x10000
	v_add_u32_e32 v140, s74, v143
	ds_read_b128 v[146:149], v140
	ds_read_b128 v[150:153], v140 offset:1024
	ds_read_b128 v[154:157], v140 offset:2048
	ds_read_b128 v[160:163], v140 offset:3072
	ds_read_b128 v[164:167], v145
	ds_read_b128 v[168:171], v145 offset:1024
	ds_read_b128 v[172:175], v145 offset:2048
	ds_read_b128 v[176:179], v145 offset:3072
	ds_read_b128 v[180:183], v145 offset:4096
	ds_read_b128 v[184:187], v145 offset:5120
	ds_read_b128 v[188:191], v145 offset:6144
	ds_read_b128 v[192:195], v145 offset:7168
	s_add_i32 s75, 0, 0x14000
	v_add_u32_e32 v140, s75, v143
	ds_read_b128 v[196:199], v140
	ds_read_b128 v[200:203], v140 offset:1024
	ds_read_b128 v[204:207], v140 offset:2048
	ds_read_b128 v[210:213], v140 offset:3072
	s_waitcnt lgkmcnt(4)
	s_barrier
	s_waitcnt lgkmcnt(0)
	v_mfma_f32_16x16x32_bf16 v[126:129], v[146:149], v[164:167], v[126:129]
	v_mfma_f32_16x16x32_bf16 v[122:125], v[154:157], v[164:167], v[122:125]
	v_mfma_f32_16x16x32_bf16 v[110:113], v[146:149], v[172:175], v[110:113]
	v_mfma_f32_16x16x32_bf16 v[106:109], v[154:157], v[172:175], v[106:109]
	v_mfma_f32_16x16x32_bf16 v[94:97], v[146:149], v[180:183], v[94:97]
	v_mfma_f32_16x16x32_bf16 v[90:93], v[154:157], v[180:183], v[90:93]
	v_mfma_f32_16x16x32_bf16 v[78:81], v[146:149], v[188:191], v[78:81]
	v_mfma_f32_16x16x32_bf16 v[74:77], v[154:157], v[188:191], v[74:77]
	v_mfma_f32_16x16x32_bf16 v[126:129], v[150:153], v[168:171], v[126:129]
	v_mfma_f32_16x16x32_bf16 v[122:125], v[160:163], v[168:171], v[122:125]
	v_mfma_f32_16x16x32_bf16 v[110:113], v[150:153], v[176:179], v[110:113]
	v_mfma_f32_16x16x32_bf16 v[106:109], v[160:163], v[176:179], v[106:109]
	v_mfma_f32_16x16x32_bf16 v[94:97], v[150:153], v[184:187], v[94:97]
	v_mfma_f32_16x16x32_bf16 v[90:93], v[160:163], v[184:187], v[90:93]
	v_mfma_f32_16x16x32_bf16 v[78:81], v[150:153], v[192:195], v[78:81]
	v_mfma_f32_16x16x32_bf16 v[74:77], v[160:163], v[192:195], v[74:77]
	v_mfma_f32_16x16x32_bf16 v[118:121], v[196:199], v[164:167], v[118:121]
	v_mfma_f32_16x16x32_bf16 v[114:117], v[204:207], v[164:167], v[114:117]
	v_mfma_f32_16x16x32_bf16 v[102:105], v[196:199], v[172:175], v[102:105]
	v_mfma_f32_16x16x32_bf16 v[98:101], v[204:207], v[172:175], v[98:101]
	v_mfma_f32_16x16x32_bf16 v[86:89], v[196:199], v[180:183], v[86:89]
	v_mfma_f32_16x16x32_bf16 v[82:85], v[204:207], v[180:183], v[82:85]
	v_mfma_f32_16x16x32_bf16 v[70:73], v[196:199], v[188:191], v[70:73]
	v_mfma_f32_16x16x32_bf16 v[66:69], v[204:207], v[188:191], v[66:69]
	v_mfma_f32_16x16x32_bf16 v[118:121], v[200:203], v[168:171], v[118:121]
	v_mfma_f32_16x16x32_bf16 v[114:117], v[210:213], v[168:171], v[114:117]
	v_mfma_f32_16x16x32_bf16 v[102:105], v[200:203], v[176:179], v[102:105]
	v_mfma_f32_16x16x32_bf16 v[98:101], v[210:213], v[176:179], v[98:101]
	v_mfma_f32_16x16x32_bf16 v[86:89], v[200:203], v[184:187], v[86:89]
	v_mfma_f32_16x16x32_bf16 v[82:85], v[210:213], v[184:187], v[82:85]
	v_mfma_f32_16x16x32_bf16 v[70:73], v[200:203], v[192:195], v[70:73]
	v_mfma_f32_16x16x32_bf16 v[66:69], v[210:213], v[192:195], v[66:69]
	s_barrier
	s_add_i32 s38, s74, s56
	v_lshl_add_u64 v[140:141], s[48:49], 0, v[0:1]
	s_mov_b32 m0, s38
	v_lshl_add_u64 v[214:215], s[48:49], 0, v[130:131]
	global_load_lds_dwordx4 v[140:141], off
	s_add_i32 m0, s38, 0x2000
	s_nop 0
	global_load_lds_dwordx4 v[214:215], off
	s_mov_b32 m0, s9
	v_lshl_add_u64 v[216:217], s[50:51], 0, v[134:135]
	global_load_lds_dwordx4 v[216:217], off
	v_lshl_add_u64 v[224:225], s[50:51], 0, v[132:133]
	s_mov_b32 m0, s60
	s_nop 0
	global_load_lds_dwordx4 v[224:225], off
	ds_read_b128 v[164:167], v145 offset:16384
	ds_read_b128 v[168:171], v145 offset:17408
	ds_read_b128 v[172:175], v145 offset:18432
	ds_read_b128 v[176:179], v145 offset:19456
	ds_read_b128 v[180:183], v145 offset:20480
	ds_read_b128 v[184:187], v145 offset:21504
	ds_read_b128 v[188:191], v145 offset:22528
	ds_read_b128 v[192:195], v145 offset:23552
	s_waitcnt vmcnt(4)
	s_waitcnt lgkmcnt(0)
	s_barrier
; #define PG8_STAGE(bufoff, gbase, voff) do { _Pragma("unroll") for (int _i = 0; _i < 2; ++_i) \
;         __builtin_amdgcn_global_load_lds((const unsigned*)((const char*)(gbase) + (voff)[_i]), (LAS unsigned*)(lds + (bufoff) + ldsw + _i * 8192), 16, 0, 0); } while (0)
; #define PG8_LDA(dst, b, h) do { _Pragma("unroll") for (int m = 0; m < 4; ++m) _Pragma("unroll") for (int k = 0; k < 2; ++k) dst[m][k] = *(const LAS bf16x8*)(lds + PG8_SA(b, h) + aoff + m * 2048 + k * 1024); } while (0)
; #define PG8_MMA(ai, bj, At, Bt) do { __builtin_amdgcn_s_setprio(1); _Pragma("unroll") for (int m = 0; m < 4; ++m) _Pragma("unroll") for (int n = 0; n < 2; ++n) _Pragma("unroll") for (int k = 0; k < 2; ++k) \
;         acc[ai][bj][m][n] = __builtin_amdgcn_mfma_f32_16x16x32_bf16(Bt[n][k], At[m][k], acc[ai][bj][m][n], 0, 0, 0); __builtin_amdgcn_s_setprio(0); } while (0)
; #define PG8_WAIT_V(n) asm volatile("s_waitcnt vmcnt(" #n ")" ::: "memory")
; #define PG8_WAIT_L(n) asm volatile("s_waitcnt lgkmcnt(" #n ")" ::: "memory")
; #define PG8_BAR __builtin_amdgcn_s_barrier()
; #define PG8_SCHED __builtin_amdgcn_sched_barrier(0)
; template <class Epi, class Sched>
; __device__ __forceinline__ void gemm_phase(LAS unsigned char* lds, const Gemm g, const Sched& S, const Epi& E) {
;     ...
;             PG8_BAR; PG8_WAIT_L(0); PG8_MMA(0, 1, At, B1); PG8_BAR;
;             PG8_LDA(At, 0, 1); PG8_STAGE(PG8_SA(0, 0), a2, voffA);
;             PG8_BAR; PG8_WAIT_L(0); PG8_MMA(1, 0, At, B0); PG8_BAR; PG8_SCHED;
;             PG8_STAGE(PG8_SB(0, 1), b2 + hstep, voffB);
;             PG8_WAIT_V(6); PG8_BAR; PG8_MMA(1, 1, At, B1); PG8_BAR;
	v_mfma_f32_16x16x32_bf16 v[62:65], v[146:149], v[164:167], v[62:65]
	v_mfma_f32_16x16x32_bf16 v[58:61], v[154:157], v[164:167], v[58:61]
	v_mfma_f32_16x16x32_bf16 v[46:49], v[146:149], v[172:175], v[46:49]
	v_mfma_f32_16x16x32_bf16 v[42:45], v[154:157], v[172:175], v[42:45]
	v_mfma_f32_16x16x32_bf16 v[30:33], v[146:149], v[180:183], v[30:33]
	v_mfma_f32_16x16x32_bf16 v[26:29], v[154:157], v[180:183], v[26:29]
	v_mfma_f32_16x16x32_bf16 v[14:17], v[146:149], v[188:191], v[14:17]
	v_mfma_f32_16x16x32_bf16 v[10:13], v[154:157], v[188:191], v[10:13]
	v_mfma_f32_16x16x32_bf16 v[62:65], v[150:153], v[168:171], v[62:65]
	v_mfma_f32_16x16x32_bf16 v[58:61], v[160:163], v[168:171], v[58:61]
	v_mfma_f32_16x16x32_bf16 v[46:49], v[150:153], v[176:179], v[46:49]
	v_mfma_f32_16x16x32_bf16 v[42:45], v[160:163], v[176:179], v[42:45]
	v_mfma_f32_16x16x32_bf16 v[30:33], v[150:153], v[184:187], v[30:33]
	v_mfma_f32_16x16x32_bf16 v[26:29], v[160:163], v[184:187], v[26:29]
	v_mfma_f32_16x16x32_bf16 v[14:17], v[150:153], v[192:195], v[14:17]
	v_mfma_f32_16x16x32_bf16 v[10:13], v[160:163], v[192:195], v[10:13]
	v_mfma_f32_16x16x32_bf16 v[54:57], v[196:199], v[164:167], v[54:57]
	v_mfma_f32_16x16x32_bf16 v[50:53], v[204:207], v[164:167], v[50:53]
	v_mfma_f32_16x16x32_bf16 v[38:41], v[196:199], v[172:175], v[38:41]
	v_mfma_f32_16x16x32_bf16 v[34:37], v[204:207], v[172:175], v[34:37]
	v_mfma_f32_16x16x32_bf16 v[22:25], v[196:199], v[180:183], v[22:25]
	v_mfma_f32_16x16x32_bf16 v[18:21], v[204:207], v[180:183], v[18:21]
	v_mfma_f32_16x16x32_bf16 v[6:9], v[196:199], v[188:191], v[6:9]
	v_mfma_f32_16x16x32_bf16 v[2:5], v[204:207], v[188:191], v[2:5]
	v_mfma_f32_16x16x32_bf16 v[54:57], v[200:203], v[168:171], v[54:57]
	v_mfma_f32_16x16x32_bf16 v[50:53], v[210:213], v[168:171], v[50:53]
	v_mfma_f32_16x16x32_bf16 v[38:41], v[200:203], v[176:179], v[38:41]
	v_mfma_f32_16x16x32_bf16 v[34:37], v[210:213], v[176:179], v[34:37]
	v_mfma_f32_16x16x32_bf16 v[22:25], v[200:203], v[184:187], v[22:25]
	v_mfma_f32_16x16x32_bf16 v[18:21], v[210:213], v[184:187], v[18:21]
	v_mfma_f32_16x16x32_bf16 v[6:9], v[200:203], v[192:195], v[6:9]
	v_mfma_f32_16x16x32_bf16 v[2:5], v[210:213], v[192:195], v[2:5]
	s_barrier
	s_add_u32 s38, s48, 0x80000
	s_addc_u32 s39, s49, 0
	s_add_i32 s74, s75, s56
	v_lshl_add_u64 v[146:147], s[38:39], 0, v[0:1]
	s_mov_b32 m0, s74
	s_nop 0
	global_load_lds_dwordx4 v[146:147], off
	v_lshl_add_u64 v[146:147], s[38:39], 0, v[130:131]
	s_add_i32 m0, s74, 0x2000
	s_nop 0
	global_load_lds_dwordx4 v[146:147], off
	s_add_u32 s38, s50, 0x80000
	s_addc_u32 s39, s51, 0
	s_mov_b32 m0, s61
	v_lshl_add_u64 v[196:197], s[38:39], 0, v[134:135]
	global_load_lds_dwordx4 v[196:197], off
	v_lshl_add_u64 v[196:197], s[38:39], 0, v[132:133]
	s_mov_b32 m0, s62
	s_nop 0
	global_load_lds_dwordx4 v[196:197], off
	s_add_i32 s74, 0, 0x18000
	v_add_u32_e32 v160, s74, v143
	ds_read_b128 v[146:149], v160
	ds_read_b128 v[150:153], v160 offset:1024
	ds_read_b128 v[154:157], v160 offset:2048
	ds_read_b128 v[160:163], v160 offset:3072
	ds_read_b128 v[164:167], v145 offset:32768
	ds_read_b128 v[168:171], v145 offset:33792
	ds_read_b128 v[172:175], v145 offset:34816
	ds_read_b128 v[176:179], v145 offset:35840
	ds_read_b128 v[180:183], v145 offset:36864
	ds_read_b128 v[184:187], v145 offset:37888
	ds_read_b128 v[188:191], v145 offset:38912
	ds_read_b128 v[192:195], v145 offset:39936
	s_add_i32 s50, 0, 0x1c000
	v_add_u32_e32 v210, s50, v143
	ds_read_b128 v[196:199], v210
	ds_read_b128 v[200:203], v210 offset:1024
	ds_read_b128 v[204:207], v210 offset:2048
	ds_read_b128 v[210:213], v210 offset:3072
	s_waitcnt lgkmcnt(4)
	s_barrier
	s_waitcnt lgkmcnt(0)
	v_mfma_f32_16x16x32_bf16 v[126:129], v[146:149], v[164:167], v[126:129]
	v_mfma_f32_16x16x32_bf16 v[122:125], v[154:157], v[164:167], v[122:125]
	v_mfma_f32_16x16x32_bf16 v[110:113], v[146:149], v[172:175], v[110:113]
	v_mfma_f32_16x16x32_bf16 v[106:109], v[154:157], v[172:175], v[106:109]
	v_mfma_f32_16x16x32_bf16 v[94:97], v[146:149], v[180:183], v[94:97]
	v_mfma_f32_16x16x32_bf16 v[90:93], v[154:157], v[180:183], v[90:93]
	v_mfma_f32_16x16x32_bf16 v[78:81], v[146:149], v[188:191], v[78:81]
	v_mfma_f32_16x16x32_bf16 v[74:77], v[154:157], v[188:191], v[74:77]
	v_mfma_f32_16x16x32_bf16 v[126:129], v[150:153], v[168:171], v[126:129]
	v_mfma_f32_16x16x32_bf16 v[122:125], v[160:163], v[168:171], v[122:125]
	v_mfma_f32_16x16x32_bf16 v[110:113], v[150:153], v[176:179], v[110:113]
	v_mfma_f32_16x16x32_bf16 v[106:109], v[160:163], v[176:179], v[106:109]
	v_mfma_f32_16x16x32_bf16 v[94:97], v[150:153], v[184:187], v[94:97]
	v_mfma_f32_16x16x32_bf16 v[90:93], v[160:163], v[184:187], v[90:93]
	v_mfma_f32_16x16x32_bf16 v[78:81], v[150:153], v[192:195], v[78:81]
	v_mfma_f32_16x16x32_bf16 v[74:77], v[160:163], v[192:195], v[74:77]
	v_mfma_f32_16x16x32_bf16 v[118:121], v[196:199], v[164:167], v[118:121]
	v_mfma_f32_16x16x32_bf16 v[114:117], v[204:207], v[164:167], v[114:117]
	v_mfma_f32_16x16x32_bf16 v[102:105], v[196:199], v[172:175], v[102:105]
	v_mfma_f32_16x16x32_bf16 v[98:101], v[204:207], v[172:175], v[98:101]
	v_mfma_f32_16x16x32_bf16 v[86:89], v[196:199], v[180:183], v[86:89]
	v_mfma_f32_16x16x32_bf16 v[82:85], v[204:207], v[180:183], v[82:85]
	v_mfma_f32_16x16x32_bf16 v[70:73], v[196:199], v[188:191], v[70:73]
	v_mfma_f32_16x16x32_bf16 v[66:69], v[204:207], v[188:191], v[66:69]
	v_mfma_f32_16x16x32_bf16 v[118:121], v[200:203], v[168:171], v[118:121]
	v_mfma_f32_16x16x32_bf16 v[114:117], v[210:213], v[168:171], v[114:117]
	v_mfma_f32_16x16x32_bf16 v[102:105], v[200:203], v[176:179], v[102:105]
	v_mfma_f32_16x16x32_bf16 v[98:101], v[210:213], v[176:179], v[98:101]
	v_mfma_f32_16x16x32_bf16 v[86:89], v[200:203], v[184:187], v[86:89]
	v_mfma_f32_16x16x32_bf16 v[82:85], v[210:213], v[184:187], v[82:85]
	v_mfma_f32_16x16x32_bf16 v[70:73], v[200:203], v[192:195], v[70:73]
	v_mfma_f32_16x16x32_bf16 v[66:69], v[210:213], v[192:195], v[66:69]
	s_barrier
; __device__ __forceinline__ unsigned cvt_pk_bf16(float lo, float hi) { unsigned r; asm("v_cvt_pk_bf16_f32 %0, %1, %2" : "=v"(r) : "v"(lo), "v"(hi)); return r; }
; #define PG8_STAGE(bufoff, gbase, voff) do { _Pragma("unroll") for (int _i = 0; _i < 2; ++_i) \
;         __builtin_amdgcn_global_load_lds((const unsigned*)((const char*)(gbase) + (voff)[_i]), (LAS unsigned*)(lds + (bufoff) + ldsw + _i * 8192), 16, 0, 0); } while (0)
; #define PG8_LDA(dst, b, h) do { _Pragma("unroll") for (int m = 0; m < 4; ++m) _Pragma("unroll") for (int k = 0; k < 2; ++k) dst[m][k] = *(const LAS bf16x8*)(lds + PG8_SA(b, h) + aoff + m * 2048 + k * 1024); } while (0)
; #define PG8_WAIT_V(n) asm volatile("s_waitcnt vmcnt(" #n ")" ::: "memory")
; #define PG8_BAR __builtin_amdgcn_s_barrier()
;     __device__ __forceinline__ void operator()(const f32x4 (&acc)[2][2][4][2], const Unit& u, int wr, int wc, int fr, int fq) const {
;         const int row0 = u.pm * BM + wr * 64 + fr, col0 = u.pn * BM + wc * 32 + 8 * fq;
; #pragma unroll
;         for (int ai = 0; ai < 2; ++ai)
; #pragma unroll
;             for (int m = 0; m < 4; ++m) { bf16_t* rowp = O + (size_t)(row0 + ai * HALF + m * 16) * ldc + col0;
; #pragma unroll
;                 for (int bj = 0; bj < 2; ++bj) { f32x4 v0 = acc[ai][bj][m][0], v1 = acc[ai][bj][m][1];
;                     if (ACT == 1) {
; #pragma unroll
;                         for (int j = 0; j < 4; ++j) { float a = fmaxf(v0[j], 0.f), b = fmaxf(v1[j], 0.f); v0[j] = a * a; v1[j] = b * b; } }
;                     u32x4 w; w.x = cvt_pk_bf16(v0[0], v0[1]); w.y = cvt_pk_bf16(v0[2], v0[3]); w.z = cvt_pk_bf16(v1[0], v1[1]); w.w = cvt_pk_bf16(v1[2], v1[3]);
;                     if (ACT == 1) __builtin_nontemporal_store(w, (u32x4*)(rowp + bj * HALF));
;                     else *(u32x4*)(rowp + bj * HALF) = w; } }
;     }
; template <class Epi, class Sched>
; __device__ __forceinline__ void gemm_phase(LAS unsigned char* lds, const Gemm g, const Sched& S, const Epi& E) {
;     ...
;             PG8_BAR; PG8_WAIT_L(0); PG8_MMA(0, 1, At, B1); PG8_BAR;
;             PG8_LDA(At, 1, 1); PG8_STAGE(PG8_SA(1, 0), a3, voffA);
;             PG8_BAR; PG8_WAIT_L(0); PG8_MMA(1, 0, At, B0); PG8_BAR; PG8_SCHED;
;             PG8_STAGE(PG8_SB(1, 1), b3 + hstep, voffB);
;             PG8_WAIT_V(6); PG8_BAR; PG8_MMA(1, 1, At, B1); PG8_BAR;
;         }
;         E(acc, cur, wr, wc, fr, fq);
	s_add_i32 s38, s74, s56
	v_lshl_add_u64 v[140:141], v[140:141], 0, s[36:37]
	s_mov_b32 m0, s38
	s_nop 0
	global_load_lds_dwordx4 v[140:141], off
	v_lshl_add_u64 v[140:141], v[214:215], 0, s[36:37]
	s_add_i32 m0, s38, 0x2000
	s_nop 0
	global_load_lds_dwordx4 v[140:141], off
	s_mov_b32 m0, s64
	v_lshl_add_u64 v[140:141], v[216:217], 0, s[36:37]
	global_load_lds_dwordx4 v[140:141], off
	v_lshl_add_u64 v[140:141], v[224:225], 0, s[36:37]
	s_mov_b32 m0, s65
	s_nop 0
	global_load_lds_dwordx4 v[140:141], off
	ds_read_b128 v[164:167], v145 offset:49152
	ds_read_b128 v[168:171], v145 offset:50176
	ds_read_b128 v[172:175], v145 offset:51200
	ds_read_b128 v[176:179], v145 offset:52224
	ds_read_b128 v[180:183], v145 offset:53248
	ds_read_b128 v[184:187], v145 offset:54272
	ds_read_b128 v[188:191], v145 offset:55296
	ds_read_b128 v[192:195], v145 offset:56320
	s_waitcnt vmcnt(4)
	s_waitcnt lgkmcnt(0)
	s_barrier
	v_mfma_f32_16x16x32_bf16 v[62:65], v[146:149], v[164:167], v[62:65]
	v_mfma_f32_16x16x32_bf16 v[58:61], v[154:157], v[164:167], v[58:61]
	v_mfma_f32_16x16x32_bf16 v[46:49], v[146:149], v[172:175], v[46:49]
	v_mfma_f32_16x16x32_bf16 v[42:45], v[154:157], v[172:175], v[42:45]
	v_mfma_f32_16x16x32_bf16 v[30:33], v[146:149], v[180:183], v[30:33]
	v_mfma_f32_16x16x32_bf16 v[26:29], v[154:157], v[180:183], v[26:29]
	v_mfma_f32_16x16x32_bf16 v[14:17], v[146:149], v[188:191], v[14:17]
	v_mfma_f32_16x16x32_bf16 v[10:13], v[154:157], v[188:191], v[10:13]
	v_mfma_f32_16x16x32_bf16 v[62:65], v[150:153], v[168:171], v[62:65]
	v_mfma_f32_16x16x32_bf16 v[58:61], v[160:163], v[168:171], v[58:61]
	v_mfma_f32_16x16x32_bf16 v[46:49], v[150:153], v[176:179], v[46:49]
	v_mfma_f32_16x16x32_bf16 v[42:45], v[160:163], v[176:179], v[42:45]
	v_mfma_f32_16x16x32_bf16 v[30:33], v[150:153], v[184:187], v[30:33]
	v_mfma_f32_16x16x32_bf16 v[26:29], v[160:163], v[184:187], v[26:29]
	v_mfma_f32_16x16x32_bf16 v[14:17], v[150:153], v[192:195], v[14:17]
	v_mfma_f32_16x16x32_bf16 v[10:13], v[160:163], v[192:195], v[10:13]
	v_mfma_f32_16x16x32_bf16 v[54:57], v[196:199], v[164:167], v[54:57]
	v_mfma_f32_16x16x32_bf16 v[50:53], v[204:207], v[164:167], v[50:53]
	v_mfma_f32_16x16x32_bf16 v[38:41], v[196:199], v[172:175], v[38:41]
	v_mfma_f32_16x16x32_bf16 v[34:37], v[204:207], v[172:175], v[34:37]
	v_mfma_f32_16x16x32_bf16 v[22:25], v[196:199], v[180:183], v[22:25]
	v_mfma_f32_16x16x32_bf16 v[18:21], v[204:207], v[180:183], v[18:21]
	v_mfma_f32_16x16x32_bf16 v[6:9], v[196:199], v[188:191], v[6:9]
	v_mfma_f32_16x16x32_bf16 v[2:5], v[204:207], v[188:191], v[2:5]
	v_mfma_f32_16x16x32_bf16 v[54:57], v[200:203], v[168:171], v[54:57]
	v_mfma_f32_16x16x32_bf16 v[50:53], v[210:213], v[168:171], v[50:53]
	v_mfma_f32_16x16x32_bf16 v[38:41], v[200:203], v[176:179], v[38:41]
	v_mfma_f32_16x16x32_bf16 v[34:37], v[210:213], v[176:179], v[34:37]
	v_mfma_f32_16x16x32_bf16 v[22:25], v[200:203], v[184:187], v[22:25]
	v_mfma_f32_16x16x32_bf16 v[18:21], v[210:213], v[184:187], v[18:21]
	v_mfma_f32_16x16x32_bf16 v[6:9], v[200:203], v[192:195], v[6:9]
	v_mfma_f32_16x16x32_bf16 v[2:5], v[210:213], v[192:195], v[2:5]
	s_add_i32 s73, s73, 2
	s_add_u32 s71, s71, 0x100
	s_addc_u32 s72, s72, 0
	s_add_u32 s46, s46, 0x100
	s_addc_u32 s47, s47, 0
	s_cmp_gt_u32 s73, 29
	s_barrier
	s_cbranch_scc0 .LBB0_73
	v_lshl_add_u32 v146, s8, 8, v142
	v_max_f32_e32 v122, v122, v122
	v_ashrrev_i32_e32 v147, 31, v146
	v_max_f32_e32 v122, 0, v122
	v_max_f32_e32 v123, v123, v123
	v_max_f32_e32 v124, v124, v124
	v_lshl_or_b32 v140, s68, 8, v144
	v_lshlrev_b64 v[148:149], 14, v[146:147]
	v_mul_f32_e32 v147, v122, v122
	v_max_f32_e32 v122, v127, v127
	v_max_f32_e32 v123, 0, v123
	v_max_f32_e32 v124, 0, v124
	v_ashrrev_i32_e32 v141, 31, v140
	v_max_f32_e32 v126, v126, v126
	v_max_f32_e32 v122, 0, v122
	v_mul_f32_e32 v127, v123, v123
	v_max_f32_e32 v123, v128, v128
	v_mul_f32_e32 v128, v124, v124
	v_max_f32_e32 v124, v129, v129
	v_max_f32_e32 v125, v125, v125
	v_lshl_add_u64 v[148:149], s[24:25], 0, v[148:149]
	v_lshlrev_b64 v[150:151], 1, v[140:141]
	v_max_f32_e32 v126, 0, v126
	v_mul_f32_e32 v122, v122, v122
	v_max_f32_e32 v123, 0, v123
	v_max_f32_e32 v124, 0, v124
	v_max_f32_e32 v125, 0, v125
	v_max_f32_e32 v114, v114, v114
	v_lshl_add_u64 v[140:141], v[148:149], 0, v[150:151]
	v_mul_f32_e32 v126, v126, v126
	v_mul_f32_e32 v123, v123, v123
	v_mul_f32_e32 v124, v124, v124
	v_mul_f32_e32 v125, v125, v125
	v_cvt_pk_bf16_f32 v122, v126, v122
	v_max_f32_e32 v114, 0, v114
	v_max_f32_e32 v115, v115, v115
	v_max_f32_e32 v116, v116, v116
	v_cvt_pk_bf16_f32 v123, v123, v124
	v_cvt_pk_bf16_f32 v124, v147, v127
	v_cvt_pk_bf16_f32 v125, v128, v125
	global_store_dwordx4 v[140:141], v[122:125], off nt
	v_max_f32_e32 v115, 0, v115
	v_max_f32_e32 v116, 0, v116
	v_mul_f32_e32 v122, v114, v114
	v_max_f32_e32 v114, v119, v119
	v_max_f32_e32 v118, v118, v118
	v_max_f32_e32 v114, 0, v114
	v_mul_f32_e32 v119, v115, v115
	v_max_f32_e32 v115, v120, v120
	v_mul_f32_e32 v120, v116, v116
	v_max_f32_e32 v116, v121, v121
	v_max_f32_e32 v117, v117, v117
	v_max_f32_e32 v118, 0, v118
	v_mul_f32_e32 v114, v114, v114
	v_max_f32_e32 v115, 0, v115
	v_max_f32_e32 v116, 0, v116
	v_max_f32_e32 v117, 0, v117
	v_mul_f32_e32 v118, v118, v118
	v_mul_f32_e32 v115, v115, v115
	v_mul_f32_e32 v116, v116, v116
	v_mul_f32_e32 v117, v117, v117
	v_cvt_pk_bf16_f32 v114, v118, v114
	v_max_f32_e32 v106, v106, v106
	v_cvt_pk_bf16_f32 v115, v115, v116
	v_cvt_pk_bf16_f32 v116, v122, v119
	v_cvt_pk_bf16_f32 v117, v120, v117
	global_store_dwordx4 v[140:141], v[114:117], off offset:256 nt
	v_max_f32_e32 v106, 0, v106
	v_max_f32_e32 v107, v107, v107
	v_or_b32_e32 v114, 16, v146
; __device__ __forceinline__ unsigned cvt_pk_bf16(float lo, float hi) { unsigned r; asm("v_cvt_pk_bf16_f32 %0, %1, %2" : "=v"(r) : "v"(lo), "v"(hi)); return r; }
;     __device__ __forceinline__ void operator()(const f32x4 (&acc)[2][2][4][2], const Unit& u, int wr, int wc, int fr, int fq) const {
;     ...
;         for (int ai = 0; ai < 2; ++ai)
; #pragma unroll
;             for (int m = 0; m < 4; ++m) { bf16_t* rowp = O + (size_t)(row0 + ai * HALF + m * 16) * ldc + col0;
; #pragma unroll
;                 for (int bj = 0; bj < 2; ++bj) { f32x4 v0 = acc[ai][bj][m][0], v1 = acc[ai][bj][m][1];
;                     if (ACT == 1) {
; #pragma unroll
;                         for (int j = 0; j < 4; ++j) { float a = fmaxf(v0[j], 0.f), b = fmaxf(v1[j], 0.f); v0[j] = a * a; v1[j] = b * b; } }
;                     u32x4 w; w.x = cvt_pk_bf16(v0[0], v0[1]); w.y = cvt_pk_bf16(v0[2], v0[3]); w.z = cvt_pk_bf16(v1[0], v1[1]); w.w = cvt_pk_bf16(v1[2], v1[3]);
;                     if (ACT == 1) __builtin_nontemporal_store(w, (u32x4*)(rowp + bj * HALF));
;                     else *(u32x4*)(rowp + bj * HALF) = w; } }
	v_max_f32_e32 v108, v108, v108
	v_ashrrev_i32_e32 v115, 31, v114
	v_mul_f32_e32 v116, v106, v106
	v_max_f32_e32 v106, v111, v111
	v_max_f32_e32 v107, 0, v107
	v_max_f32_e32 v108, 0, v108
	v_lshlrev_b64 v[114:115], 14, v[114:115]
	v_max_f32_e32 v110, v110, v110
	v_max_f32_e32 v106, 0, v106
	v_mul_f32_e32 v111, v107, v107
	v_max_f32_e32 v107, v112, v112
	v_mul_f32_e32 v112, v108, v108
	v_max_f32_e32 v108, v113, v113
	v_max_f32_e32 v109, v109, v109
	v_lshl_add_u64 v[114:115], s[24:25], 0, v[114:115]
	v_max_f32_e32 v110, 0, v110
	v_mul_f32_e32 v106, v106, v106
	v_max_f32_e32 v107, 0, v107
	v_max_f32_e32 v108, 0, v108
	v_max_f32_e32 v109, 0, v109
	v_max_f32_e32 v98, v98, v98
	v_lshl_add_u64 v[114:115], v[114:115], 0, v[150:151]
	v_mul_f32_e32 v110, v110, v110
	v_mul_f32_e32 v107, v107, v107
	v_mul_f32_e32 v108, v108, v108
	v_mul_f32_e32 v109, v109, v109
	v_cvt_pk_bf16_f32 v106, v110, v106
	v_max_f32_e32 v98, 0, v98
	v_max_f32_e32 v99, v99, v99
	v_max_f32_e32 v100, v100, v100
	v_cvt_pk_bf16_f32 v107, v107, v108
	v_cvt_pk_bf16_f32 v108, v116, v111
	v_cvt_pk_bf16_f32 v109, v112, v109
	global_store_dwordx4 v[114:115], v[106:109], off nt
	v_max_f32_e32 v99, 0, v99
	v_max_f32_e32 v100, 0, v100
	v_mul_f32_e32 v106, v98, v98
	v_max_f32_e32 v98, v103, v103
	v_max_f32_e32 v102, v102, v102
	v_max_f32_e32 v98, 0, v98
	v_mul_f32_e32 v103, v99, v99
	v_max_f32_e32 v99, v104, v104
	v_mul_f32_e32 v104, v100, v100
	v_max_f32_e32 v100, v105, v105
	v_max_f32_e32 v101, v101, v101
	v_max_f32_e32 v102, 0, v102
	v_mul_f32_e32 v98, v98, v98
	v_max_f32_e32 v99, 0, v99
	v_max_f32_e32 v100, 0, v100
	v_max_f32_e32 v101, 0, v101
	v_mul_f32_e32 v102, v102, v102
	v_mul_f32_e32 v99, v99, v99
	v_mul_f32_e32 v100, v100, v100
	v_mul_f32_e32 v101, v101, v101
	v_cvt_pk_bf16_f32 v98, v102, v98
	v_max_f32_e32 v90, v90, v90
	v_cvt_pk_bf16_f32 v99, v99, v100
	v_cvt_pk_bf16_f32 v100, v106, v103
	v_cvt_pk_bf16_f32 v101, v104, v101
	global_store_dwordx4 v[114:115], v[98:101], off offset:256 nt
	v_max_f32_e32 v90, 0, v90
	v_max_f32_e32 v91, v91, v91
	v_or_b32_e32 v98, 32, v146
	v_max_f32_e32 v92, v92, v92
	v_ashrrev_i32_e32 v99, 31, v98
	v_mul_f32_e32 v100, v90, v90
	v_max_f32_e32 v90, v95, v95
	v_max_f32_e32 v91, 0, v91
	v_max_f32_e32 v92, 0, v92
	v_lshlrev_b64 v[98:99], 14, v[98:99]
	v_max_f32_e32 v94, v94, v94
	v_max_f32_e32 v90, 0, v90
	v_mul_f32_e32 v95, v91, v91
	v_max_f32_e32 v91, v96, v96
	v_mul_f32_e32 v96, v92, v92
	v_max_f32_e32 v92, v97, v97
	v_max_f32_e32 v93, v93, v93
	v_lshl_add_u64 v[98:99], s[24:25], 0, v[98:99]
	v_max_f32_e32 v94, 0, v94
	v_mul_f32_e32 v90, v90, v90
	v_max_f32_e32 v91, 0, v91
	v_max_f32_e32 v92, 0, v92
	v_max_f32_e32 v93, 0, v93
	v_max_f32_e32 v82, v82, v82
	v_lshl_add_u64 v[98:99], v[98:99], 0, v[150:151]
	v_mul_f32_e32 v94, v94, v94
	v_mul_f32_e32 v91, v91, v91
	v_mul_f32_e32 v92, v92, v92
	v_mul_f32_e32 v93, v93, v93
	v_cvt_pk_bf16_f32 v90, v94, v90
	v_max_f32_e32 v82, 0, v82
	v_max_f32_e32 v83, v83, v83
	v_max_f32_e32 v84, v84, v84
	v_cvt_pk_bf16_f32 v91, v91, v92
	v_cvt_pk_bf16_f32 v92, v100, v95
	v_cvt_pk_bf16_f32 v93, v96, v93
	global_store_dwordx4 v[98:99], v[90:93], off nt
	v_max_f32_e32 v83, 0, v83
	v_max_f32_e32 v84, 0, v84
	v_mul_f32_e32 v90, v82, v82
	v_max_f32_e32 v82, v87, v87
	v_max_f32_e32 v86, v86, v86
	v_max_f32_e32 v82, 0, v82
	v_mul_f32_e32 v87, v83, v83
	v_max_f32_e32 v83, v88, v88
	v_mul_f32_e32 v88, v84, v84
	v_max_f32_e32 v84, v89, v89
	v_max_f32_e32 v85, v85, v85
	v_max_f32_e32 v86, 0, v86
	v_mul_f32_e32 v82, v82, v82
	v_max_f32_e32 v83, 0, v83
	v_max_f32_e32 v84, 0, v84
	v_max_f32_e32 v85, 0, v85
	v_mul_f32_e32 v86, v86, v86
	v_mul_f32_e32 v83, v83, v83
	v_mul_f32_e32 v84, v84, v84
	v_mul_f32_e32 v85, v85, v85
	v_cvt_pk_bf16_f32 v82, v86, v82
	v_max_f32_e32 v74, v74, v74
	v_cvt_pk_bf16_f32 v83, v83, v84
	v_cvt_pk_bf16_f32 v84, v90, v87
	v_cvt_pk_bf16_f32 v85, v88, v85
	global_store_dwordx4 v[98:99], v[82:85], off offset:256 nt
	v_max_f32_e32 v74, 0, v74
	v_max_f32_e32 v75, v75, v75
	v_or_b32_e32 v82, 48, v146
	v_max_f32_e32 v76, v76, v76
	v_ashrrev_i32_e32 v83, 31, v82
	v_mul_f32_e32 v84, v74, v74
	v_max_f32_e32 v74, v79, v79
	v_max_f32_e32 v75, 0, v75
	v_max_f32_e32 v76, 0, v76
	v_lshlrev_b64 v[82:83], 14, v[82:83]
	v_max_f32_e32 v78, v78, v78
	v_max_f32_e32 v74, 0, v74
	v_mul_f32_e32 v79, v75, v75
	v_max_f32_e32 v75, v80, v80
	v_mul_f32_e32 v80, v76, v76
	v_max_f32_e32 v76, v81, v81
	v_max_f32_e32 v77, v77, v77
	v_lshl_add_u64 v[82:83], s[24:25], 0, v[82:83]
	v_max_f32_e32 v78, 0, v78
	v_mul_f32_e32 v74, v74, v74
	v_max_f32_e32 v75, 0, v75
	v_max_f32_e32 v76, 0, v76
	v_max_f32_e32 v77, 0, v77
	v_max_f32_e32 v66, v66, v66
	v_max_f32_e32 v67, v67, v67
	v_max_f32_e32 v68, v68, v68
	v_lshl_add_u64 v[82:83], v[82:83], 0, v[150:151]
	v_mul_f32_e32 v78, v78, v78
	v_mul_f32_e32 v75, v75, v75
	v_mul_f32_e32 v76, v76, v76
	v_mul_f32_e32 v77, v77, v77
	v_cvt_pk_bf16_f32 v74, v78, v74
	v_max_f32_e32 v66, 0, v66
	v_max_f32_e32 v67, 0, v67
	v_max_f32_e32 v68, 0, v68
	v_cvt_pk_bf16_f32 v75, v75, v76
	v_cvt_pk_bf16_f32 v76, v84, v79
	v_cvt_pk_bf16_f32 v77, v80, v77
	global_store_dwordx4 v[82:83], v[74:77], off nt
	v_max_f32_e32 v69, v69, v69
	v_max_f32_e32 v70, v70, v70
	v_mul_f32_e32 v74, v66, v66
	v_max_f32_e32 v66, v71, v71
	v_mul_f32_e32 v71, v67, v67
	v_max_f32_e32 v67, v72, v72
	v_mul_f32_e32 v72, v68, v68
	v_max_f32_e32 v68, v73, v73
	v_max_f32_e32 v67, 0, v67
	v_max_f32_e32 v68, 0, v68
	v_max_f32_e32 v66, 0, v66
	v_mul_f32_e32 v67, v67, v67
	v_max_f32_e32 v69, 0, v69
	v_mul_f32_e32 v68, v68, v68
	v_max_f32_e32 v58, v58, v58
	v_max_f32_e32 v70, 0, v70
	v_mul_f32_e32 v66, v66, v66
	v_mul_f32_e32 v69, v69, v69
	v_cvt_pk_bf16_f32 v67, v67, v68
; __device__ __forceinline__ unsigned cvt_pk_bf16(float lo, float hi) { unsigned r; asm("v_cvt_pk_bf16_f32 %0, %1, %2" : "=v"(r) : "v"(lo), "v"(hi)); return r; }
;     __device__ __forceinline__ void operator()(const f32x4 (&acc)[2][2][4][2], const Unit& u, int wr, int wc, int fr, int fq) const {
;     ...
;         for (int ai = 0; ai < 2; ++ai)
; #pragma unroll
;             for (int m = 0; m < 4; ++m) { bf16_t* rowp = O + (size_t)(row0 + ai * HALF + m * 16) * ldc + col0;
; #pragma unroll
;                 for (int bj = 0; bj < 2; ++bj) { f32x4 v0 = acc[ai][bj][m][0], v1 = acc[ai][bj][m][1];
;                     if (ACT == 1) {
; #pragma unroll
;                         for (int j = 0; j < 4; ++j) { float a = fmaxf(v0[j], 0.f), b = fmaxf(v1[j], 0.f); v0[j] = a * a; v1[j] = b * b; } }
;                     u32x4 w; w.x = cvt_pk_bf16(v0[0], v0[1]); w.y = cvt_pk_bf16(v0[2], v0[3]); w.z = cvt_pk_bf16(v1[0], v1[1]); w.w = cvt_pk_bf16(v1[2], v1[3]);
;                     if (ACT == 1) __builtin_nontemporal_store(w, (u32x4*)(rowp + bj * HALF));
;                     else *(u32x4*)(rowp + bj * HALF) = w; } }
	v_cvt_pk_bf16_f32 v68, v74, v71
	v_max_f32_e32 v58, 0, v58
	v_max_f32_e32 v59, v59, v59
	v_max_f32_e32 v60, v60, v60
	v_mul_f32_e32 v70, v70, v70
	v_cvt_pk_bf16_f32 v66, v70, v66
	v_cvt_pk_bf16_f32 v69, v72, v69
	global_store_dwordx4 v[82:83], v[66:69], off offset:256 nt
	v_max_f32_e32 v62, v62, v62
	v_max_f32_e32 v59, 0, v59
	v_mul_f32_e32 v68, v58, v58
	v_max_f32_e32 v58, v63, v63
	v_max_f32_e32 v60, 0, v60
	v_max_f32_e32 v62, 0, v62
	v_max_f32_e32 v58, 0, v58
	v_mul_f32_e32 v63, v59, v59
	v_max_f32_e32 v59, v64, v64
	v_mul_f32_e32 v64, v60, v60
	v_max_f32_e32 v60, v65, v65
	v_mul_f32_e32 v62, v62, v62
	v_mul_f32_e32 v58, v58, v58
	v_max_f32_e32 v59, 0, v59
	v_max_f32_e32 v60, 0, v60
	v_max_f32_e32 v61, v61, v61
	s_mov_b32 s8, 0x200000
	v_mul_f32_e32 v59, v59, v59
	v_max_f32_e32 v61, 0, v61
	v_mul_f32_e32 v60, v60, v60
	v_cvt_pk_bf16_f32 v58, v62, v58
	v_add_co_u32_e32 v62, vcc, s8, v140
	v_max_f32_e32 v50, v50, v50
	v_max_f32_e32 v51, v51, v51
	v_max_f32_e32 v52, v52, v52
	v_mul_f32_e32 v61, v61, v61
	v_cvt_pk_bf16_f32 v59, v59, v60
	v_cvt_pk_bf16_f32 v60, v68, v63
	v_addc_co_u32_e32 v63, vcc, 0, v141, vcc
	v_max_f32_e32 v50, 0, v50
	v_max_f32_e32 v51, 0, v51
	v_max_f32_e32 v52, 0, v52
	v_cvt_pk_bf16_f32 v61, v64, v61
	global_store_dwordx4 v[62:63], v[58:61], off nt
	v_max_f32_e32 v53, v53, v53
	s_mov_b64 s[38:39], 0x200000
	v_mul_f32_e32 v58, v50, v50
	v_max_f32_e32 v50, v55, v55
	v_mul_f32_e32 v55, v51, v51
	v_max_f32_e32 v51, v56, v56
	v_mul_f32_e32 v56, v52, v52
	v_max_f32_e32 v52, v57, v57
	v_max_f32_e32 v51, 0, v51
	v_max_f32_e32 v52, 0, v52
	v_max_f32_e32 v54, v54, v54
	v_max_f32_e32 v50, 0, v50
	v_mul_f32_e32 v51, v51, v51
	v_max_f32_e32 v53, 0, v53
	v_mul_f32_e32 v52, v52, v52
	v_max_f32_e32 v42, v42, v42
	v_lshl_add_u64 v[66:67], v[140:141], 0, s[38:39]
	v_max_f32_e32 v54, 0, v54
	v_mul_f32_e32 v50, v50, v50
	v_mul_f32_e32 v53, v53, v53
	v_cvt_pk_bf16_f32 v51, v51, v52
	v_cvt_pk_bf16_f32 v52, v58, v55
	v_max_f32_e32 v42, 0, v42
	v_max_f32_e32 v43, v43, v43
	v_max_f32_e32 v44, v44, v44
	v_mul_f32_e32 v54, v54, v54
	v_cvt_pk_bf16_f32 v50, v54, v50
	v_cvt_pk_bf16_f32 v53, v56, v53
	global_store_dwordx4 v[66:67], v[50:53], off offset:256 nt
	v_max_f32_e32 v46, v46, v46
	v_max_f32_e32 v43, 0, v43
	v_mul_f32_e32 v52, v42, v42
	v_max_f32_e32 v42, v47, v47
	v_max_f32_e32 v44, 0, v44
	v_max_f32_e32 v46, 0, v46
	v_max_f32_e32 v42, 0, v42
	v_mul_f32_e32 v47, v43, v43
	v_max_f32_e32 v43, v48, v48
	v_mul_f32_e32 v48, v44, v44
	v_max_f32_e32 v44, v49, v49
	v_mul_f32_e32 v46, v46, v46
	v_mul_f32_e32 v42, v42, v42
	v_max_f32_e32 v43, 0, v43
	v_max_f32_e32 v44, 0, v44
	v_max_f32_e32 v45, v45, v45
	s_mov_b32 s8, 0x240000
	v_mul_f32_e32 v43, v43, v43
	v_max_f32_e32 v45, 0, v45
	v_mul_f32_e32 v44, v44, v44
	v_cvt_pk_bf16_f32 v42, v46, v42
	v_add_co_u32_e32 v46, vcc, s8, v140
	v_max_f32_e32 v34, v34, v34
	v_max_f32_e32 v35, v35, v35
	v_max_f32_e32 v36, v36, v36
	v_mul_f32_e32 v45, v45, v45
	v_cvt_pk_bf16_f32 v43, v43, v44
	v_cvt_pk_bf16_f32 v44, v52, v47
	v_addc_co_u32_e32 v47, vcc, 0, v141, vcc
	v_max_f32_e32 v34, 0, v34
	v_max_f32_e32 v35, 0, v35
	v_max_f32_e32 v36, 0, v36
	v_cvt_pk_bf16_f32 v45, v48, v45
	global_store_dwordx4 v[46:47], v[42:45], off nt
	v_max_f32_e32 v37, v37, v37
	s_mov_b64 s[38:39], 0x240000
	v_mul_f32_e32 v42, v34, v34
	v_max_f32_e32 v34, v39, v39
	v_mul_f32_e32 v39, v35, v35
	v_max_f32_e32 v35, v40, v40
	v_mul_f32_e32 v40, v36, v36
	v_max_f32_e32 v36, v41, v41
	v_max_f32_e32 v35, 0, v35
	v_max_f32_e32 v36, 0, v36
	v_max_f32_e32 v38, v38, v38
	v_max_f32_e32 v34, 0, v34
	v_mul_f32_e32 v35, v35, v35
	v_max_f32_e32 v37, 0, v37
	v_mul_f32_e32 v36, v36, v36
	v_max_f32_e32 v26, v26, v26
	v_lshl_add_u64 v[50:51], v[140:141], 0, s[38:39]
	v_max_f32_e32 v38, 0, v38
	v_mul_f32_e32 v34, v34, v34
	v_mul_f32_e32 v37, v37, v37
	v_cvt_pk_bf16_f32 v35, v35, v36
	v_cvt_pk_bf16_f32 v36, v42, v39
	v_max_f32_e32 v26, 0, v26
	v_max_f32_e32 v27, v27, v27
	v_max_f32_e32 v28, v28, v28
	v_mul_f32_e32 v38, v38, v38
; __device__ __forceinline__ unsigned cvt_pk_bf16(float lo, float hi) { unsigned r; asm("v_cvt_pk_bf16_f32 %0, %1, %2" : "=v"(r) : "v"(lo), "v"(hi)); return r; }
;     __device__ __forceinline__ void operator()(const f32x4 (&acc)[2][2][4][2], const Unit& u, int wr, int wc, int fr, int fq) const {
;     ...
;         for (int ai = 0; ai < 2; ++ai)
; #pragma unroll
;             for (int m = 0; m < 4; ++m) { bf16_t* rowp = O + (size_t)(row0 + ai * HALF + m * 16) * ldc + col0;
; #pragma unroll
;                 for (int bj = 0; bj < 2; ++bj) { f32x4 v0 = acc[ai][bj][m][0], v1 = acc[ai][bj][m][1];
;                     if (ACT == 1) {
; #pragma unroll
;                         for (int j = 0; j < 4; ++j) { float a = fmaxf(v0[j], 0.f), b = fmaxf(v1[j], 0.f); v0[j] = a * a; v1[j] = b * b; } }
;                     u32x4 w; w.x = cvt_pk_bf16(v0[0], v0[1]); w.y = cvt_pk_bf16(v0[2], v0[3]); w.z = cvt_pk_bf16(v1[0], v1[1]); w.w = cvt_pk_bf16(v1[2], v1[3]);
;                     if (ACT == 1) __builtin_nontemporal_store(w, (u32x4*)(rowp + bj * HALF));
;                     else *(u32x4*)(rowp + bj * HALF) = w; } }
; template <class Epi, class Sched>
; __device__ __forceinline__ void gemm_phase(LAS unsigned char* lds, const Gemm g, const Sched& S, const Epi& E) {
;     ...
;         if (!has_next) break;
; #pragma unroll
;         for (int a = 0; a < 2; ++a)
; #pragma unroll
;             for (int b = 0; b < 2; ++b)
; #pragma unroll
;                 for (int m = 0; m < 4; ++m)
; #pragma unroll
;                     for (int n = 0; n < 2; ++n) acc[a][b][m][n] = (f32x4){0.f, 0.f, 0.f, 0.f};
;         cur = nxt; cA = nA; cB = nB; ++ui;
	v_cvt_pk_bf16_f32 v34, v38, v34
	v_cvt_pk_bf16_f32 v37, v40, v37
	global_store_dwordx4 v[50:51], v[34:37], off offset:256 nt
	v_max_f32_e32 v30, v30, v30
	v_max_f32_e32 v27, 0, v27
	v_mul_f32_e32 v36, v26, v26
	v_max_f32_e32 v26, v31, v31
	v_max_f32_e32 v28, 0, v28
	v_max_f32_e32 v30, 0, v30
	v_max_f32_e32 v26, 0, v26
	v_mul_f32_e32 v31, v27, v27
	v_max_f32_e32 v27, v32, v32
	v_mul_f32_e32 v32, v28, v28
	v_max_f32_e32 v28, v33, v33
	v_mul_f32_e32 v30, v30, v30
	v_mul_f32_e32 v26, v26, v26
	v_max_f32_e32 v27, 0, v27
	v_max_f32_e32 v28, 0, v28
	v_max_f32_e32 v29, v29, v29
	s_mov_b32 s8, 0x280000
	v_mul_f32_e32 v27, v27, v27
	v_max_f32_e32 v29, 0, v29
	v_mul_f32_e32 v28, v28, v28
	v_cvt_pk_bf16_f32 v26, v30, v26
	v_add_co_u32_e32 v30, vcc, s8, v140
	v_max_f32_e32 v18, v18, v18
	v_max_f32_e32 v19, v19, v19
	v_max_f32_e32 v20, v20, v20
	v_mul_f32_e32 v29, v29, v29
	v_cvt_pk_bf16_f32 v27, v27, v28
	v_cvt_pk_bf16_f32 v28, v36, v31
	v_addc_co_u32_e32 v31, vcc, 0, v141, vcc
	v_max_f32_e32 v18, 0, v18
	v_max_f32_e32 v19, 0, v19
	v_max_f32_e32 v20, 0, v20
	v_cvt_pk_bf16_f32 v29, v32, v29
	global_store_dwordx4 v[30:31], v[26:29], off nt
	v_max_f32_e32 v21, v21, v21
	s_mov_b64 s[38:39], 0x280000
	v_mul_f32_e32 v26, v18, v18
	v_max_f32_e32 v18, v23, v23
	v_mul_f32_e32 v23, v19, v19
	v_max_f32_e32 v19, v24, v24
	v_mul_f32_e32 v24, v20, v20
	v_max_f32_e32 v20, v25, v25
	v_max_f32_e32 v19, 0, v19
	v_max_f32_e32 v20, 0, v20
	v_max_f32_e32 v22, v22, v22
	v_max_f32_e32 v18, 0, v18
	v_mul_f32_e32 v19, v19, v19
	v_max_f32_e32 v21, 0, v21
	v_mul_f32_e32 v20, v20, v20
	v_max_f32_e32 v10, v10, v10
	v_lshl_add_u64 v[34:35], v[140:141], 0, s[38:39]
	v_max_f32_e32 v22, 0, v22
	v_mul_f32_e32 v18, v18, v18
	v_mul_f32_e32 v21, v21, v21
	v_cvt_pk_bf16_f32 v19, v19, v20
	v_cvt_pk_bf16_f32 v20, v26, v23
	v_max_f32_e32 v10, 0, v10
	v_max_f32_e32 v11, v11, v11
	v_max_f32_e32 v12, v12, v12
	v_mul_f32_e32 v22, v22, v22
	v_cvt_pk_bf16_f32 v18, v22, v18
	v_cvt_pk_bf16_f32 v21, v24, v21
	global_store_dwordx4 v[34:35], v[18:21], off offset:256 nt
	v_max_f32_e32 v14, v14, v14
	v_max_f32_e32 v11, 0, v11
	v_mul_f32_e32 v20, v10, v10
	v_max_f32_e32 v10, v15, v15
	v_max_f32_e32 v12, 0, v12
	v_max_f32_e32 v14, 0, v14
	v_max_f32_e32 v10, 0, v10
	v_mul_f32_e32 v15, v11, v11
	v_max_f32_e32 v11, v16, v16
	v_mul_f32_e32 v16, v12, v12
	v_max_f32_e32 v12, v17, v17
	v_mul_f32_e32 v14, v14, v14
	v_mul_f32_e32 v10, v10, v10
	v_max_f32_e32 v11, 0, v11
	v_max_f32_e32 v12, 0, v12
	v_max_f32_e32 v13, v13, v13
	s_mov_b32 s8, 0x2c0000
	v_mul_f32_e32 v11, v11, v11
	v_max_f32_e32 v13, 0, v13
	v_mul_f32_e32 v12, v12, v12
	v_cvt_pk_bf16_f32 v10, v14, v10
	v_add_co_u32_e32 v14, vcc, s8, v140
	v_max_f32_e32 v2, v2, v2
	v_max_f32_e32 v3, v3, v3
	v_max_f32_e32 v4, v4, v4
	v_mul_f32_e32 v13, v13, v13
	v_cvt_pk_bf16_f32 v11, v11, v12
	v_cvt_pk_bf16_f32 v12, v20, v15
	v_addc_co_u32_e32 v15, vcc, 0, v141, vcc
	v_max_f32_e32 v2, 0, v2
	v_max_f32_e32 v3, 0, v3
	v_max_f32_e32 v4, 0, v4
	v_cvt_pk_bf16_f32 v13, v16, v13
	global_store_dwordx4 v[14:15], v[10:13], off nt
	v_max_f32_e32 v5, v5, v5
	s_mov_b64 s[38:39], 0x2c0000
	v_mul_f32_e32 v10, v2, v2
	v_max_f32_e32 v2, v7, v7
	v_mul_f32_e32 v7, v3, v3
	v_max_f32_e32 v3, v8, v8
	v_mul_f32_e32 v8, v4, v4
	v_max_f32_e32 v4, v9, v9
	v_max_f32_e32 v6, v6, v6
	v_max_f32_e32 v2, 0, v2
	v_max_f32_e32 v3, 0, v3
	v_max_f32_e32 v4, 0, v4
	v_max_f32_e32 v5, 0, v5
	v_lshl_add_u64 v[18:19], v[140:141], 0, s[38:39]
	v_max_f32_e32 v6, 0, v6
	v_mul_f32_e32 v2, v2, v2
	v_mul_f32_e32 v3, v3, v3
	v_mul_f32_e32 v4, v4, v4
	v_mul_f32_e32 v5, v5, v5
	s_and_b64 vcc, exec, s[40:41]
	s_mov_b32 s68, s26
	s_mov_b32 s8, s28
	s_mov_b64 s[46:47], s[44:45]
	s_mov_b64 s[48:49], s[42:43]
	v_mul_f32_e32 v6, v6, v6
	v_cvt_pk_bf16_f32 v2, v6, v2
	v_cvt_pk_bf16_f32 v3, v3, v4
	v_cvt_pk_bf16_f32 v4, v10, v7
	v_cvt_pk_bf16_f32 v5, v8, v5
	global_store_dwordx4 v[18:19], v[2:5], off offset:256 nt
	s_cbranch_vccz .LBB0_70
	s_waitcnt vmcnt(0)
	s_cmpk_gt_u32 s52, 0xff
	s_cbranch_scc1 .LBB0_77
	s_barrier

; #define PG8_STAGE(bufoff, gbase, voff) do { _Pragma("unroll") for (int _i = 0; _i < 2; ++_i) \
;         __builtin_amdgcn_global_load_lds((const unsigned*)((const char*)(gbase) + (voff)[_i]), (LAS unsigned*)(lds + (bufoff) + ldsw + _i * 8192), 16, 0, 0); } while (0)
; #define PG8_LDA(dst, b, h) do { _Pragma("unroll") for (int m = 0; m < 4; ++m) _Pragma("unroll") for (int k = 0; k < 2; ++k) dst[m][k] = *(const LAS bf16x8*)(lds + PG8_SA(b, h) + aoff + m * 2048 + k * 1024); } while (0)
; #define PG8_LDB(dst, b, h) do { _Pragma("unroll") for (int n = 0; n < 2; ++n) _Pragma("unroll") for (int k = 0; k < 2; ++k) dst[n][k] = *(const LAS bf16x8*)(lds + PG8_SB(b, h) + boff + n * 2048 + k * 1024); } while (0)
; #define PG8_MMA(ai, bj, At, Bt) do { __builtin_amdgcn_s_setprio(1); _Pragma("unroll") for (int m = 0; m < 4; ++m) _Pragma("unroll") for (int n = 0; n < 2; ++n) _Pragma("unroll") for (int k = 0; k < 2; ++k) \
;         acc[ai][bj][m][n] = __builtin_amdgcn_mfma_f32_16x16x32_bf16(Bt[n][k], At[m][k], acc[ai][bj][m][n], 0, 0, 0); __builtin_amdgcn_s_setprio(0); } while (0)
; #define PG8_WAIT_L(n) asm volatile("s_waitcnt lgkmcnt(" #n ")" ::: "memory")
; #define PG8_BAR __builtin_amdgcn_s_barrier()
; #define PG8_SCHED __builtin_amdgcn_sched_barrier(0)
; template <class Epi, class Sched>
; __device__ __forceinline__ void gemm_phase(LAS unsigned char* lds, const Gemm g, const Sched& S, const Epi& E) {
;     ...
;         for (int t = 0; t < nt; t += 2) {
;             const bool last = (t == nt - 2);
;             const char* a1 = cA + (size_t)(t + 1) * kstep;
;             const char* a2 = last ? nA : cA + (size_t)(t + 2) * kstep; const char* b2 = last ? nB : cB + (size_t)(t + 2) * kstep;
;             const char* a3 = a2 + kstep; const char* b3 = b2 + kstep;
;             PG8_LDB(B0, 0, 0); PG8_SCHED; PG8_LDA(At, 0, 0); PG8_STAGE(PG8_SA(1, 1), a1 + hstep, voffA);
;             PG8_WAIT_L(8); PG8_BAR; PG8_WAIT_L(0); PG8_MMA(0, 0, At, B0); PG8_BAR; PG8_SCHED;
;             PG8_LDB(B1, 0, 1); PG8_STAGE(PG8_SB(0, 0), b2, voffB);
;             PG8_BAR; PG8_WAIT_L(0); PG8_MMA(0, 1, At, B1); PG8_BAR;
;             PG8_LDA(At, 0, 1); PG8_STAGE(PG8_SA(0, 0), a2, voffA);
;             PG8_BAR; PG8_WAIT_L(0); PG8_MMA(1, 0, At, B0); PG8_BAR; PG8_SCHED;
.LBB0_99:
	s_add_u32 s100, s79, 0x7ff80
	s_addc_u32 s101, s80, 0
	v_lshl_add_u64 v[98:99], s[100:101], 0, v[0:1]
	s_add_i32 m0, s67, 0x1c000
	s_nop 0
	global_load_lds_dwordx4 v[98:99], off
	v_lshl_add_u64 v[98:99], s[100:101], 0, v[146:147]
	s_add_i32 m0, s67, 0x1e000
	s_nop 0
	global_load_lds_dwordx4 v[98:99], off
	s_add_u32 s56, s28, 0x100
	s_addc_u32 s57, s29, 0
	s_cmp_eq_u32 s81, 28
	s_cselect_b32 s61, s51, s57
	s_cselect_b32 s60, s77, s56
	s_cselect_b32 s59, s49, s80
	s_cselect_b32 s58, s78, s79
	v_lshl_add_u64 v[156:157], s[28:29], 0, v[150:151]
	s_add_i32 m0, s9, 0xc000
	s_nop 0
	global_load_lds_dwordx4 v[156:157], off
	v_lshl_add_u64 v[156:157], s[28:29], 0, v[148:149]
	s_add_i32 m0, s9, 0xe000
	s_nop 0
	global_load_lds_dwordx4 v[156:157], off
	s_add_i32 s38, 0, 0x10000
	v_add_u32_e32 v110, s38, v169
	ds_read_b128 v[98:101], v110
	ds_read_b128 v[102:105], v110 offset:1024
	ds_read_b128 v[106:109], v110 offset:2048
	ds_read_b128 v[110:113], v110 offset:3072
	ds_read_b128 v[152:155], v171
	ds_read_b128 v[160:163], v171 offset:1024
	ds_read_b128 v[164:167], v171 offset:2048
	ds_read_b128 v[172:175], v171 offset:3072
	ds_read_b128 v[176:179], v171 offset:4096
	ds_read_b128 v[180:183], v171 offset:5120
	ds_read_b128 v[184:187], v171 offset:6144
	ds_read_b128 v[188:191], v171 offset:7168
	s_add_i32 s39, 0, 0x14000
	v_add_u32_e32 v156, s39, v169
	ds_read_b128 v[192:195], v156
	ds_read_b128 v[196:199], v156 offset:1024
	ds_read_b128 v[200:203], v156 offset:2048
	ds_read_b128 v[204:207], v156 offset:3072
	s_waitcnt lgkmcnt(4)
	s_barrier
	s_waitcnt lgkmcnt(0)
	v_mfma_f32_16x16x32_bf16 v[142:145], v[98:101], v[152:155], v[142:145]
	v_mfma_f32_16x16x32_bf16 v[138:141], v[106:109], v[152:155], v[138:141]
	v_mfma_f32_16x16x32_bf16 v[126:129], v[98:101], v[164:167], v[126:129]
	v_mfma_f32_16x16x32_bf16 v[122:125], v[106:109], v[164:167], v[122:125]
	v_mfma_f32_16x16x32_bf16 v[94:97], v[98:101], v[176:179], v[94:97]
	v_mfma_f32_16x16x32_bf16 v[90:93], v[106:109], v[176:179], v[90:93]
	v_mfma_f32_16x16x32_bf16 v[86:89], v[98:101], v[184:187], v[86:89]
	v_mfma_f32_16x16x32_bf16 v[82:85], v[106:109], v[184:187], v[82:85]
	v_mfma_f32_16x16x32_bf16 v[142:145], v[102:105], v[160:163], v[142:145]
	v_mfma_f32_16x16x32_bf16 v[138:141], v[110:113], v[160:163], v[138:141]
	v_mfma_f32_16x16x32_bf16 v[126:129], v[102:105], v[172:175], v[126:129]
	v_mfma_f32_16x16x32_bf16 v[122:125], v[110:113], v[172:175], v[122:125]
	v_mfma_f32_16x16x32_bf16 v[94:97], v[102:105], v[180:183], v[94:97]
	v_mfma_f32_16x16x32_bf16 v[90:93], v[110:113], v[180:183], v[90:93]
	v_mfma_f32_16x16x32_bf16 v[86:89], v[102:105], v[188:191], v[86:89]
	v_mfma_f32_16x16x32_bf16 v[82:85], v[110:113], v[188:191], v[82:85]
	v_mfma_f32_16x16x32_bf16 v[134:137], v[192:195], v[152:155], v[134:137]
	v_mfma_f32_16x16x32_bf16 v[130:133], v[200:203], v[152:155], v[130:133]
	v_mfma_f32_16x16x32_bf16 v[118:121], v[192:195], v[164:167], v[118:121]
	v_mfma_f32_16x16x32_bf16 v[114:117], v[200:203], v[164:167], v[114:117]
	v_mfma_f32_16x16x32_bf16 v[78:81], v[192:195], v[176:179], v[78:81]
	v_mfma_f32_16x16x32_bf16 v[74:77], v[200:203], v[176:179], v[74:77]
	v_mfma_f32_16x16x32_bf16 v[70:73], v[192:195], v[184:187], v[70:73]
	v_mfma_f32_16x16x32_bf16 v[66:69], v[200:203], v[184:187], v[66:69]
	v_mfma_f32_16x16x32_bf16 v[134:137], v[196:199], v[160:163], v[134:137]
	v_mfma_f32_16x16x32_bf16 v[130:133], v[204:207], v[160:163], v[130:133]
	v_mfma_f32_16x16x32_bf16 v[118:121], v[196:199], v[172:175], v[118:121]
	v_mfma_f32_16x16x32_bf16 v[114:117], v[204:207], v[172:175], v[114:117]
	v_mfma_f32_16x16x32_bf16 v[78:81], v[196:199], v[180:183], v[78:81]
	v_mfma_f32_16x16x32_bf16 v[74:77], v[204:207], v[180:183], v[74:77]
	v_mfma_f32_16x16x32_bf16 v[70:73], v[196:199], v[188:191], v[70:73]
	v_mfma_f32_16x16x32_bf16 v[66:69], v[204:207], v[188:191], v[66:69]
	s_barrier
	s_add_i32 s28, s38, s67
	v_lshl_add_u64 v[156:157], s[58:59], 0, v[0:1]
	s_mov_b32 m0, s28
	v_lshl_add_u64 v[210:211], s[58:59], 0, v[146:147]
	global_load_lds_dwordx4 v[156:157], off
	s_add_i32 m0, s28, 0x2000
	s_nop 0
	global_load_lds_dwordx4 v[210:211], off
	s_mov_b32 m0, s9
	v_lshl_add_u64 v[212:213], s[60:61], 0, v[0:1]
	global_load_lds_dwordx4 v[212:213], off
	v_lshl_add_u64 v[214:215], s[60:61], 0, v[146:147]
	s_mov_b32 m0, s68
	s_nop 0
	global_load_lds_dwordx4 v[214:215], off
	ds_read_b128 v[152:155], v171 offset:16384
	ds_read_b128 v[160:163], v171 offset:17408
	ds_read_b128 v[164:167], v171 offset:18432
	ds_read_b128 v[172:175], v171 offset:19456
	ds_read_b128 v[176:179], v171 offset:20480
	ds_read_b128 v[180:183], v171 offset:21504
	ds_read_b128 v[184:187], v171 offset:22528
	ds_read_b128 v[188:191], v171 offset:23552
	s_waitcnt vmcnt(4)
	s_waitcnt lgkmcnt(0)
	s_barrier
; #define PG8_STAGE(bufoff, gbase, voff) do { _Pragma("unroll") for (int _i = 0; _i < 2; ++_i) \
;         __builtin_amdgcn_global_load_lds((const unsigned*)((const char*)(gbase) + (voff)[_i]), (LAS unsigned*)(lds + (bufoff) + ldsw + _i * 8192), 16, 0, 0); } while (0)
; #define PG8_LDA(dst, b, h) do { _Pragma("unroll") for (int m = 0; m < 4; ++m) _Pragma("unroll") for (int k = 0; k < 2; ++k) dst[m][k] = *(const LAS bf16x8*)(lds + PG8_SA(b, h) + aoff + m * 2048 + k * 1024); } while (0)
; #define PG8_MMA(ai, bj, At, Bt) do { __builtin_amdgcn_s_setprio(1); _Pragma("unroll") for (int m = 0; m < 4; ++m) _Pragma("unroll") for (int n = 0; n < 2; ++n) _Pragma("unroll") for (int k = 0; k < 2; ++k) \
;         acc[ai][bj][m][n] = __builtin_amdgcn_mfma_f32_16x16x32_bf16(Bt[n][k], At[m][k], acc[ai][bj][m][n], 0, 0, 0); __builtin_amdgcn_s_setprio(0); } while (0)
; #define PG8_WAIT_V(n) asm volatile("s_waitcnt vmcnt(" #n ")" ::: "memory")
; #define PG8_WAIT_L(n) asm volatile("s_waitcnt lgkmcnt(" #n ")" ::: "memory")
; #define PG8_BAR __builtin_amdgcn_s_barrier()
; #define PG8_SCHED __builtin_amdgcn_sched_barrier(0)
; template <class Epi, class Sched>
; __device__ __forceinline__ void gemm_phase(LAS unsigned char* lds, const Gemm g, const Sched& S, const Epi& E) {
;     ...
;             PG8_BAR; PG8_WAIT_L(0); PG8_MMA(0, 1, At, B1); PG8_BAR;
;             PG8_LDA(At, 0, 1); PG8_STAGE(PG8_SA(0, 0), a2, voffA);
;             PG8_BAR; PG8_WAIT_L(0); PG8_MMA(1, 0, At, B0); PG8_BAR; PG8_SCHED;
;             PG8_STAGE(PG8_SB(0, 1), b2 + hstep, voffB);
;             PG8_WAIT_V(6); PG8_BAR; PG8_MMA(1, 1, At, B1); PG8_BAR;
	v_mfma_f32_16x16x32_bf16 v[62:65], v[98:101], v[152:155], v[62:65]
	v_mfma_f32_16x16x32_bf16 v[58:61], v[106:109], v[152:155], v[58:61]
	v_mfma_f32_16x16x32_bf16 v[46:49], v[98:101], v[164:167], v[46:49]
	v_mfma_f32_16x16x32_bf16 v[42:45], v[106:109], v[164:167], v[42:45]
	v_mfma_f32_16x16x32_bf16 v[30:33], v[98:101], v[176:179], v[30:33]
	v_mfma_f32_16x16x32_bf16 v[26:29], v[106:109], v[176:179], v[26:29]
	v_mfma_f32_16x16x32_bf16 v[22:25], v[98:101], v[184:187], v[22:25]
	v_mfma_f32_16x16x32_bf16 v[18:21], v[106:109], v[184:187], v[18:21]
	v_mfma_f32_16x16x32_bf16 v[62:65], v[102:105], v[160:163], v[62:65]
	v_mfma_f32_16x16x32_bf16 v[58:61], v[110:113], v[160:163], v[58:61]
	v_mfma_f32_16x16x32_bf16 v[46:49], v[102:105], v[172:175], v[46:49]
	v_mfma_f32_16x16x32_bf16 v[42:45], v[110:113], v[172:175], v[42:45]
	v_mfma_f32_16x16x32_bf16 v[30:33], v[102:105], v[180:183], v[30:33]
	v_mfma_f32_16x16x32_bf16 v[26:29], v[110:113], v[180:183], v[26:29]
	v_mfma_f32_16x16x32_bf16 v[22:25], v[102:105], v[188:191], v[22:25]
	v_mfma_f32_16x16x32_bf16 v[18:21], v[110:113], v[188:191], v[18:21]
	v_mfma_f32_16x16x32_bf16 v[54:57], v[192:195], v[152:155], v[54:57]
	v_mfma_f32_16x16x32_bf16 v[50:53], v[200:203], v[152:155], v[50:53]
	v_mfma_f32_16x16x32_bf16 v[38:41], v[192:195], v[164:167], v[38:41]
	v_mfma_f32_16x16x32_bf16 v[34:37], v[200:203], v[164:167], v[34:37]
	v_mfma_f32_16x16x32_bf16 v[14:17], v[192:195], v[176:179], v[14:17]
	v_mfma_f32_16x16x32_bf16 v[10:13], v[200:203], v[176:179], v[10:13]
	v_mfma_f32_16x16x32_bf16 v[6:9], v[192:195], v[184:187], v[6:9]
	v_mfma_f32_16x16x32_bf16 v[2:5], v[200:203], v[184:187], v[2:5]
	v_mfma_f32_16x16x32_bf16 v[54:57], v[196:199], v[160:163], v[54:57]
	v_mfma_f32_16x16x32_bf16 v[50:53], v[204:207], v[160:163], v[50:53]
	v_mfma_f32_16x16x32_bf16 v[38:41], v[196:199], v[172:175], v[38:41]
	v_mfma_f32_16x16x32_bf16 v[34:37], v[204:207], v[172:175], v[34:37]
	v_mfma_f32_16x16x32_bf16 v[14:17], v[196:199], v[180:183], v[14:17]
	v_mfma_f32_16x16x32_bf16 v[10:13], v[204:207], v[180:183], v[10:13]
	v_mfma_f32_16x16x32_bf16 v[6:9], v[196:199], v[188:191], v[6:9]
	v_mfma_f32_16x16x32_bf16 v[2:5], v[204:207], v[188:191], v[2:5]
	s_barrier
	s_add_u32 s28, s58, 0x80000
	s_addc_u32 s29, s59, 0
	s_add_i32 s38, s39, s67
	v_lshl_add_u64 v[98:99], s[28:29], 0, v[0:1]
	s_mov_b32 m0, s38
	s_nop 0
	global_load_lds_dwordx4 v[98:99], off
	v_lshl_add_u64 v[98:99], s[28:29], 0, v[146:147]
	s_add_i32 m0, s38, 0x2000
	s_nop 0
	global_load_lds_dwordx4 v[98:99], off
	s_add_u32 s28, s60, 0x80000
	s_addc_u32 s29, s61, 0
	s_mov_b32 m0, s69
	v_lshl_add_u64 v[192:193], s[28:29], 0, v[0:1]
	global_load_lds_dwordx4 v[192:193], off
	v_lshl_add_u64 v[192:193], s[28:29], 0, v[146:147]
	s_mov_b32 m0, s70
	s_nop 0
	global_load_lds_dwordx4 v[192:193], off
	s_add_i32 s38, 0, 0x18000
	v_add_u32_e32 v110, s38, v169
	ds_read_b128 v[98:101], v110
	ds_read_b128 v[102:105], v110 offset:1024
	ds_read_b128 v[106:109], v110 offset:2048
	ds_read_b128 v[110:113], v110 offset:3072
	ds_read_b128 v[152:155], v171 offset:32768
	ds_read_b128 v[160:163], v171 offset:33792
	ds_read_b128 v[164:167], v171 offset:34816
	ds_read_b128 v[172:175], v171 offset:35840
	ds_read_b128 v[176:179], v171 offset:36864
	ds_read_b128 v[180:183], v171 offset:37888
	ds_read_b128 v[184:187], v171 offset:38912
	ds_read_b128 v[188:191], v171 offset:39936
	s_add_i32 s39, 0, 0x1c000
	v_add_u32_e32 v204, s39, v169
	ds_read_b128 v[192:195], v204
	ds_read_b128 v[196:199], v204 offset:1024
	ds_read_b128 v[200:203], v204 offset:2048
	ds_read_b128 v[204:207], v204 offset:3072
	s_waitcnt lgkmcnt(4)
	s_barrier
; #define PG8_STAGE(bufoff, gbase, voff) do { _Pragma("unroll") for (int _i = 0; _i < 2; ++_i) \
;         __builtin_amdgcn_global_load_lds((const unsigned*)((const char*)(gbase) + (voff)[_i]), (LAS unsigned*)(lds + (bufoff) + ldsw + _i * 8192), 16, 0, 0); } while (0)
; #define PG8_LDA(dst, b, h) do { _Pragma("unroll") for (int m = 0; m < 4; ++m) _Pragma("unroll") for (int k = 0; k < 2; ++k) dst[m][k] = *(const LAS bf16x8*)(lds + PG8_SA(b, h) + aoff + m * 2048 + k * 1024); } while (0)
; #define PG8_LDB(dst, b, h) do { _Pragma("unroll") for (int n = 0; n < 2; ++n) _Pragma("unroll") for (int k = 0; k < 2; ++k) dst[n][k] = *(const LAS bf16x8*)(lds + PG8_SB(b, h) + boff + n * 2048 + k * 1024); } while (0)
; #define PG8_MMA(ai, bj, At, Bt) do { __builtin_amdgcn_s_setprio(1); _Pragma("unroll") for (int m = 0; m < 4; ++m) _Pragma("unroll") for (int n = 0; n < 2; ++n) _Pragma("unroll") for (int k = 0; k < 2; ++k) \
;         acc[ai][bj][m][n] = __builtin_amdgcn_mfma_f32_16x16x32_bf16(Bt[n][k], At[m][k], acc[ai][bj][m][n], 0, 0, 0); __builtin_amdgcn_s_setprio(0); } while (0)
;     __device__ __forceinline__ void operator()(const f32x4 (&acc)[2][2][4][2], const Unit& u, int wr, int wc, int fr, int fq) const {
;         const bool lat = u.pm < 64; const int r = lat ? (u.pm >> 3) : 8;
;         const float* s = lat ? src_lat : src_ctx; float* d = lat ? dst_lat : dst_ctx;
;         const int row0 = (lat ? u.pm : u.pm - 64) * BM + wr * 64 + fr, col0 = u.pn * BM + wc * 32 + 4 * fq;
; template <class Epi, class Sched>
; __device__ __forceinline__ void gemm_phase(LAS unsigned char* lds, const Gemm g, const Sched& S, const Epi& E) {
;     ...
;             PG8_WAIT_V(6); PG8_BAR; PG8_MMA(1, 1, At, B1); PG8_BAR;
;             PG8_LDB(B0, 1, 0); PG8_SCHED; PG8_LDA(At, 1, 0); PG8_STAGE(PG8_SA(0, 1), a2 + hstep, voffA);
;             PG8_WAIT_L(8); PG8_BAR; PG8_WAIT_L(0); PG8_MMA(0, 0, At, B0); PG8_BAR; PG8_SCHED;
;             PG8_LDB(B1, 1, 1); PG8_STAGE(PG8_SB(1, 0), b3, voffB);
;             PG8_BAR; PG8_WAIT_L(0); PG8_MMA(0, 1, At, B1); PG8_BAR;
;             PG8_LDA(At, 1, 1); PG8_STAGE(PG8_SA(1, 0), a3, voffA);
;             PG8_BAR; PG8_WAIT_L(0); PG8_MMA(1, 0, At, B0); PG8_BAR; PG8_SCHED;
;             PG8_STAGE(PG8_SB(1, 1), b3 + hstep, voffB);
;             PG8_WAIT_V(6); PG8_BAR; PG8_MMA(1, 1, At, B1); PG8_BAR;
;         }
;         E(acc, cur, wr, wc, fr, fq);
	s_waitcnt lgkmcnt(0)
	v_mfma_f32_16x16x32_bf16 v[142:145], v[98:101], v[152:155], v[142:145]
	v_mfma_f32_16x16x32_bf16 v[138:141], v[106:109], v[152:155], v[138:141]
	v_mfma_f32_16x16x32_bf16 v[126:129], v[98:101], v[164:167], v[126:129]
	v_mfma_f32_16x16x32_bf16 v[122:125], v[106:109], v[164:167], v[122:125]
	v_mfma_f32_16x16x32_bf16 v[94:97], v[98:101], v[176:179], v[94:97]
	v_mfma_f32_16x16x32_bf16 v[90:93], v[106:109], v[176:179], v[90:93]
	v_mfma_f32_16x16x32_bf16 v[86:89], v[98:101], v[184:187], v[86:89]
	v_mfma_f32_16x16x32_bf16 v[82:85], v[106:109], v[184:187], v[82:85]
	v_mfma_f32_16x16x32_bf16 v[142:145], v[102:105], v[160:163], v[142:145]
	v_mfma_f32_16x16x32_bf16 v[138:141], v[110:113], v[160:163], v[138:141]
	v_mfma_f32_16x16x32_bf16 v[126:129], v[102:105], v[172:175], v[126:129]
	v_mfma_f32_16x16x32_bf16 v[122:125], v[110:113], v[172:175], v[122:125]
	v_mfma_f32_16x16x32_bf16 v[94:97], v[102:105], v[180:183], v[94:97]
	v_mfma_f32_16x16x32_bf16 v[90:93], v[110:113], v[180:183], v[90:93]
	v_mfma_f32_16x16x32_bf16 v[86:89], v[102:105], v[188:191], v[86:89]
	v_mfma_f32_16x16x32_bf16 v[82:85], v[110:113], v[188:191], v[82:85]
	v_mfma_f32_16x16x32_bf16 v[134:137], v[192:195], v[152:155], v[134:137]
	v_mfma_f32_16x16x32_bf16 v[130:133], v[200:203], v[152:155], v[130:133]
	v_mfma_f32_16x16x32_bf16 v[118:121], v[192:195], v[164:167], v[118:121]
	v_mfma_f32_16x16x32_bf16 v[114:117], v[200:203], v[164:167], v[114:117]
	v_mfma_f32_16x16x32_bf16 v[78:81], v[192:195], v[176:179], v[78:81]
	v_mfma_f32_16x16x32_bf16 v[74:77], v[200:203], v[176:179], v[74:77]
	v_mfma_f32_16x16x32_bf16 v[70:73], v[192:195], v[184:187], v[70:73]
	v_mfma_f32_16x16x32_bf16 v[66:69], v[200:203], v[184:187], v[66:69]
	v_mfma_f32_16x16x32_bf16 v[134:137], v[196:199], v[160:163], v[134:137]
	v_mfma_f32_16x16x32_bf16 v[130:133], v[204:207], v[160:163], v[130:133]
	v_mfma_f32_16x16x32_bf16 v[118:121], v[196:199], v[172:175], v[118:121]
	v_mfma_f32_16x16x32_bf16 v[114:117], v[204:207], v[172:175], v[114:117]
	v_mfma_f32_16x16x32_bf16 v[78:81], v[196:199], v[180:183], v[78:81]
	v_mfma_f32_16x16x32_bf16 v[74:77], v[204:207], v[180:183], v[74:77]
	v_mfma_f32_16x16x32_bf16 v[70:73], v[196:199], v[188:191], v[70:73]
	v_mfma_f32_16x16x32_bf16 v[66:69], v[204:207], v[188:191], v[66:69]
	s_barrier
	s_add_i32 s28, s38, s67
	v_lshl_add_u64 v[156:157], v[156:157], 0, s[36:37]
	s_mov_b32 m0, s28
	s_nop 0
	global_load_lds_dwordx4 v[156:157], off
	v_lshl_add_u64 v[156:157], v[210:211], 0, s[36:37]
	s_add_i32 m0, s28, 0x2000
	s_nop 0
	global_load_lds_dwordx4 v[156:157], off
	s_mov_b32 m0, s72
	v_lshl_add_u64 v[156:157], v[212:213], 0, s[36:37]
	global_load_lds_dwordx4 v[156:157], off
	v_lshl_add_u64 v[156:157], v[214:215], 0, s[36:37]
	s_mov_b32 m0, s73
	s_nop 0
	global_load_lds_dwordx4 v[156:157], off
	ds_read_b128 v[152:155], v171 offset:49152
	ds_read_b128 v[160:163], v171 offset:50176
	ds_read_b128 v[164:167], v171 offset:51200
	ds_read_b128 v[172:175], v171 offset:52224
	ds_read_b128 v[176:179], v171 offset:53248
	ds_read_b128 v[180:183], v171 offset:54272
	ds_read_b128 v[184:187], v171 offset:55296
	ds_read_b128 v[188:191], v171 offset:56320
	s_waitcnt vmcnt(4)
	s_waitcnt lgkmcnt(0)
	s_barrier
	v_mfma_f32_16x16x32_bf16 v[62:65], v[98:101], v[152:155], v[62:65]
	v_mfma_f32_16x16x32_bf16 v[58:61], v[106:109], v[152:155], v[58:61]
	v_mfma_f32_16x16x32_bf16 v[46:49], v[98:101], v[164:167], v[46:49]
	v_mfma_f32_16x16x32_bf16 v[42:45], v[106:109], v[164:167], v[42:45]
	v_mfma_f32_16x16x32_bf16 v[30:33], v[98:101], v[176:179], v[30:33]
	v_mfma_f32_16x16x32_bf16 v[26:29], v[106:109], v[176:179], v[26:29]
	v_mfma_f32_16x16x32_bf16 v[22:25], v[98:101], v[184:187], v[22:25]
	v_mfma_f32_16x16x32_bf16 v[18:21], v[106:109], v[184:187], v[18:21]
	v_mfma_f32_16x16x32_bf16 v[62:65], v[102:105], v[160:163], v[62:65]
	v_mfma_f32_16x16x32_bf16 v[58:61], v[110:113], v[160:163], v[58:61]
	v_mfma_f32_16x16x32_bf16 v[46:49], v[102:105], v[172:175], v[46:49]
	v_mfma_f32_16x16x32_bf16 v[42:45], v[110:113], v[172:175], v[42:45]
	v_mfma_f32_16x16x32_bf16 v[30:33], v[102:105], v[180:183], v[30:33]
	v_mfma_f32_16x16x32_bf16 v[26:29], v[110:113], v[180:183], v[26:29]
	v_mfma_f32_16x16x32_bf16 v[22:25], v[102:105], v[188:191], v[22:25]
	v_mfma_f32_16x16x32_bf16 v[18:21], v[110:113], v[188:191], v[18:21]
	v_mfma_f32_16x16x32_bf16 v[54:57], v[192:195], v[152:155], v[54:57]
	v_mfma_f32_16x16x32_bf16 v[50:53], v[200:203], v[152:155], v[50:53]
	v_mfma_f32_16x16x32_bf16 v[38:41], v[192:195], v[164:167], v[38:41]
	v_mfma_f32_16x16x32_bf16 v[34:37], v[200:203], v[164:167], v[34:37]
	v_mfma_f32_16x16x32_bf16 v[14:17], v[192:195], v[176:179], v[14:17]
	v_mfma_f32_16x16x32_bf16 v[10:13], v[200:203], v[176:179], v[10:13]
	v_mfma_f32_16x16x32_bf16 v[6:9], v[192:195], v[184:187], v[6:9]
	v_mfma_f32_16x16x32_bf16 v[2:5], v[200:203], v[184:187], v[2:5]
	v_mfma_f32_16x16x32_bf16 v[54:57], v[196:199], v[160:163], v[54:57]
	v_mfma_f32_16x16x32_bf16 v[50:53], v[204:207], v[160:163], v[50:53]
	v_mfma_f32_16x16x32_bf16 v[38:41], v[196:199], v[172:175], v[38:41]
	v_mfma_f32_16x16x32_bf16 v[34:37], v[204:207], v[172:175], v[34:37]
	v_mfma_f32_16x16x32_bf16 v[14:17], v[196:199], v[180:183], v[14:17]
	v_mfma_f32_16x16x32_bf16 v[10:13], v[204:207], v[180:183], v[10:13]
	v_mfma_f32_16x16x32_bf16 v[6:9], v[196:199], v[188:191], v[6:9]
	v_mfma_f32_16x16x32_bf16 v[2:5], v[204:207], v[188:191], v[2:5]
	s_add_i32 s81, s81, 2
	s_add_u32 s79, s79, 0x100
	s_addc_u32 s80, s80, 0
	s_cmp_gt_u32 s81, 29
	s_mov_b64 s[28:29], s[56:57]
	s_barrier
	s_cbranch_scc0 .LBB0_99
	s_cmp_lt_i32 s8, 64
	s_cselect_b64 s[58:59], -1, 0
	s_cmp_gt_i32 s8, 63
	s_cbranch_scc0 .LBB0_90
	s_mov_b64 s[60:61], 0x18000
	s_mov_b64 s[28:29], s[46:47]
	s_mov_b64 s[56:57], s[24:25]
	s_branch .LBB0_91

; #define PG8_STAGE(bufoff, gbase, voff) do { _Pragma("unroll") for (int _i = 0; _i < 2; ++_i) \
;         __builtin_amdgcn_global_load_lds((const unsigned*)((const char*)(gbase) + (voff)[_i]), (LAS unsigned*)(lds + (bufoff) + ldsw + _i * 8192), 16, 0, 0); } while (0)
; #define PG8_LDA(dst, b, h) do { _Pragma("unroll") for (int m = 0; m < 4; ++m) _Pragma("unroll") for (int k = 0; k < 2; ++k) dst[m][k] = *(const LAS bf16x8*)(lds + PG8_SA(b, h) + aoff + m * 2048 + k * 1024); } while (0)
; #define PG8_LDB(dst, b, h) do { _Pragma("unroll") for (int n = 0; n < 2; ++n) _Pragma("unroll") for (int k = 0; k < 2; ++k) dst[n][k] = *(const LAS bf16x8*)(lds + PG8_SB(b, h) + boff + n * 2048 + k * 1024); } while (0)
; #define PG8_MMA(ai, bj, At, Bt) do { __builtin_amdgcn_s_setprio(1); _Pragma("unroll") for (int m = 0; m < 4; ++m) _Pragma("unroll") for (int n = 0; n < 2; ++n) _Pragma("unroll") for (int k = 0; k < 2; ++k) \
;         acc[ai][bj][m][n] = __builtin_amdgcn_mfma_f32_16x16x32_bf16(Bt[n][k], At[m][k], acc[ai][bj][m][n], 0, 0, 0); __builtin_amdgcn_s_setprio(0); } while (0)
; #define PG8_WAIT_L(n) asm volatile("s_waitcnt lgkmcnt(" #n ")" ::: "memory")
; #define PG8_BAR __builtin_amdgcn_s_barrier()
; #define PG8_SCHED __builtin_amdgcn_sched_barrier(0)
; template <class Epi, class Sched>
; __device__ __forceinline__ void gemm_phase(LAS unsigned char* lds, const Gemm g, const Sched& S, const Epi& E) {
;     ...
;         for (int t = 0; t < nt; t += 2) {
;             const bool last = (t == nt - 2);
;             const char* a1 = cA + (size_t)(t + 1) * kstep;
;             const char* a2 = last ? nA : cA + (size_t)(t + 2) * kstep; const char* b2 = last ? nB : cB + (size_t)(t + 2) * kstep;
;             const char* a3 = a2 + kstep; const char* b3 = b2 + kstep;
;             PG8_LDB(B0, 0, 0); PG8_SCHED; PG8_LDA(At, 0, 0); PG8_STAGE(PG8_SA(1, 1), a1 + hstep, voffA);
;             PG8_WAIT_L(8); PG8_BAR; PG8_WAIT_L(0); PG8_MMA(0, 0, At, B0); PG8_BAR; PG8_SCHED;
;             PG8_LDB(B1, 0, 1); PG8_STAGE(PG8_SB(0, 0), b2, voffB);
;             PG8_BAR; PG8_WAIT_L(0); PG8_MMA(0, 1, At, B1); PG8_BAR;
;             PG8_LDA(At, 0, 1); PG8_STAGE(PG8_SA(0, 0), a2, voffA);
;             PG8_BAR; PG8_WAIT_L(0); PG8_MMA(1, 0, At, B0); PG8_BAR; PG8_SCHED;
.LBB0_113:
	s_add_u32 s100, s71, 0x7ff80
	s_addc_u32 s101, s72, 0
	v_lshl_add_u64 v[140:141], s[100:101], 0, v[0:1]
	s_add_i32 m0, s65, 0x1c000
	s_nop 0
	global_load_lds_dwordx4 v[140:141], off
	v_lshl_add_u64 v[140:141], s[100:101], 0, v[130:131]
	s_add_i32 m0, s65, 0x1e000
	s_nop 0
	global_load_lds_dwordx4 v[140:141], off
	s_add_u32 s54, s52, 0x100
	s_addc_u32 s55, s53, 0
	s_cmp_eq_u32 s73, 4
	s_cselect_b32 s59, s11, s55
	s_cselect_b32 s58, s29, s54
	s_cselect_b32 s57, s41, s72
	s_cselect_b32 s56, s45, s71
	v_lshl_add_u64 v[156:157], s[52:53], 0, v[134:135]
	s_add_i32 m0, s25, 0xc000
	s_nop 0
	global_load_lds_dwordx4 v[156:157], off
	v_lshl_add_u64 v[156:157], s[52:53], 0, v[132:133]
	s_add_i32 m0, s25, 0xe000
	s_nop 0
	global_load_lds_dwordx4 v[156:157], off
	s_add_i32 s38, 0, 0x10000
	v_add_u32_e32 v152, s38, v137
	ds_read_b128 v[140:143], v152
	ds_read_b128 v[144:147], v152 offset:1024
	ds_read_b128 v[148:151], v152 offset:2048
	ds_read_b128 v[152:155], v152 offset:3072
	ds_read_b128 v[160:163], v139
	ds_read_b128 v[164:167], v139 offset:1024
	ds_read_b128 v[168:171], v139 offset:2048
	ds_read_b128 v[172:175], v139 offset:3072
	ds_read_b128 v[176:179], v139 offset:4096
	ds_read_b128 v[180:183], v139 offset:5120
	ds_read_b128 v[184:187], v139 offset:6144
	ds_read_b128 v[188:191], v139 offset:7168
	s_add_i32 s52, 0, 0x14000
	v_add_u32_e32 v156, s52, v137
	ds_read_b128 v[192:195], v156
	ds_read_b128 v[196:199], v156 offset:1024
	ds_read_b128 v[200:203], v156 offset:2048
	ds_read_b128 v[204:207], v156 offset:3072
	s_waitcnt lgkmcnt(4)
	s_barrier
	s_waitcnt lgkmcnt(0)
	v_mfma_f32_16x16x32_bf16 v[126:129], v[140:143], v[160:163], v[126:129]
	v_mfma_f32_16x16x32_bf16 v[122:125], v[148:151], v[160:163], v[122:125]
	v_mfma_f32_16x16x32_bf16 v[118:121], v[140:143], v[168:171], v[118:121]
	v_mfma_f32_16x16x32_bf16 v[114:117], v[148:151], v[168:171], v[114:117]
	v_mfma_f32_16x16x32_bf16 v[106:109], v[140:143], v[176:179], v[106:109]
	v_mfma_f32_16x16x32_bf16 v[98:101], v[148:151], v[176:179], v[98:101]
	v_mfma_f32_16x16x32_bf16 v[90:93], v[140:143], v[184:187], v[90:93]
	v_mfma_f32_16x16x32_bf16 v[82:85], v[148:151], v[184:187], v[82:85]
	v_mfma_f32_16x16x32_bf16 v[126:129], v[144:147], v[164:167], v[126:129]
	v_mfma_f32_16x16x32_bf16 v[122:125], v[152:155], v[164:167], v[122:125]
	v_mfma_f32_16x16x32_bf16 v[118:121], v[144:147], v[172:175], v[118:121]
	v_mfma_f32_16x16x32_bf16 v[114:117], v[152:155], v[172:175], v[114:117]
	v_mfma_f32_16x16x32_bf16 v[106:109], v[144:147], v[180:183], v[106:109]
	v_mfma_f32_16x16x32_bf16 v[98:101], v[152:155], v[180:183], v[98:101]
	v_mfma_f32_16x16x32_bf16 v[90:93], v[144:147], v[188:191], v[90:93]
	v_mfma_f32_16x16x32_bf16 v[82:85], v[152:155], v[188:191], v[82:85]
	v_mfma_f32_16x16x32_bf16 v[110:113], v[192:195], v[160:163], v[110:113]
	v_mfma_f32_16x16x32_bf16 v[102:105], v[200:203], v[160:163], v[102:105]
	v_mfma_f32_16x16x32_bf16 v[94:97], v[192:195], v[168:171], v[94:97]
	v_mfma_f32_16x16x32_bf16 v[86:89], v[200:203], v[168:171], v[86:89]
	v_mfma_f32_16x16x32_bf16 v[78:81], v[192:195], v[176:179], v[78:81]
	v_mfma_f32_16x16x32_bf16 v[74:77], v[200:203], v[176:179], v[74:77]
	v_mfma_f32_16x16x32_bf16 v[70:73], v[192:195], v[184:187], v[70:73]
	v_mfma_f32_16x16x32_bf16 v[66:69], v[200:203], v[184:187], v[66:69]
	v_mfma_f32_16x16x32_bf16 v[110:113], v[196:199], v[164:167], v[110:113]
	v_mfma_f32_16x16x32_bf16 v[102:105], v[204:207], v[164:167], v[102:105]
	v_mfma_f32_16x16x32_bf16 v[94:97], v[196:199], v[172:175], v[94:97]
	v_mfma_f32_16x16x32_bf16 v[86:89], v[204:207], v[172:175], v[86:89]
	v_mfma_f32_16x16x32_bf16 v[78:81], v[196:199], v[180:183], v[78:81]
	v_mfma_f32_16x16x32_bf16 v[74:77], v[204:207], v[180:183], v[74:77]
	v_mfma_f32_16x16x32_bf16 v[70:73], v[196:199], v[188:191], v[70:73]
	v_mfma_f32_16x16x32_bf16 v[66:69], v[204:207], v[188:191], v[66:69]
	s_barrier
	s_add_i32 s38, s38, s65
	v_lshl_add_u64 v[156:157], s[56:57], 0, v[0:1]
	s_mov_b32 m0, s38
	v_lshl_add_u64 v[210:211], s[56:57], 0, v[130:131]
	global_load_lds_dwordx4 v[156:157], off
	s_add_i32 m0, s38, 0x2000
	s_nop 0
	global_load_lds_dwordx4 v[210:211], off
	s_mov_b32 m0, s25
	v_lshl_add_u64 v[212:213], s[58:59], 0, v[0:1]
	global_load_lds_dwordx4 v[212:213], off
	v_lshl_add_u64 v[214:215], s[58:59], 0, v[130:131]
	s_mov_b32 m0, s27
	s_nop 0
	global_load_lds_dwordx4 v[214:215], off
	ds_read_b128 v[160:163], v139 offset:16384
	ds_read_b128 v[164:167], v139 offset:17408
	ds_read_b128 v[168:171], v139 offset:18432
	ds_read_b128 v[172:175], v139 offset:19456
	ds_read_b128 v[176:179], v139 offset:20480
	ds_read_b128 v[180:183], v139 offset:21504
	ds_read_b128 v[184:187], v139 offset:22528
	ds_read_b128 v[188:191], v139 offset:23552
	s_waitcnt vmcnt(4)
	s_waitcnt lgkmcnt(0)
	s_barrier
; #define PG8_STAGE(bufoff, gbase, voff) do { _Pragma("unroll") for (int _i = 0; _i < 2; ++_i) \
;         __builtin_amdgcn_global_load_lds((const unsigned*)((const char*)(gbase) + (voff)[_i]), (LAS unsigned*)(lds + (bufoff) + ldsw + _i * 8192), 16, 0, 0); } while (0)
; #define PG8_LDA(dst, b, h) do { _Pragma("unroll") for (int m = 0; m < 4; ++m) _Pragma("unroll") for (int k = 0; k < 2; ++k) dst[m][k] = *(const LAS bf16x8*)(lds + PG8_SA(b, h) + aoff + m * 2048 + k * 1024); } while (0)
; #define PG8_MMA(ai, bj, At, Bt) do { __builtin_amdgcn_s_setprio(1); _Pragma("unroll") for (int m = 0; m < 4; ++m) _Pragma("unroll") for (int n = 0; n < 2; ++n) _Pragma("unroll") for (int k = 0; k < 2; ++k) \
;         acc[ai][bj][m][n] = __builtin_amdgcn_mfma_f32_16x16x32_bf16(Bt[n][k], At[m][k], acc[ai][bj][m][n], 0, 0, 0); __builtin_amdgcn_s_setprio(0); } while (0)
; #define PG8_WAIT_V(n) asm volatile("s_waitcnt vmcnt(" #n ")" ::: "memory")
; #define PG8_WAIT_L(n) asm volatile("s_waitcnt lgkmcnt(" #n ")" ::: "memory")
; #define PG8_BAR __builtin_amdgcn_s_barrier()
; #define PG8_SCHED __builtin_amdgcn_sched_barrier(0)
; template <class Epi, class Sched>
; __device__ __forceinline__ void gemm_phase(LAS unsigned char* lds, const Gemm g, const Sched& S, const Epi& E) {
;     ...
;             PG8_BAR; PG8_WAIT_L(0); PG8_MMA(0, 1, At, B1); PG8_BAR;
;             PG8_LDA(At, 0, 1); PG8_STAGE(PG8_SA(0, 0), a2, voffA);
;             PG8_BAR; PG8_WAIT_L(0); PG8_MMA(1, 0, At, B0); PG8_BAR; PG8_SCHED;
;             PG8_STAGE(PG8_SB(0, 1), b2 + hstep, voffB);
;             PG8_WAIT_V(6); PG8_BAR; PG8_MMA(1, 1, At, B1); PG8_BAR;
	v_mfma_f32_16x16x32_bf16 v[62:65], v[140:143], v[160:163], v[62:65]
	v_mfma_f32_16x16x32_bf16 v[58:61], v[148:151], v[160:163], v[58:61]
	v_mfma_f32_16x16x32_bf16 v[54:57], v[140:143], v[168:171], v[54:57]
	v_mfma_f32_16x16x32_bf16 v[50:53], v[148:151], v[168:171], v[50:53]
	v_mfma_f32_16x16x32_bf16 v[38:41], v[140:143], v[176:179], v[38:41]
	v_mfma_f32_16x16x32_bf16 v[34:37], v[148:151], v[176:179], v[34:37]
	v_mfma_f32_16x16x32_bf16 v[22:25], v[140:143], v[184:187], v[22:25]
	v_mfma_f32_16x16x32_bf16 v[18:21], v[148:151], v[184:187], v[18:21]
	v_mfma_f32_16x16x32_bf16 v[62:65], v[144:147], v[164:167], v[62:65]
	v_mfma_f32_16x16x32_bf16 v[58:61], v[152:155], v[164:167], v[58:61]
	v_mfma_f32_16x16x32_bf16 v[54:57], v[144:147], v[172:175], v[54:57]
	v_mfma_f32_16x16x32_bf16 v[50:53], v[152:155], v[172:175], v[50:53]
	v_mfma_f32_16x16x32_bf16 v[38:41], v[144:147], v[180:183], v[38:41]
	v_mfma_f32_16x16x32_bf16 v[34:37], v[152:155], v[180:183], v[34:37]
	v_mfma_f32_16x16x32_bf16 v[22:25], v[144:147], v[188:191], v[22:25]
	v_mfma_f32_16x16x32_bf16 v[18:21], v[152:155], v[188:191], v[18:21]
	v_mfma_f32_16x16x32_bf16 v[46:49], v[192:195], v[160:163], v[46:49]
	v_mfma_f32_16x16x32_bf16 v[42:45], v[200:203], v[160:163], v[42:45]
	v_mfma_f32_16x16x32_bf16 v[30:33], v[192:195], v[168:171], v[30:33]
	v_mfma_f32_16x16x32_bf16 v[26:29], v[200:203], v[168:171], v[26:29]
	v_mfma_f32_16x16x32_bf16 v[14:17], v[192:195], v[176:179], v[14:17]
	v_mfma_f32_16x16x32_bf16 v[10:13], v[200:203], v[176:179], v[10:13]
	v_mfma_f32_16x16x32_bf16 v[6:9], v[192:195], v[184:187], v[6:9]
	v_mfma_f32_16x16x32_bf16 v[2:5], v[200:203], v[184:187], v[2:5]
	v_mfma_f32_16x16x32_bf16 v[46:49], v[196:199], v[164:167], v[46:49]
	v_mfma_f32_16x16x32_bf16 v[42:45], v[204:207], v[164:167], v[42:45]
	v_mfma_f32_16x16x32_bf16 v[30:33], v[196:199], v[172:175], v[30:33]
	v_mfma_f32_16x16x32_bf16 v[26:29], v[204:207], v[172:175], v[26:29]
	v_mfma_f32_16x16x32_bf16 v[14:17], v[196:199], v[180:183], v[14:17]
	v_mfma_f32_16x16x32_bf16 v[10:13], v[204:207], v[180:183], v[10:13]
	v_mfma_f32_16x16x32_bf16 v[6:9], v[196:199], v[188:191], v[6:9]
	v_mfma_f32_16x16x32_bf16 v[2:5], v[204:207], v[188:191], v[2:5]
	s_barrier
	s_add_u32 s38, s56, 0x80000
	s_addc_u32 s39, s57, 0
	s_add_i32 s52, s52, s65
	v_lshl_add_u64 v[140:141], s[38:39], 0, v[0:1]
	s_mov_b32 m0, s52
	s_nop 0
	global_load_lds_dwordx4 v[140:141], off
	v_lshl_add_u64 v[140:141], s[38:39], 0, v[130:131]
	s_add_i32 m0, s52, 0x2000
	s_nop 0
	global_load_lds_dwordx4 v[140:141], off
	s_add_u32 s38, s58, 0x80000
	s_addc_u32 s39, s59, 0
	s_mov_b32 m0, s66
	v_lshl_add_u64 v[192:193], s[38:39], 0, v[0:1]
	global_load_lds_dwordx4 v[192:193], off
	v_lshl_add_u64 v[192:193], s[38:39], 0, v[130:131]
	s_mov_b32 m0, s67
	s_nop 0
	global_load_lds_dwordx4 v[192:193], off
	s_add_i32 s52, 0, 0x18000
	v_add_u32_e32 v152, s52, v137
	ds_read_b128 v[140:143], v152
	ds_read_b128 v[144:147], v152 offset:1024
	ds_read_b128 v[148:151], v152 offset:2048
	ds_read_b128 v[152:155], v152 offset:3072
	ds_read_b128 v[160:163], v139 offset:32768
	ds_read_b128 v[164:167], v139 offset:33792
	ds_read_b128 v[168:171], v139 offset:34816
	ds_read_b128 v[172:175], v139 offset:35840
	ds_read_b128 v[176:179], v139 offset:36864
	ds_read_b128 v[180:183], v139 offset:37888
	ds_read_b128 v[184:187], v139 offset:38912
	ds_read_b128 v[188:191], v139 offset:39936
	s_add_i32 s53, 0, 0x1c000
	v_add_u32_e32 v204, s53, v137
	ds_read_b128 v[192:195], v204
	ds_read_b128 v[196:199], v204 offset:1024
	ds_read_b128 v[200:203], v204 offset:2048
	ds_read_b128 v[204:207], v204 offset:3072
	s_waitcnt lgkmcnt(4)
	s_barrier
	s_waitcnt lgkmcnt(0)
	v_mfma_f32_16x16x32_bf16 v[126:129], v[140:143], v[160:163], v[126:129]
	v_mfma_f32_16x16x32_bf16 v[122:125], v[148:151], v[160:163], v[122:125]
	v_mfma_f32_16x16x32_bf16 v[118:121], v[140:143], v[168:171], v[118:121]
	v_mfma_f32_16x16x32_bf16 v[114:117], v[148:151], v[168:171], v[114:117]
	v_mfma_f32_16x16x32_bf16 v[106:109], v[140:143], v[176:179], v[106:109]
	v_mfma_f32_16x16x32_bf16 v[98:101], v[148:151], v[176:179], v[98:101]
	v_mfma_f32_16x16x32_bf16 v[90:93], v[140:143], v[184:187], v[90:93]
	v_mfma_f32_16x16x32_bf16 v[82:85], v[148:151], v[184:187], v[82:85]
	v_mfma_f32_16x16x32_bf16 v[126:129], v[144:147], v[164:167], v[126:129]
	v_mfma_f32_16x16x32_bf16 v[122:125], v[152:155], v[164:167], v[122:125]
	v_mfma_f32_16x16x32_bf16 v[118:121], v[144:147], v[172:175], v[118:121]
	v_mfma_f32_16x16x32_bf16 v[114:117], v[152:155], v[172:175], v[114:117]
	v_mfma_f32_16x16x32_bf16 v[106:109], v[144:147], v[180:183], v[106:109]
	v_mfma_f32_16x16x32_bf16 v[98:101], v[152:155], v[180:183], v[98:101]
	v_mfma_f32_16x16x32_bf16 v[90:93], v[144:147], v[188:191], v[90:93]
	v_mfma_f32_16x16x32_bf16 v[82:85], v[152:155], v[188:191], v[82:85]
	v_mfma_f32_16x16x32_bf16 v[110:113], v[192:195], v[160:163], v[110:113]
	v_mfma_f32_16x16x32_bf16 v[102:105], v[200:203], v[160:163], v[102:105]
	v_mfma_f32_16x16x32_bf16 v[94:97], v[192:195], v[168:171], v[94:97]
	v_mfma_f32_16x16x32_bf16 v[86:89], v[200:203], v[168:171], v[86:89]
	v_mfma_f32_16x16x32_bf16 v[78:81], v[192:195], v[176:179], v[78:81]
	v_mfma_f32_16x16x32_bf16 v[74:77], v[200:203], v[176:179], v[74:77]
	v_mfma_f32_16x16x32_bf16 v[70:73], v[192:195], v[184:187], v[70:73]
	v_mfma_f32_16x16x32_bf16 v[66:69], v[200:203], v[184:187], v[66:69]
	v_mfma_f32_16x16x32_bf16 v[110:113], v[196:199], v[164:167], v[110:113]
	v_mfma_f32_16x16x32_bf16 v[102:105], v[204:207], v[164:167], v[102:105]
	v_mfma_f32_16x16x32_bf16 v[94:97], v[196:199], v[172:175], v[94:97]
	v_mfma_f32_16x16x32_bf16 v[86:89], v[204:207], v[172:175], v[86:89]
	v_mfma_f32_16x16x32_bf16 v[78:81], v[196:199], v[180:183], v[78:81]
	v_mfma_f32_16x16x32_bf16 v[74:77], v[204:207], v[180:183], v[74:77]
	v_mfma_f32_16x16x32_bf16 v[70:73], v[196:199], v[188:191], v[70:73]
	v_mfma_f32_16x16x32_bf16 v[66:69], v[204:207], v[188:191], v[66:69]
	s_barrier
; #define PG8_STAGE(bufoff, gbase, voff) do { _Pragma("unroll") for (int _i = 0; _i < 2; ++_i) \
;         __builtin_amdgcn_global_load_lds((const unsigned*)((const char*)(gbase) + (voff)[_i]), (LAS unsigned*)(lds + (bufoff) + ldsw + _i * 8192), 16, 0, 0); } while (0)
; #define PG8_LDA(dst, b, h) do { _Pragma("unroll") for (int m = 0; m < 4; ++m) _Pragma("unroll") for (int k = 0; k < 2; ++k) dst[m][k] = *(const LAS bf16x8*)(lds + PG8_SA(b, h) + aoff + m * 2048 + k * 1024); } while (0)
; #define PG8_LDB(dst, b, h) do { _Pragma("unroll") for (int n = 0; n < 2; ++n) _Pragma("unroll") for (int k = 0; k < 2; ++k) dst[n][k] = *(const LAS bf16x8*)(lds + PG8_SB(b, h) + boff + n * 2048 + k * 1024); } while (0)
; #define PG8_WAIT_V(n) asm volatile("s_waitcnt vmcnt(" #n ")" ::: "memory")
; #define PG8_BAR __builtin_amdgcn_s_barrier()
;     __device__ __forceinline__ void operator()(const f32x4 (&acc)[2][2][4][2], const Unit& u, int wr, int wc, int fr, int fq) const {
;         const int row0 = u.pm * BM + wr * 64 + fr, col0 = u.pn * BM + wc * 32 + 4 * fq;
;         float* base = part + (size_t)u.ks * Mp * ldc;
; #pragma unroll
;         for (int ai = 0; ai < 2; ++ai)
; #pragma unroll
;             for (int m = 0; m < 4; ++m) { float* rowp = base + (size_t)(row0 + ai * HALF + m * 16) * ldc + col0;
; #pragma unroll
;                 for (int bj = 0; bj < 2; ++bj)
; #pragma unroll
;                     for (int n = 0; n < 2; ++n) *(f32x4*)(rowp + bj * HALF + n * 16) = acc[ai][bj][m][n]; }
;     }
; template <class Epi, class Sched>
; __device__ __forceinline__ void gemm_phase(LAS unsigned char* lds, const Gemm g, const Sched& S, const Epi& E) {
;     ...
;             PG8_WAIT_V(6); PG8_BAR; PG8_MMA(1, 1, At, B1); PG8_BAR;
;             PG8_LDB(B0, 1, 0); PG8_SCHED; PG8_LDA(At, 1, 0); PG8_STAGE(PG8_SA(0, 1), a2 + hstep, voffA);
;             PG8_WAIT_L(8); PG8_BAR; PG8_WAIT_L(0); PG8_MMA(0, 0, At, B0); PG8_BAR; PG8_SCHED;
;             PG8_LDB(B1, 1, 1); PG8_STAGE(PG8_SB(1, 0), b3, voffB);
;             PG8_BAR; PG8_WAIT_L(0); PG8_MMA(0, 1, At, B1); PG8_BAR;
;             PG8_LDA(At, 1, 1); PG8_STAGE(PG8_SA(1, 0), a3, voffA);
;             PG8_BAR; PG8_WAIT_L(0); PG8_MMA(1, 0, At, B0); PG8_BAR; PG8_SCHED;
;             PG8_STAGE(PG8_SB(1, 1), b3 + hstep, voffB);
;             PG8_WAIT_V(6); PG8_BAR; PG8_MMA(1, 1, At, B1); PG8_BAR;
;         }
;         E(acc, cur, wr, wc, fr, fq);
	s_add_i32 s38, s52, s65
	v_lshl_add_u64 v[156:157], v[156:157], 0, s[36:37]
	s_mov_b32 m0, s38
	s_nop 0
	global_load_lds_dwordx4 v[156:157], off
	v_lshl_add_u64 v[156:157], v[210:211], 0, s[36:37]
	s_add_i32 m0, s38, 0x2000
	s_nop 0
	global_load_lds_dwordx4 v[156:157], off
	s_mov_b32 m0, s68
	v_lshl_add_u64 v[156:157], v[212:213], 0, s[36:37]
	global_load_lds_dwordx4 v[156:157], off
	v_lshl_add_u64 v[156:157], v[214:215], 0, s[36:37]
	s_mov_b32 m0, s69
	s_nop 0
	global_load_lds_dwordx4 v[156:157], off
	ds_read_b128 v[160:163], v139 offset:49152
	ds_read_b128 v[164:167], v139 offset:50176
	ds_read_b128 v[168:171], v139 offset:51200
	ds_read_b128 v[172:175], v139 offset:52224
	ds_read_b128 v[176:179], v139 offset:53248
	ds_read_b128 v[180:183], v139 offset:54272
	ds_read_b128 v[184:187], v139 offset:55296
	ds_read_b128 v[188:191], v139 offset:56320
	s_waitcnt vmcnt(4)
	s_waitcnt lgkmcnt(0)
	s_barrier
	v_mfma_f32_16x16x32_bf16 v[62:65], v[140:143], v[160:163], v[62:65]
	v_mfma_f32_16x16x32_bf16 v[58:61], v[148:151], v[160:163], v[58:61]
	v_mfma_f32_16x16x32_bf16 v[54:57], v[140:143], v[168:171], v[54:57]
	v_mfma_f32_16x16x32_bf16 v[50:53], v[148:151], v[168:171], v[50:53]
	v_mfma_f32_16x16x32_bf16 v[38:41], v[140:143], v[176:179], v[38:41]
	v_mfma_f32_16x16x32_bf16 v[34:37], v[148:151], v[176:179], v[34:37]
	v_mfma_f32_16x16x32_bf16 v[22:25], v[140:143], v[184:187], v[22:25]
	v_mfma_f32_16x16x32_bf16 v[18:21], v[148:151], v[184:187], v[18:21]
	v_mfma_f32_16x16x32_bf16 v[62:65], v[144:147], v[164:167], v[62:65]
	v_mfma_f32_16x16x32_bf16 v[58:61], v[152:155], v[164:167], v[58:61]
	v_mfma_f32_16x16x32_bf16 v[54:57], v[144:147], v[172:175], v[54:57]
	v_mfma_f32_16x16x32_bf16 v[50:53], v[152:155], v[172:175], v[50:53]
	v_mfma_f32_16x16x32_bf16 v[38:41], v[144:147], v[180:183], v[38:41]
	v_mfma_f32_16x16x32_bf16 v[34:37], v[152:155], v[180:183], v[34:37]
	v_mfma_f32_16x16x32_bf16 v[22:25], v[144:147], v[188:191], v[22:25]
	v_mfma_f32_16x16x32_bf16 v[18:21], v[152:155], v[188:191], v[18:21]
	v_mfma_f32_16x16x32_bf16 v[46:49], v[192:195], v[160:163], v[46:49]
	v_mfma_f32_16x16x32_bf16 v[42:45], v[200:203], v[160:163], v[42:45]
	v_mfma_f32_16x16x32_bf16 v[30:33], v[192:195], v[168:171], v[30:33]
	v_mfma_f32_16x16x32_bf16 v[26:29], v[200:203], v[168:171], v[26:29]
	v_mfma_f32_16x16x32_bf16 v[14:17], v[192:195], v[176:179], v[14:17]
	v_mfma_f32_16x16x32_bf16 v[10:13], v[200:203], v[176:179], v[10:13]
	v_mfma_f32_16x16x32_bf16 v[6:9], v[192:195], v[184:187], v[6:9]
	v_mfma_f32_16x16x32_bf16 v[2:5], v[200:203], v[184:187], v[2:5]
	v_mfma_f32_16x16x32_bf16 v[46:49], v[196:199], v[164:167], v[46:49]
	v_mfma_f32_16x16x32_bf16 v[42:45], v[204:207], v[164:167], v[42:45]
	v_mfma_f32_16x16x32_bf16 v[30:33], v[196:199], v[172:175], v[30:33]
	v_mfma_f32_16x16x32_bf16 v[26:29], v[204:207], v[172:175], v[26:29]
	v_mfma_f32_16x16x32_bf16 v[14:17], v[196:199], v[180:183], v[14:17]
	v_mfma_f32_16x16x32_bf16 v[10:13], v[204:207], v[180:183], v[10:13]
	v_mfma_f32_16x16x32_bf16 v[6:9], v[196:199], v[188:191], v[6:9]
	v_mfma_f32_16x16x32_bf16 v[2:5], v[204:207], v[188:191], v[2:5]
	s_add_i32 s73, s73, 2
	s_add_u32 s71, s71, 0x100
	s_addc_u32 s72, s72, 0
	s_cmp_gt_u32 s73, 5
	s_mov_b64 s[52:53], s[54:55]
	s_barrier
	s_cbranch_scc0 .LBB0_113
	s_ashr_i32 s11, s10, 31
	s_lshl_b64 s[10:11], s[10:11], 24
	v_lshl_or_b32 v140, s26, 8, v138
	s_add_u32 s10, s8, s10
	v_lshl_add_u32 v142, s24, 8, v136
	s_addc_u32 s11, s9, s11
	v_ashrrev_i32_e32 v141, 31, v140
	v_ashrrev_i32_e32 v143, 31, v142
	v_lshl_add_u64 v[140:141], v[140:141], 2, s[10:11]
	v_lshlrev_b64 v[144:145], 13, v[142:143]
	v_lshl_add_u64 v[144:145], v[140:141], 0, v[144:145]
	global_store_dwordx4 v[144:145], v[126:129], off
	global_store_dwordx4 v[144:145], v[122:125], off offset:64
	global_store_dwordx4 v[144:145], v[110:113], off offset:512
	global_store_dwordx4 v[144:145], v[102:105], off offset:576
	s_mov_b64 s[10:11], 0x100000
	s_mov_b32 s26, s40
	v_or_b32_e32 v102, 16, v142
	v_ashrrev_i32_e32 v103, 31, v102
	v_lshlrev_b64 v[102:103], 13, v[102:103]
	v_lshl_add_u64 v[102:103], v[140:141], 0, v[102:103]
	global_store_dwordx4 v[102:103], v[118:121], off
	global_store_dwordx4 v[102:103], v[114:117], off offset:64
	global_store_dwordx4 v[102:103], v[94:97], off offset:512
	global_store_dwordx4 v[102:103], v[86:89], off offset:576
	s_mov_b32 s24, s44
	s_mov_b64 s[54:55], s[50:51]
	v_or_b32_e32 v86, 32, v142
	v_ashrrev_i32_e32 v87, 31, v86
	v_lshlrev_b64 v[86:87], 13, v[86:87]
	v_lshl_add_u64 v[86:87], v[140:141], 0, v[86:87]
	global_store_dwordx4 v[86:87], v[106:109], off
	global_store_dwordx4 v[86:87], v[98:101], off offset:64
	global_store_dwordx4 v[86:87], v[78:81], off offset:512
	global_store_dwordx4 v[86:87], v[74:77], off offset:576
	s_mov_b64 s[52:53], s[48:49]
	s_nop 0
	v_or_b32_e32 v74, 48, v142
	v_ashrrev_i32_e32 v75, 31, v74
	v_lshlrev_b64 v[74:75], 13, v[74:75]
	v_lshl_add_u64 v[74:75], v[140:141], 0, v[74:75]
	global_store_dwordx4 v[74:75], v[90:93], off
	global_store_dwordx4 v[74:75], v[82:85], off offset:64
	global_store_dwordx4 v[74:75], v[70:73], off offset:512
	global_store_dwordx4 v[74:75], v[66:69], off offset:576
	s_nop 1
	v_add_co_u32_e32 v68, vcc, s93, v144
	v_lshl_add_u64 v[66:67], v[144:145], 0, s[10:11]
	s_nop 0
	v_addc_co_u32_e32 v69, vcc, 0, v145, vcc
	s_mov_b64 s[10:11], 0x120000
	global_store_dwordx4 v[68:69], v[62:65], off
	global_store_dwordx4 v[66:67], v[58:61], off offset:64
	global_store_dwordx4 v[66:67], v[46:49], off offset:512
	global_store_dwordx4 v[66:67], v[42:45], off offset:576
	s_nop 1
	v_lshl_add_u64 v[42:43], v[144:145], 0, s[10:11]
	s_mov_b32 s10, 0x120000
	v_add_co_u32_e32 v44, vcc, s10, v144
	s_mov_b64 s[10:11], 0x140000
	s_nop 0
	v_addc_co_u32_e32 v45, vcc, 0, v145, vcc
	global_store_dwordx4 v[44:45], v[54:57], off
	global_store_dwordx4 v[42:43], v[50:53], off offset:64
	global_store_dwordx4 v[42:43], v[30:33], off offset:512
	global_store_dwordx4 v[42:43], v[26:29], off offset:576
	s_nop 1
	v_lshl_add_u64 v[26:27], v[144:145], 0, s[10:11]
	s_mov_b32 s10, 0x140000
	v_add_co_u32_e32 v28, vcc, s10, v144
	s_mov_b64 s[10:11], 0x160000
	s_nop 0
	v_addc_co_u32_e32 v29, vcc, 0, v145, vcc
	global_store_dwordx4 v[28:29], v[38:41], off
	global_store_dwordx4 v[26:27], v[34:37], off offset:64
	global_store_dwordx4 v[26:27], v[14:17], off offset:512
	global_store_dwordx4 v[26:27], v[10:13], off offset:576
	s_nop 1
	v_add_co_u32_e32 v12, vcc, 0x160000, v144
	v_lshl_add_u64 v[10:11], v[144:145], 0, s[10:11]
	s_nop 0
	v_addc_co_u32_e32 v13, vcc, 0, v145, vcc
	s_and_b64 vcc, exec, s[46:47]
	s_mov_b32 s10, s28
	global_store_dwordx4 v[12:13], v[22:25], off
	global_store_dwordx4 v[10:11], v[18:21], off offset:64
	global_store_dwordx4 v[10:11], v[6:9], off offset:512
	global_store_dwordx4 v[10:11], v[2:5], off offset:576
	s_cbranch_vccz .LBB0_110
	s_waitcnt vmcnt(0)
	s_cmpk_gt_u32 s60, 0xff
	s_cbranch_scc1 .LBB0_117
	s_barrier

; #define PG8_STAGE(bufoff, gbase, voff) do { _Pragma("unroll") for (int _i = 0; _i < 2; ++_i) \
;         __builtin_amdgcn_global_load_lds((const unsigned*)((const char*)(gbase) + (voff)[_i]), (LAS unsigned*)(lds + (bufoff) + ldsw + _i * 8192), 16, 0, 0); } while (0)
; #define PG8_LDA(dst, b, h) do { _Pragma("unroll") for (int m = 0; m < 4; ++m) _Pragma("unroll") for (int k = 0; k < 2; ++k) dst[m][k] = *(const LAS bf16x8*)(lds + PG8_SA(b, h) + aoff + m * 2048 + k * 1024); } while (0)
; #define PG8_LDB(dst, b, h) do { _Pragma("unroll") for (int n = 0; n < 2; ++n) _Pragma("unroll") for (int k = 0; k < 2; ++k) dst[n][k] = *(const LAS bf16x8*)(lds + PG8_SB(b, h) + boff + n * 2048 + k * 1024); } while (0)
; #define PG8_MMA(ai, bj, At, Bt) do { __builtin_amdgcn_s_setprio(1); _Pragma("unroll") for (int m = 0; m < 4; ++m) _Pragma("unroll") for (int n = 0; n < 2; ++n) _Pragma("unroll") for (int k = 0; k < 2; ++k) \
;         acc[ai][bj][m][n] = __builtin_amdgcn_mfma_f32_16x16x32_bf16(Bt[n][k], At[m][k], acc[ai][bj][m][n], 0, 0, 0); __builtin_amdgcn_s_setprio(0); } while (0)
; #define PG8_WAIT_L(n) asm volatile("s_waitcnt lgkmcnt(" #n ")" ::: "memory")
; #define PG8_BAR __builtin_amdgcn_s_barrier()
; #define PG8_SCHED __builtin_amdgcn_sched_barrier(0)
; template <class Epi, class Sched>
; __device__ __forceinline__ void gemm_phase(LAS unsigned char* lds, const Gemm g, const Sched& S, const Epi& E) {
;     ...
;         for (int t = 0; t < nt; t += 2) {
;             const bool last = (t == nt - 2);
;             const char* a1 = cA + (size_t)(t + 1) * kstep;
;             const char* a2 = last ? nA : cA + (size_t)(t + 2) * kstep; const char* b2 = last ? nB : cB + (size_t)(t + 2) * kstep;
;             const char* a3 = a2 + kstep; const char* b3 = b2 + kstep;
;             PG8_LDB(B0, 0, 0); PG8_SCHED; PG8_LDA(At, 0, 0); PG8_STAGE(PG8_SA(1, 1), a1 + hstep, voffA);
;             PG8_WAIT_L(8); PG8_BAR; PG8_WAIT_L(0); PG8_MMA(0, 0, At, B0); PG8_BAR; PG8_SCHED;
;             PG8_LDB(B1, 0, 1); PG8_STAGE(PG8_SB(0, 0), b2, voffB);
;             PG8_BAR; PG8_WAIT_L(0); PG8_MMA(0, 1, At, B1); PG8_BAR;
;             PG8_LDA(At, 0, 1); PG8_STAGE(PG8_SA(0, 0), a2, voffA);
;             PG8_BAR; PG8_WAIT_L(0); PG8_MMA(1, 0, At, B0); PG8_BAR; PG8_SCHED;
.LBB0_354:
	s_add_u32 s100, s68, 0x7ff80
	s_addc_u32 s101, s69, 0
	v_lshl_add_u64 v[140:141], s[100:101], 0, v[0:1]
	s_add_i32 m0, s56, 0x1c000
	s_nop 0
	global_load_lds_dwordx4 v[140:141], off
	v_lshl_add_u64 v[140:141], s[100:101], 0, v[134:135]
	s_add_i32 m0, s56, 0x1e000
	s_nop 0
	global_load_lds_dwordx4 v[140:141], off
	s_add_u32 s38, s50, 0xfff80080
	s_addc_u32 s39, s51, -1
	s_cmp_eq_u32 s70, 28
	s_cselect_b32 s55, s9, s39
	s_cselect_b32 s54, s66, s38
	s_cselect_b32 s53, s43, s69
	s_cselect_b32 s52, s67, s68
	v_lshl_add_u64 v[156:157], s[50:51], 0, v[138:139]
	s_add_i32 m0, s29, 0xc000
	s_nop 0
	global_load_lds_dwordx4 v[156:157], off
	v_lshl_add_u64 v[156:157], s[50:51], 0, v[136:137]
	s_add_i32 m0, s29, 0xe000
	s_nop 0
	global_load_lds_dwordx4 v[156:157], off
	s_add_i32 s71, 0, 0x10000
	v_add_u32_e32 v156, s71, v145
	ds_read_b128 v[140:143], v156
	ds_read_b128 v[148:151], v156 offset:1024
	ds_read_b128 v[152:155], v156 offset:2048
	ds_read_b128 v[160:163], v156 offset:3072
	ds_read_b128 v[164:167], v147
	ds_read_b128 v[168:171], v147 offset:1024
	ds_read_b128 v[172:175], v147 offset:2048
	ds_read_b128 v[176:179], v147 offset:3072
	ds_read_b128 v[180:183], v147 offset:4096
	ds_read_b128 v[184:187], v147 offset:5120
	ds_read_b128 v[188:191], v147 offset:6144
	ds_read_b128 v[192:195], v147 offset:7168
	s_add_i32 s38, 0, 0x14000
	v_add_u32_e32 v156, s38, v145
	ds_read_b128 v[196:199], v156
	ds_read_b128 v[200:203], v156 offset:1024
	ds_read_b128 v[204:207], v156 offset:2048
	ds_read_b128 v[210:213], v156 offset:3072
	s_waitcnt lgkmcnt(4)
	s_barrier
	s_waitcnt lgkmcnt(0)
	v_mfma_f32_16x16x32_bf16 v[126:129], v[140:143], v[164:167], v[126:129]
	v_mfma_f32_16x16x32_bf16 v[122:125], v[152:155], v[164:167], v[122:125]
	v_mfma_f32_16x16x32_bf16 v[118:121], v[140:143], v[172:175], v[118:121]
	v_mfma_f32_16x16x32_bf16 v[110:113], v[152:155], v[172:175], v[110:113]
	v_mfma_f32_16x16x32_bf16 v[102:105], v[140:143], v[180:183], v[102:105]
	v_mfma_f32_16x16x32_bf16 v[94:97], v[152:155], v[180:183], v[94:97]
	v_mfma_f32_16x16x32_bf16 v[86:89], v[140:143], v[188:191], v[86:89]
	v_mfma_f32_16x16x32_bf16 v[78:81], v[152:155], v[188:191], v[78:81]
	v_mfma_f32_16x16x32_bf16 v[126:129], v[148:151], v[168:171], v[126:129]
	v_mfma_f32_16x16x32_bf16 v[122:125], v[160:163], v[168:171], v[122:125]
	v_mfma_f32_16x16x32_bf16 v[118:121], v[148:151], v[176:179], v[118:121]
	v_mfma_f32_16x16x32_bf16 v[110:113], v[160:163], v[176:179], v[110:113]
	v_mfma_f32_16x16x32_bf16 v[102:105], v[148:151], v[184:187], v[102:105]
	v_mfma_f32_16x16x32_bf16 v[94:97], v[160:163], v[184:187], v[94:97]
	v_mfma_f32_16x16x32_bf16 v[86:89], v[148:151], v[192:195], v[86:89]
	v_mfma_f32_16x16x32_bf16 v[78:81], v[160:163], v[192:195], v[78:81]
	v_mfma_f32_16x16x32_bf16 v[114:117], v[196:199], v[164:167], v[114:117]
	v_mfma_f32_16x16x32_bf16 v[106:109], v[204:207], v[164:167], v[106:109]
	v_mfma_f32_16x16x32_bf16 v[98:101], v[196:199], v[172:175], v[98:101]
	v_mfma_f32_16x16x32_bf16 v[90:93], v[204:207], v[172:175], v[90:93]
	v_mfma_f32_16x16x32_bf16 v[82:85], v[196:199], v[180:183], v[82:85]
	v_mfma_f32_16x16x32_bf16 v[74:77], v[204:207], v[180:183], v[74:77]
	v_mfma_f32_16x16x32_bf16 v[70:73], v[196:199], v[188:191], v[70:73]
	v_mfma_f32_16x16x32_bf16 v[66:69], v[204:207], v[188:191], v[66:69]
	v_mfma_f32_16x16x32_bf16 v[114:117], v[200:203], v[168:171], v[114:117]
	v_mfma_f32_16x16x32_bf16 v[106:109], v[210:213], v[168:171], v[106:109]
	v_mfma_f32_16x16x32_bf16 v[98:101], v[200:203], v[176:179], v[98:101]
	v_mfma_f32_16x16x32_bf16 v[90:93], v[210:213], v[176:179], v[90:93]
	v_mfma_f32_16x16x32_bf16 v[82:85], v[200:203], v[184:187], v[82:85]
	v_mfma_f32_16x16x32_bf16 v[74:77], v[210:213], v[184:187], v[74:77]
	v_mfma_f32_16x16x32_bf16 v[70:73], v[200:203], v[192:195], v[70:73]
	v_mfma_f32_16x16x32_bf16 v[66:69], v[210:213], v[192:195], v[66:69]
	s_barrier
	s_add_i32 s39, s71, s56
	v_lshl_add_u64 v[156:157], s[52:53], 0, v[0:1]
	s_mov_b32 m0, s39
	v_lshl_add_u64 v[214:215], s[52:53], 0, v[134:135]
	global_load_lds_dwordx4 v[156:157], off
	s_add_i32 m0, s39, 0x2000
	s_nop 0
	global_load_lds_dwordx4 v[214:215], off
	s_mov_b32 m0, s29
	v_lshl_add_u64 v[216:217], s[54:55], 0, v[130:131]
	global_load_lds_dwordx4 v[216:217], off
	v_lshl_add_u64 v[224:225], s[54:55], 0, v[132:133]
	s_mov_b32 m0, s41
	s_nop 0
	global_load_lds_dwordx4 v[224:225], off
	ds_read_b128 v[164:167], v147 offset:16384
	ds_read_b128 v[168:171], v147 offset:17408
	ds_read_b128 v[172:175], v147 offset:18432
	ds_read_b128 v[176:179], v147 offset:19456
	ds_read_b128 v[180:183], v147 offset:20480
	ds_read_b128 v[184:187], v147 offset:21504
	ds_read_b128 v[188:191], v147 offset:22528
	ds_read_b128 v[192:195], v147 offset:23552
	s_waitcnt vmcnt(4)
	s_waitcnt lgkmcnt(0)
	s_barrier
; #define PG8_STAGE(bufoff, gbase, voff) do { _Pragma("unroll") for (int _i = 0; _i < 2; ++_i) \
;         __builtin_amdgcn_global_load_lds((const unsigned*)((const char*)(gbase) + (voff)[_i]), (LAS unsigned*)(lds + (bufoff) + ldsw + _i * 8192), 16, 0, 0); } while (0)
; #define PG8_LDA(dst, b, h) do { _Pragma("unroll") for (int m = 0; m < 4; ++m) _Pragma("unroll") for (int k = 0; k < 2; ++k) dst[m][k] = *(const LAS bf16x8*)(lds + PG8_SA(b, h) + aoff + m * 2048 + k * 1024); } while (0)
; #define PG8_MMA(ai, bj, At, Bt) do { __builtin_amdgcn_s_setprio(1); _Pragma("unroll") for (int m = 0; m < 4; ++m) _Pragma("unroll") for (int n = 0; n < 2; ++n) _Pragma("unroll") for (int k = 0; k < 2; ++k) \
;         acc[ai][bj][m][n] = __builtin_amdgcn_mfma_f32_16x16x32_bf16(Bt[n][k], At[m][k], acc[ai][bj][m][n], 0, 0, 0); __builtin_amdgcn_s_setprio(0); } while (0)
; #define PG8_WAIT_V(n) asm volatile("s_waitcnt vmcnt(" #n ")" ::: "memory")
; #define PG8_WAIT_L(n) asm volatile("s_waitcnt lgkmcnt(" #n ")" ::: "memory")
; #define PG8_BAR __builtin_amdgcn_s_barrier()
; #define PG8_SCHED __builtin_amdgcn_sched_barrier(0)
; template <class Epi, class Sched>
; __device__ __forceinline__ void gemm_phase(LAS unsigned char* lds, const Gemm g, const Sched& S, const Epi& E) {
;     ...
;             PG8_BAR; PG8_WAIT_L(0); PG8_MMA(0, 1, At, B1); PG8_BAR;
;             PG8_LDA(At, 0, 1); PG8_STAGE(PG8_SA(0, 0), a2, voffA);
;             PG8_BAR; PG8_WAIT_L(0); PG8_MMA(1, 0, At, B0); PG8_BAR; PG8_SCHED;
;             PG8_STAGE(PG8_SB(0, 1), b2 + hstep, voffB);
;             PG8_WAIT_V(6); PG8_BAR; PG8_MMA(1, 1, At, B1); PG8_BAR;
	v_mfma_f32_16x16x32_bf16 v[62:65], v[140:143], v[164:167], v[62:65]
	v_mfma_f32_16x16x32_bf16 v[58:61], v[152:155], v[164:167], v[58:61]
	v_mfma_f32_16x16x32_bf16 v[54:57], v[140:143], v[172:175], v[54:57]
	v_mfma_f32_16x16x32_bf16 v[46:49], v[152:155], v[172:175], v[46:49]
	v_mfma_f32_16x16x32_bf16 v[38:41], v[140:143], v[180:183], v[38:41]
	v_mfma_f32_16x16x32_bf16 v[30:33], v[152:155], v[180:183], v[30:33]
	v_mfma_f32_16x16x32_bf16 v[22:25], v[140:143], v[188:191], v[22:25]
	v_mfma_f32_16x16x32_bf16 v[14:17], v[152:155], v[188:191], v[14:17]
	v_mfma_f32_16x16x32_bf16 v[62:65], v[148:151], v[168:171], v[62:65]
	v_mfma_f32_16x16x32_bf16 v[58:61], v[160:163], v[168:171], v[58:61]
	v_mfma_f32_16x16x32_bf16 v[54:57], v[148:151], v[176:179], v[54:57]
	v_mfma_f32_16x16x32_bf16 v[46:49], v[160:163], v[176:179], v[46:49]
	v_mfma_f32_16x16x32_bf16 v[38:41], v[148:151], v[184:187], v[38:41]
	v_mfma_f32_16x16x32_bf16 v[30:33], v[160:163], v[184:187], v[30:33]
	v_mfma_f32_16x16x32_bf16 v[22:25], v[148:151], v[192:195], v[22:25]
	v_mfma_f32_16x16x32_bf16 v[14:17], v[160:163], v[192:195], v[14:17]
	v_mfma_f32_16x16x32_bf16 v[50:53], v[196:199], v[164:167], v[50:53]
	v_mfma_f32_16x16x32_bf16 v[42:45], v[204:207], v[164:167], v[42:45]
	v_mfma_f32_16x16x32_bf16 v[34:37], v[196:199], v[172:175], v[34:37]
	v_mfma_f32_16x16x32_bf16 v[26:29], v[204:207], v[172:175], v[26:29]
	v_mfma_f32_16x16x32_bf16 v[18:21], v[196:199], v[180:183], v[18:21]
	v_mfma_f32_16x16x32_bf16 v[10:13], v[204:207], v[180:183], v[10:13]
	v_mfma_f32_16x16x32_bf16 v[6:9], v[196:199], v[188:191], v[6:9]
	v_mfma_f32_16x16x32_bf16 v[2:5], v[204:207], v[188:191], v[2:5]
	v_mfma_f32_16x16x32_bf16 v[50:53], v[200:203], v[168:171], v[50:53]
	v_mfma_f32_16x16x32_bf16 v[42:45], v[210:213], v[168:171], v[42:45]
	v_mfma_f32_16x16x32_bf16 v[34:37], v[200:203], v[176:179], v[34:37]
	v_mfma_f32_16x16x32_bf16 v[26:29], v[210:213], v[176:179], v[26:29]
	v_mfma_f32_16x16x32_bf16 v[18:21], v[200:203], v[184:187], v[18:21]
	v_mfma_f32_16x16x32_bf16 v[10:13], v[210:213], v[184:187], v[10:13]
	v_mfma_f32_16x16x32_bf16 v[6:9], v[200:203], v[192:195], v[6:9]
	v_mfma_f32_16x16x32_bf16 v[2:5], v[210:213], v[192:195], v[2:5]
	s_barrier
	s_add_u32 s72, s52, 0x80000
	s_addc_u32 s73, s53, 0
	s_add_i32 s38, s38, s56
	v_lshl_add_u64 v[140:141], s[72:73], 0, v[0:1]
	s_mov_b32 m0, s38
	s_nop 0
	global_load_lds_dwordx4 v[140:141], off
	v_lshl_add_u64 v[140:141], s[72:73], 0, v[134:135]
	s_add_i32 m0, s38, 0x2000
	s_nop 0
	global_load_lds_dwordx4 v[140:141], off
	s_add_u32 s54, s54, 0x80000
	s_addc_u32 s55, s55, 0
	s_mov_b32 m0, s57
	v_lshl_add_u64 v[196:197], s[54:55], 0, v[130:131]
	global_load_lds_dwordx4 v[196:197], off
	v_lshl_add_u64 v[196:197], s[54:55], 0, v[132:133]
	s_mov_b32 m0, s58
	s_nop 0
	global_load_lds_dwordx4 v[196:197], off
	s_add_i32 s38, 0, 0x18000
	v_add_u32_e32 v160, s38, v145
	ds_read_b128 v[140:143], v160
	ds_read_b128 v[148:151], v160 offset:1024
	ds_read_b128 v[152:155], v160 offset:2048
	ds_read_b128 v[160:163], v160 offset:3072
	ds_read_b128 v[164:167], v147 offset:32768
	ds_read_b128 v[168:171], v147 offset:33792
	ds_read_b128 v[172:175], v147 offset:34816
	ds_read_b128 v[176:179], v147 offset:35840
	ds_read_b128 v[180:183], v147 offset:36864
	ds_read_b128 v[184:187], v147 offset:37888
	ds_read_b128 v[188:191], v147 offset:38912
	ds_read_b128 v[192:195], v147 offset:39936
	s_add_i32 s39, 0, 0x1c000
	v_add_u32_e32 v210, s39, v145
	ds_read_b128 v[196:199], v210
	ds_read_b128 v[200:203], v210 offset:1024
	ds_read_b128 v[204:207], v210 offset:2048
	ds_read_b128 v[210:213], v210 offset:3072
	s_waitcnt lgkmcnt(4)
	s_barrier
	s_waitcnt lgkmcnt(0)
	v_mfma_f32_16x16x32_bf16 v[126:129], v[140:143], v[164:167], v[126:129]
	v_mfma_f32_16x16x32_bf16 v[122:125], v[152:155], v[164:167], v[122:125]
	v_mfma_f32_16x16x32_bf16 v[118:121], v[140:143], v[172:175], v[118:121]
	v_mfma_f32_16x16x32_bf16 v[110:113], v[152:155], v[172:175], v[110:113]
	v_mfma_f32_16x16x32_bf16 v[102:105], v[140:143], v[180:183], v[102:105]
	v_mfma_f32_16x16x32_bf16 v[94:97], v[152:155], v[180:183], v[94:97]
	v_mfma_f32_16x16x32_bf16 v[86:89], v[140:143], v[188:191], v[86:89]
	v_mfma_f32_16x16x32_bf16 v[78:81], v[152:155], v[188:191], v[78:81]
	v_mfma_f32_16x16x32_bf16 v[126:129], v[148:151], v[168:171], v[126:129]
	v_mfma_f32_16x16x32_bf16 v[122:125], v[160:163], v[168:171], v[122:125]
	v_mfma_f32_16x16x32_bf16 v[118:121], v[148:151], v[176:179], v[118:121]
	v_mfma_f32_16x16x32_bf16 v[110:113], v[160:163], v[176:179], v[110:113]
	v_mfma_f32_16x16x32_bf16 v[102:105], v[148:151], v[184:187], v[102:105]
	v_mfma_f32_16x16x32_bf16 v[94:97], v[160:163], v[184:187], v[94:97]
	v_mfma_f32_16x16x32_bf16 v[86:89], v[148:151], v[192:195], v[86:89]
	v_mfma_f32_16x16x32_bf16 v[78:81], v[160:163], v[192:195], v[78:81]
	v_mfma_f32_16x16x32_bf16 v[114:117], v[196:199], v[164:167], v[114:117]
	v_mfma_f32_16x16x32_bf16 v[106:109], v[204:207], v[164:167], v[106:109]
	v_mfma_f32_16x16x32_bf16 v[98:101], v[196:199], v[172:175], v[98:101]
	v_mfma_f32_16x16x32_bf16 v[90:93], v[204:207], v[172:175], v[90:93]
	v_mfma_f32_16x16x32_bf16 v[82:85], v[196:199], v[180:183], v[82:85]
	v_mfma_f32_16x16x32_bf16 v[74:77], v[204:207], v[180:183], v[74:77]
	v_mfma_f32_16x16x32_bf16 v[70:73], v[196:199], v[188:191], v[70:73]
	v_mfma_f32_16x16x32_bf16 v[66:69], v[204:207], v[188:191], v[66:69]
	v_mfma_f32_16x16x32_bf16 v[114:117], v[200:203], v[168:171], v[114:117]
	v_mfma_f32_16x16x32_bf16 v[106:109], v[210:213], v[168:171], v[106:109]
	v_mfma_f32_16x16x32_bf16 v[98:101], v[200:203], v[176:179], v[98:101]
	v_mfma_f32_16x16x32_bf16 v[90:93], v[210:213], v[176:179], v[90:93]
	v_mfma_f32_16x16x32_bf16 v[82:85], v[200:203], v[184:187], v[82:85]
	v_mfma_f32_16x16x32_bf16 v[74:77], v[210:213], v[184:187], v[74:77]
	v_mfma_f32_16x16x32_bf16 v[70:73], v[200:203], v[192:195], v[70:73]
	v_mfma_f32_16x16x32_bf16 v[66:69], v[210:213], v[192:195], v[66:69]
	s_barrier
; #define PG8_STAGE(bufoff, gbase, voff) do { _Pragma("unroll") for (int _i = 0; _i < 2; ++_i) \
;         __builtin_amdgcn_global_load_lds((const unsigned*)((const char*)(gbase) + (voff)[_i]), (LAS unsigned*)(lds + (bufoff) + ldsw + _i * 8192), 16, 0, 0); } while (0)
; #define PG8_LDA(dst, b, h) do { _Pragma("unroll") for (int m = 0; m < 4; ++m) _Pragma("unroll") for (int k = 0; k < 2; ++k) dst[m][k] = *(const LAS bf16x8*)(lds + PG8_SA(b, h) + aoff + m * 2048 + k * 1024); } while (0)
; #define PG8_LDB(dst, b, h) do { _Pragma("unroll") for (int n = 0; n < 2; ++n) _Pragma("unroll") for (int k = 0; k < 2; ++k) dst[n][k] = *(const LAS bf16x8*)(lds + PG8_SB(b, h) + boff + n * 2048 + k * 1024); } while (0)
; #define PG8_MMA(ai, bj, At, Bt) do { __builtin_amdgcn_s_setprio(1); _Pragma("unroll") for (int m = 0; m < 4; ++m) _Pragma("unroll") for (int n = 0; n < 2; ++n) _Pragma("unroll") for (int k = 0; k < 2; ++k) \
;         acc[ai][bj][m][n] = __builtin_amdgcn_mfma_f32_16x16x32_bf16(Bt[n][k], At[m][k], acc[ai][bj][m][n], 0, 0, 0); __builtin_amdgcn_s_setprio(0); } while (0)
; #define PG8_WAIT_V(n) asm volatile("s_waitcnt vmcnt(" #n ")" ::: "memory")
; #define PG8_WAIT_L(n) asm volatile("s_waitcnt lgkmcnt(" #n ")" ::: "memory")
; #define PG8_BAR __builtin_amdgcn_s_barrier()
; #define PG8_SCHED __builtin_amdgcn_sched_barrier(0)
; template <class Epi, class Sched>
; __device__ __forceinline__ void gemm_phase(LAS unsigned char* lds, const Gemm g, const Sched& S, const Epi& E) {
;     ...
;             PG8_WAIT_V(6); PG8_BAR; PG8_MMA(1, 1, At, B1); PG8_BAR;
;             PG8_LDB(B0, 1, 0); PG8_SCHED; PG8_LDA(At, 1, 0); PG8_STAGE(PG8_SA(0, 1), a2 + hstep, voffA);
;             PG8_WAIT_L(8); PG8_BAR; PG8_WAIT_L(0); PG8_MMA(0, 0, At, B0); PG8_BAR; PG8_SCHED;
;             PG8_LDB(B1, 1, 1); PG8_STAGE(PG8_SB(1, 0), b3, voffB);
;             PG8_BAR; PG8_WAIT_L(0); PG8_MMA(0, 1, At, B1); PG8_BAR;
;             PG8_LDA(At, 1, 1); PG8_STAGE(PG8_SA(1, 0), a3, voffA);
;             PG8_BAR; PG8_WAIT_L(0); PG8_MMA(1, 0, At, B0); PG8_BAR; PG8_SCHED;
;             PG8_STAGE(PG8_SB(1, 1), b3 + hstep, voffB);
;             PG8_WAIT_V(6); PG8_BAR; PG8_MMA(1, 1, At, B1); PG8_BAR;
	s_add_i32 s38, s38, s56
	v_lshl_add_u64 v[156:157], v[156:157], 0, s[36:37]
	s_mov_b32 m0, s38
	s_nop 0
	global_load_lds_dwordx4 v[156:157], off
	v_lshl_add_u64 v[156:157], v[214:215], 0, s[36:37]
	s_add_i32 m0, s38, 0x2000
	s_nop 0
	global_load_lds_dwordx4 v[156:157], off
	s_mov_b32 m0, s59
	v_lshl_add_u64 v[156:157], v[216:217], 0, s[36:37]
	global_load_lds_dwordx4 v[156:157], off
	v_lshl_add_u64 v[156:157], v[224:225], 0, s[36:37]
	s_mov_b32 m0, s60
	s_nop 0
	global_load_lds_dwordx4 v[156:157], off
	ds_read_b128 v[164:167], v147 offset:49152
	ds_read_b128 v[168:171], v147 offset:50176
	ds_read_b128 v[172:175], v147 offset:51200
	ds_read_b128 v[176:179], v147 offset:52224
	ds_read_b128 v[180:183], v147 offset:53248
	ds_read_b128 v[184:187], v147 offset:54272
	ds_read_b128 v[188:191], v147 offset:55296
	ds_read_b128 v[192:195], v147 offset:56320
	s_waitcnt vmcnt(4)
	s_waitcnt lgkmcnt(0)
	s_barrier
	v_mfma_f32_16x16x32_bf16 v[62:65], v[140:143], v[164:167], v[62:65]
	v_mfma_f32_16x16x32_bf16 v[58:61], v[152:155], v[164:167], v[58:61]
	v_mfma_f32_16x16x32_bf16 v[54:57], v[140:143], v[172:175], v[54:57]
	v_mfma_f32_16x16x32_bf16 v[46:49], v[152:155], v[172:175], v[46:49]
	v_mfma_f32_16x16x32_bf16 v[38:41], v[140:143], v[180:183], v[38:41]
	v_mfma_f32_16x16x32_bf16 v[30:33], v[152:155], v[180:183], v[30:33]
	v_mfma_f32_16x16x32_bf16 v[22:25], v[140:143], v[188:191], v[22:25]
	v_mfma_f32_16x16x32_bf16 v[14:17], v[152:155], v[188:191], v[14:17]
	v_mfma_f32_16x16x32_bf16 v[62:65], v[148:151], v[168:171], v[62:65]
	v_mfma_f32_16x16x32_bf16 v[58:61], v[160:163], v[168:171], v[58:61]
	v_mfma_f32_16x16x32_bf16 v[54:57], v[148:151], v[176:179], v[54:57]
	v_mfma_f32_16x16x32_bf16 v[46:49], v[160:163], v[176:179], v[46:49]
	v_mfma_f32_16x16x32_bf16 v[38:41], v[148:151], v[184:187], v[38:41]
	v_mfma_f32_16x16x32_bf16 v[30:33], v[160:163], v[184:187], v[30:33]
	v_mfma_f32_16x16x32_bf16 v[22:25], v[148:151], v[192:195], v[22:25]
	v_mfma_f32_16x16x32_bf16 v[14:17], v[160:163], v[192:195], v[14:17]
	v_mfma_f32_16x16x32_bf16 v[50:53], v[196:199], v[164:167], v[50:53]
	v_mfma_f32_16x16x32_bf16 v[42:45], v[204:207], v[164:167], v[42:45]
	v_mfma_f32_16x16x32_bf16 v[34:37], v[196:199], v[172:175], v[34:37]
	v_mfma_f32_16x16x32_bf16 v[26:29], v[204:207], v[172:175], v[26:29]
	v_mfma_f32_16x16x32_bf16 v[18:21], v[196:199], v[180:183], v[18:21]
	v_mfma_f32_16x16x32_bf16 v[10:13], v[204:207], v[180:183], v[10:13]
	v_mfma_f32_16x16x32_bf16 v[6:9], v[196:199], v[188:191], v[6:9]
	v_mfma_f32_16x16x32_bf16 v[2:5], v[204:207], v[188:191], v[2:5]
	v_mfma_f32_16x16x32_bf16 v[50:53], v[200:203], v[168:171], v[50:53]
	v_mfma_f32_16x16x32_bf16 v[42:45], v[210:213], v[168:171], v[42:45]
	v_mfma_f32_16x16x32_bf16 v[34:37], v[200:203], v[176:179], v[34:37]
	v_mfma_f32_16x16x32_bf16 v[26:29], v[210:213], v[176:179], v[26:29]
	v_mfma_f32_16x16x32_bf16 v[18:21], v[200:203], v[184:187], v[18:21]
	v_mfma_f32_16x16x32_bf16 v[10:13], v[210:213], v[184:187], v[10:13]
	v_mfma_f32_16x16x32_bf16 v[6:9], v[200:203], v[192:195], v[6:9]
	v_mfma_f32_16x16x32_bf16 v[2:5], v[210:213], v[192:195], v[2:5]
	s_add_i32 s70, s70, 2
	s_add_u32 s68, s68, 0x100
	s_addc_u32 s69, s69, 0
	s_add_u32 s50, s50, 0x100
	s_addc_u32 s51, s51, 0
	s_cmp_gt_u32 s70, 29
	s_barrier
	s_cbranch_scc0 .LBB0_354
; __device__ __forceinline__ unsigned cvt_pk_bf16(float lo, float hi) { unsigned r; asm("v_cvt_pk_bf16_f32 %0, %1, %2" : "=v"(r) : "v"(lo), "v"(hi)); return r; }
;     __device__ __forceinline__ void operator()(const f32x4 (&acc)[2][2][4][2], const Unit& u, int wr, int wc, int fr, int fq) const {
;         const int row0 = u.pm * BM + wr * 64 + fr, col0 = u.pn * BM + wc * 32 + 8 * fq;
; #pragma unroll
;         for (int ai = 0; ai < 2; ++ai)
; #pragma unroll
;             for (int m = 0; m < 4; ++m) { bf16_t* rowp = O + (size_t)(row0 + ai * HALF + m * 16) * ldc + col0;
; #pragma unroll
;                 for (int bj = 0; bj < 2; ++bj) { f32x4 v0 = acc[ai][bj][m][0], v1 = acc[ai][bj][m][1];
;                     if (ACT == 1) {
; #pragma unroll
;                         for (int j = 0; j < 4; ++j) { float a = fmaxf(v0[j], 0.f), b = fmaxf(v1[j], 0.f); v0[j] = a * a; v1[j] = b * b; } }
;                     u32x4 w; w.x = cvt_pk_bf16(v0[0], v0[1]); w.y = cvt_pk_bf16(v0[2], v0[3]); w.z = cvt_pk_bf16(v1[0], v1[1]); w.w = cvt_pk_bf16(v1[2], v1[3]);
;                     if (ACT == 1) __builtin_nontemporal_store(w, (u32x4*)(rowp + bj * HALF));
;                     else *(u32x4*)(rowp + bj * HALF) = w; } }
; template <class Epi, class Sched>
; __device__ __forceinline__ void gemm_phase(LAS unsigned char* lds, const Gemm g, const Sched& S, const Epi& E) {
;     ...
;         if (!has_next) break;
; #pragma unroll
;         for (int a = 0; a < 2; ++a)
; #pragma unroll
;             for (int b = 0; b < 2; ++b)
; #pragma unroll
;                 for (int m = 0; m < 4; ++m)
; #pragma unroll
;                     for (int n = 0; n < 2; ++n) acc[a][b][m][n] = (f32x4){0.f, 0.f, 0.f, 0.f};
;         cur = nxt; cA = nA; cB = nB; ++ui;
	s_load_dwordx2 s[50:51], s[0:1], 0xc0
	v_lshl_add_u32 v150, s28, 8, v144
	v_lshl_or_b32 v142, s40, 8, v146
	v_ashrrev_i32_e32 v143, 31, v142
	v_cvt_pk_bf16_f32 v70, v70, v71
	s_waitcnt lgkmcnt(0)
	v_mov_b64_e32 v[140:141], s[50:51]
	v_cvt_pk_bf16_f32 v71, v72, v73
	v_cvt_pk_bf16_f32 v72, v66, v67
	v_add_u32_e32 v66, 0x80, v150
	v_mad_i64_i32 v[148:149], s[50:51], v150, s17, v[140:141]
	v_lshlrev_b64 v[142:143], 1, v[142:143]
	v_cvt_pk_bf16_f32 v114, v114, v115
	v_cvt_pk_bf16_f32 v115, v116, v117
	v_cvt_pk_bf16_f32 v116, v106, v107
	v_or_b32_e32 v106, 16, v150
	v_mad_i64_i32 v[66:67], s[50:51], v66, s17, v[140:141]
	v_cvt_pk_bf16_f32 v50, v50, v51
	v_cvt_pk_bf16_f32 v51, v52, v53
	v_cvt_pk_bf16_f32 v52, v42, v43
	v_add_u32_e32 v42, 0x90, v150
	v_lshl_add_u64 v[148:149], v[148:149], 0, v[142:143]
	v_mad_i64_i32 v[106:107], s[50:51], v106, s17, v[140:141]
	v_cvt_pk_bf16_f32 v98, v98, v99
	v_cvt_pk_bf16_f32 v99, v100, v101
	v_cvt_pk_bf16_f32 v100, v90, v91
	v_or_b32_e32 v90, 32, v150
	v_lshl_add_u64 v[66:67], v[66:67], 0, v[142:143]
	v_mad_i64_i32 v[42:43], s[50:51], v42, s17, v[140:141]
	v_cvt_pk_bf16_f32 v34, v34, v35
	v_cvt_pk_bf16_f32 v35, v36, v37
	v_cvt_pk_bf16_f32 v36, v26, v27
	v_add_u32_e32 v26, 0xa0, v150
	v_cvt_pk_bf16_f32 v117, v108, v109
	global_store_dwordx4 v[148:149], v[114:117], off offset:256
	v_mad_i64_i32 v[90:91], s[50:51], v90, s17, v[140:141]
	s_nop 0
	v_lshl_add_u64 v[114:115], v[106:107], 0, v[142:143]
	v_cvt_pk_bf16_f32 v82, v82, v83
	v_cvt_pk_bf16_f32 v83, v84, v85
	v_cvt_pk_bf16_f32 v84, v74, v75
	v_or_b32_e32 v74, 48, v150
	v_cvt_pk_bf16_f32 v53, v44, v45
	global_store_dwordx4 v[66:67], v[50:53], off offset:256
	v_mad_i64_i32 v[26:27], s[50:51], v26, s17, v[140:141]
	s_nop 0
	v_lshl_add_u64 v[50:51], v[42:43], 0, v[142:143]
	v_cvt_pk_bf16_f32 v18, v18, v19
	v_cvt_pk_bf16_f32 v19, v20, v21
	v_cvt_pk_bf16_f32 v20, v10, v11
	v_add_u32_e32 v10, 0xb0, v150
	v_cvt_pk_bf16_f32 v101, v92, v93
	global_store_dwordx4 v[114:115], v[98:101], off offset:256
	v_mad_i64_i32 v[74:75], s[50:51], v74, s17, v[140:141]
	s_nop 0
	v_lshl_add_u64 v[98:99], v[90:91], 0, v[142:143]
	v_cvt_pk_bf16_f32 v37, v28, v29
	global_store_dwordx4 v[50:51], v[34:37], off offset:256
	v_mad_i64_i32 v[10:11], s[50:51], v10, s17, v[140:141]
	s_nop 0
	v_lshl_add_u64 v[34:35], v[26:27], 0, v[142:143]
	v_cvt_pk_bf16_f32 v85, v76, v77
	global_store_dwordx4 v[98:99], v[82:85], off offset:256
	v_cvt_pk_bf16_f32 v21, v12, v13
	global_store_dwordx4 v[34:35], v[18:21], off offset:256
	s_and_b64 vcc, exec, s[46:47]
	v_lshl_add_u64 v[82:83], v[74:75], 0, v[142:143]
	v_lshl_add_u64 v[18:19], v[10:11], 0, v[142:143]
	s_mov_b32 s40, s42
	s_mov_b32 s28, s8
	s_mov_b32 s43, s42
	s_mov_b32 s46, s8
	s_mov_b64 s[50:51], s[48:49]
	s_mov_b64 s[52:53], s[44:45]
	v_cvt_pk_bf16_f32 v126, v126, v127
	v_cvt_pk_bf16_f32 v127, v128, v129
	v_cvt_pk_bf16_f32 v128, v122, v123
	v_cvt_pk_bf16_f32 v129, v124, v125
	global_store_dwordx4 v[148:149], v[126:129], off
	v_cvt_pk_bf16_f32 v106, v118, v119
	v_cvt_pk_bf16_f32 v107, v120, v121
	v_cvt_pk_bf16_f32 v108, v110, v111
	v_cvt_pk_bf16_f32 v109, v112, v113
	global_store_dwordx4 v[114:115], v[106:109], off
	v_cvt_pk_bf16_f32 v90, v102, v103
	v_cvt_pk_bf16_f32 v91, v104, v105
	v_cvt_pk_bf16_f32 v92, v94, v95
	v_cvt_pk_bf16_f32 v93, v96, v97
	global_store_dwordx4 v[98:99], v[90:93], off
	v_cvt_pk_bf16_f32 v74, v86, v87
	v_cvt_pk_bf16_f32 v75, v88, v89
	v_cvt_pk_bf16_f32 v76, v78, v79
	v_cvt_pk_bf16_f32 v77, v80, v81
	global_store_dwordx4 v[82:83], v[74:77], off
	v_cvt_pk_bf16_f32 v73, v68, v69
	global_store_dwordx4 v[82:83], v[70:73], off offset:256
	v_cvt_pk_bf16_f32 v62, v62, v63
	v_cvt_pk_bf16_f32 v63, v64, v65
	v_cvt_pk_bf16_f32 v64, v58, v59
	v_cvt_pk_bf16_f32 v65, v60, v61
	global_store_dwordx4 v[66:67], v[62:65], off
	v_cvt_pk_bf16_f32 v42, v54, v55
	v_cvt_pk_bf16_f32 v43, v56, v57
	v_cvt_pk_bf16_f32 v44, v46, v47
	v_cvt_pk_bf16_f32 v45, v48, v49
	global_store_dwordx4 v[50:51], v[42:45], off
	v_cvt_pk_bf16_f32 v26, v38, v39
	v_cvt_pk_bf16_f32 v27, v40, v41
	v_cvt_pk_bf16_f32 v28, v30, v31
	v_cvt_pk_bf16_f32 v29, v32, v33
	global_store_dwordx4 v[34:35], v[26:29], off
	v_cvt_pk_bf16_f32 v10, v22, v23
	v_cvt_pk_bf16_f32 v11, v24, v25
	v_cvt_pk_bf16_f32 v12, v14, v15
	v_cvt_pk_bf16_f32 v13, v16, v17
	global_store_dwordx4 v[18:19], v[10:13], off
	v_cvt_pk_bf16_f32 v6, v6, v7
	v_cvt_pk_bf16_f32 v7, v8, v9
	v_cvt_pk_bf16_f32 v8, v2, v3
	v_cvt_pk_bf16_f32 v9, v4, v5
	global_store_dwordx4 v[18:19], v[6:9], off offset:256
	s_cbranch_vccz .LBB0_346
	s_waitcnt vmcnt(0)
	s_cmpk_gt_u32 s25, 0xff
	s_cbranch_scc1 .LBB0_358
	s_barrier
